# GEMM MFMA blocks: back-to-back s_setprio 0 / s_setprio 1 pairs between the two 16-MFMA groups removed (priority unchanged)
# speedup vs baseline: 1.0039x; 1.0039x over previous
.LBB0_187:
	s_ashr_i32 s15, s14, 31
	s_lshl_b64 s[16:17], s[14:15], 19
	s_add_u32 s16, s30, s16
	s_addc_u32 s17, s31, s17
	s_and_b64 s[18:19], s[0:1], exec
	s_cselect_b32 s3, s17, s25
	s_cselect_b32 s15, s16, s24
	s_ashr_i32 s13, s12, 31
	s_lshl_b64 s[18:19], s[12:13], 19
	s_add_u32 s18, s34, s18
	s_addc_u32 s19, s35, s19
	s_and_b64 s[26:27], s[0:1], exec
	s_cselect_b32 s13, s19, s23
	s_cselect_b32 s21, s18, s22
	s_add_u32 s48, s22, 0x100
	s_addc_u32 s49, s23, 0
	s_add_u32 s22, s24, 0x40080
	s_addc_u32 s23, s25, 0
	s_mov_b32 s50, -2
	s_waitcnt vmcnt(0)
	s_add_u32 s24, s22, 0xfffc0080
	s_addc_u32 s25, s23, -1
	s_add_i32 s51, 0, 0x10000
	s_cmp_eq_u32 s50, 12
	s_cselect_b32 s27, s3, s25
	s_cselect_b32 s26, s15, s24
	v_add_u32_e32 v142, s51, v144
	s_cselect_b32 s25, s13, s49
	s_cselect_b32 s24, s21, s48
	s_add_i32 s54, 0, 0x14000
	ds_read_b128 v[138:141], v142
	ds_read_b128 v[146:149], v142 offset:1024
	ds_read_b128 v[150:153], v142 offset:2048
	ds_read_b128 v[154:157], v142 offset:3072
	v_add_u32_e32 v142, s54, v144
	ds_read_b128 v[158:161], v142
	ds_read_b128 v[162:165], v142 offset:1024
	ds_read_b128 v[166:169], v142 offset:2048
	ds_read_b128 v[170:173], v142 offset:3072
	v_lshl_add_u64 v[142:143], s[22:23], 0, v[136:137]
	s_add_i32 m0, s37, 0xc000
	ds_read_b128 v[174:177], v145
	ds_read_b128 v[178:181], v145 offset:1024
	ds_read_b128 v[182:185], v145 offset:2048
	ds_read_b128 v[186:189], v145 offset:3072
	ds_read_b128 v[190:193], v145 offset:4096
	ds_read_b128 v[194:197], v145 offset:5120
	ds_read_b128 v[198:201], v145 offset:6144
	ds_read_b128 v[202:205], v145 offset:7168
	global_load_lds_dwordx4 v[142:143], off
	v_lshl_add_u64 v[142:143], s[22:23], 0, v[134:135]
	s_add_i32 m0, s37, 0xe000
	s_nop 0
	global_load_lds_dwordx4 v[142:143], off
	s_waitcnt vmcnt(8)
	s_waitcnt lgkmcnt(0)
	s_barrier
	s_setprio 1
	s_waitcnt lgkmcnt(0)
	v_mfma_f32_16x16x32_bf16 v[124:127], v[138:141], v[174:177], 0
	v_mfma_f32_16x16x32_bf16 v[120:123], v[150:153], v[174:177], 0
	v_mfma_f32_16x16x32_bf16 v[112:115], v[138:141], v[182:185], 0
	v_mfma_f32_16x16x32_bf16 v[104:107], v[150:153], v[182:185], 0
	v_mfma_f32_16x16x32_bf16 v[96:99], v[138:141], v[190:193], 0
	v_mfma_f32_16x16x32_bf16 v[88:91], v[150:153], v[190:193], 0
	v_mfma_f32_16x16x32_bf16 v[80:83], v[138:141], v[198:201], 0
	v_mfma_f32_16x16x32_bf16 v[72:75], v[150:153], v[198:201], 0
	v_mfma_f32_16x16x32_bf16 v[124:127], v[146:149], v[178:181], v[124:127]
	v_mfma_f32_16x16x32_bf16 v[120:123], v[154:157], v[178:181], v[120:123]
	v_mfma_f32_16x16x32_bf16 v[112:115], v[146:149], v[186:189], v[112:115]
	v_mfma_f32_16x16x32_bf16 v[104:107], v[154:157], v[186:189], v[104:107]
	v_mfma_f32_16x16x32_bf16 v[96:99], v[146:149], v[194:197], v[96:99]
	v_mfma_f32_16x16x32_bf16 v[88:91], v[154:157], v[194:197], v[88:91]
	v_mfma_f32_16x16x32_bf16 v[80:83], v[146:149], v[202:205], v[80:83]
	v_mfma_f32_16x16x32_bf16 v[72:75], v[154:157], v[202:205], v[72:75]
	v_mfma_f32_16x16x32_bf16 v[116:119], v[158:161], v[174:177], 0
	v_mfma_f32_16x16x32_bf16 v[108:111], v[166:169], v[174:177], 0
	v_mfma_f32_16x16x32_bf16 v[100:103], v[158:161], v[182:185], 0
	v_mfma_f32_16x16x32_bf16 v[92:95], v[166:169], v[182:185], 0
	v_mfma_f32_16x16x32_bf16 v[84:87], v[158:161], v[190:193], 0
	v_mfma_f32_16x16x32_bf16 v[76:79], v[166:169], v[190:193], 0
	v_mfma_f32_16x16x32_bf16 v[68:71], v[158:161], v[198:201], 0
	v_mfma_f32_16x16x32_bf16 v[64:67], v[166:169], v[198:201], 0
	v_mfma_f32_16x16x32_bf16 v[116:119], v[162:165], v[178:181], v[116:119]
	v_mfma_f32_16x16x32_bf16 v[108:111], v[170:173], v[178:181], v[108:111]
	v_mfma_f32_16x16x32_bf16 v[100:103], v[162:165], v[186:189], v[100:103]
	v_mfma_f32_16x16x32_bf16 v[92:95], v[170:173], v[186:189], v[92:95]
	v_mfma_f32_16x16x32_bf16 v[84:87], v[162:165], v[194:197], v[84:87]
	v_mfma_f32_16x16x32_bf16 v[76:79], v[170:173], v[194:197], v[76:79]
	v_mfma_f32_16x16x32_bf16 v[68:71], v[162:165], v[202:205], v[68:71]
	v_mfma_f32_16x16x32_bf16 v[64:67], v[170:173], v[202:205], v[64:67]
	s_setprio 0
	s_barrier
	s_add_i32 s51, s51, s36
	v_lshl_add_u64 v[142:143], s[24:25], 0, v[232:233]
	s_mov_b32 m0, s51
	ds_read_b128 v[174:177], v145 offset:16384
	ds_read_b128 v[178:181], v145 offset:17408
	ds_read_b128 v[182:185], v145 offset:18432
	ds_read_b128 v[186:189], v145 offset:19456
	ds_read_b128 v[190:193], v145 offset:20480
	ds_read_b128 v[194:197], v145 offset:21504
	ds_read_b128 v[198:201], v145 offset:22528
	ds_read_b128 v[202:205], v145 offset:23552
	global_load_lds_dwordx4 v[142:143], off
	s_add_i32 m0, s51, 0x2000
	s_add_u32 s52, s24, 0x40000
	v_lshl_add_u64 v[206:207], s[24:25], 0, v[132:133]
	s_addc_u32 s53, s25, 0
	s_add_i32 s51, s54, s36
	global_load_lds_dwordx4 v[206:207], off
	v_lshl_add_u64 v[208:209], s[52:53], 0, v[232:233]
	s_mov_b32 m0, s51
	v_lshl_add_u64 v[210:211], s[26:27], 0, v[130:131]
	global_load_lds_dwordx4 v[208:209], off
	v_lshl_add_u64 v[208:209], s[52:53], 0, v[132:133]
	s_add_i32 m0, s51, 0x2000
	s_nop 0
	global_load_lds_dwordx4 v[208:209], off
	v_lshl_add_u64 v[208:209], s[26:27], 0, v[128:129]
	s_waitcnt vmcnt(6)
	s_waitcnt lgkmcnt(0)
	s_barrier
	s_setprio 1
	s_waitcnt lgkmcnt(0)
	v_mfma_f32_16x16x32_bf16 v[60:63], v[138:141], v[174:177], 0
	v_mfma_f32_16x16x32_bf16 v[56:59], v[150:153], v[174:177], 0
	v_mfma_f32_16x16x32_bf16 v[48:51], v[138:141], v[182:185], 0
	v_mfma_f32_16x16x32_bf16 v[40:43], v[150:153], v[182:185], 0
	v_mfma_f32_16x16x32_bf16 v[32:35], v[138:141], v[190:193], 0
	v_mfma_f32_16x16x32_bf16 v[24:27], v[150:153], v[190:193], 0
	v_mfma_f32_16x16x32_bf16 v[16:19], v[138:141], v[198:201], 0
	v_mfma_f32_16x16x32_bf16 v[8:11], v[150:153], v[198:201], 0
	v_mfma_f32_16x16x32_bf16 v[60:63], v[146:149], v[178:181], v[60:63]
	v_mfma_f32_16x16x32_bf16 v[56:59], v[154:157], v[178:181], v[56:59]
	v_mfma_f32_16x16x32_bf16 v[48:51], v[146:149], v[186:189], v[48:51]
	v_mfma_f32_16x16x32_bf16 v[40:43], v[154:157], v[186:189], v[40:43]
	v_mfma_f32_16x16x32_bf16 v[32:35], v[146:149], v[194:197], v[32:35]
	v_mfma_f32_16x16x32_bf16 v[24:27], v[154:157], v[194:197], v[24:27]
	v_mfma_f32_16x16x32_bf16 v[16:19], v[146:149], v[202:205], v[16:19]
	v_mfma_f32_16x16x32_bf16 v[8:11], v[154:157], v[202:205], v[8:11]
	v_mfma_f32_16x16x32_bf16 v[52:55], v[158:161], v[174:177], 0
	v_mfma_f32_16x16x32_bf16 v[44:47], v[166:169], v[174:177], 0
	v_mfma_f32_16x16x32_bf16 v[36:39], v[158:161], v[182:185], 0
	v_mfma_f32_16x16x32_bf16 v[28:31], v[166:169], v[182:185], 0
	v_mfma_f32_16x16x32_bf16 v[20:23], v[158:161], v[190:193], 0
	v_mfma_f32_16x16x32_bf16 v[12:15], v[166:169], v[190:193], 0
	v_mfma_f32_16x16x32_bf16 v[4:7], v[158:161], v[198:201], 0
	v_mfma_f32_16x16x32_bf16 v[0:3], v[166:169], v[198:201], 0
	v_mfma_f32_16x16x32_bf16 v[52:55], v[162:165], v[178:181], v[52:55]
	v_mfma_f32_16x16x32_bf16 v[44:47], v[170:173], v[178:181], v[44:47]
	v_mfma_f32_16x16x32_bf16 v[36:39], v[162:165], v[186:189], v[36:39]
	v_mfma_f32_16x16x32_bf16 v[28:31], v[170:173], v[186:189], v[28:31]
	v_mfma_f32_16x16x32_bf16 v[20:23], v[162:165], v[194:197], v[20:23]
	v_mfma_f32_16x16x32_bf16 v[12:15], v[170:173], v[194:197], v[12:15]
	v_mfma_f32_16x16x32_bf16 v[4:7], v[162:165], v[202:205], v[4:7]
	v_mfma_f32_16x16x32_bf16 v[0:3], v[170:173], v[202:205], v[0:3]
	s_setprio 0
	s_barrier
	s_branch .Lzmid_1
.LBB0_188:
	s_add_u32 s24, s22, 0xfffc0080
	s_addc_u32 s25, s23, -1
	s_add_i32 s51, 0, 0x10000
	s_cmp_eq_u32 s50, 12
	s_cselect_b32 s27, s3, s25
	s_cselect_b32 s26, s15, s24
	v_add_u32_e32 v142, s51, v144
	s_cselect_b32 s25, s13, s49
	s_cselect_b32 s24, s21, s48
	s_add_i32 s54, 0, 0x14000
	ds_read_b128 v[138:141], v142
	ds_read_b128 v[146:149], v142 offset:1024
	ds_read_b128 v[150:153], v142 offset:2048
	ds_read_b128 v[154:157], v142 offset:3072
	v_add_u32_e32 v142, s54, v144
	ds_read_b128 v[158:161], v142
	ds_read_b128 v[162:165], v142 offset:1024
	ds_read_b128 v[166:169], v142 offset:2048
	ds_read_b128 v[170:173], v142 offset:3072
	v_lshl_add_u64 v[142:143], s[22:23], 0, v[136:137]
	s_add_i32 m0, s37, 0xc000
	ds_read_b128 v[174:177], v145
	ds_read_b128 v[178:181], v145 offset:1024
	ds_read_b128 v[182:185], v145 offset:2048
	ds_read_b128 v[186:189], v145 offset:3072
	ds_read_b128 v[190:193], v145 offset:4096
	ds_read_b128 v[194:197], v145 offset:5120
	ds_read_b128 v[198:201], v145 offset:6144
	ds_read_b128 v[202:205], v145 offset:7168
	global_load_lds_dwordx4 v[142:143], off
	v_lshl_add_u64 v[142:143], s[22:23], 0, v[134:135]
	s_add_i32 m0, s37, 0xe000
	s_nop 0
	global_load_lds_dwordx4 v[142:143], off
	s_waitcnt vmcnt(8)
	s_waitcnt lgkmcnt(0)
	s_barrier
	s_setprio 1
	s_waitcnt lgkmcnt(0)
	v_mfma_f32_16x16x32_bf16 v[124:127], v[138:141], v[174:177], v[124:127]
	v_mfma_f32_16x16x32_bf16 v[120:123], v[150:153], v[174:177], v[120:123]
	v_mfma_f32_16x16x32_bf16 v[112:115], v[138:141], v[182:185], v[112:115]
	v_mfma_f32_16x16x32_bf16 v[104:107], v[150:153], v[182:185], v[104:107]
	v_mfma_f32_16x16x32_bf16 v[96:99], v[138:141], v[190:193], v[96:99]
	v_mfma_f32_16x16x32_bf16 v[88:91], v[150:153], v[190:193], v[88:91]
	v_mfma_f32_16x16x32_bf16 v[80:83], v[138:141], v[198:201], v[80:83]
	v_mfma_f32_16x16x32_bf16 v[72:75], v[150:153], v[198:201], v[72:75]
	v_mfma_f32_16x16x32_bf16 v[124:127], v[146:149], v[178:181], v[124:127]
	v_mfma_f32_16x16x32_bf16 v[120:123], v[154:157], v[178:181], v[120:123]
	v_mfma_f32_16x16x32_bf16 v[112:115], v[146:149], v[186:189], v[112:115]
	v_mfma_f32_16x16x32_bf16 v[104:107], v[154:157], v[186:189], v[104:107]
	v_mfma_f32_16x16x32_bf16 v[96:99], v[146:149], v[194:197], v[96:99]
	v_mfma_f32_16x16x32_bf16 v[88:91], v[154:157], v[194:197], v[88:91]
	v_mfma_f32_16x16x32_bf16 v[80:83], v[146:149], v[202:205], v[80:83]
	v_mfma_f32_16x16x32_bf16 v[72:75], v[154:157], v[202:205], v[72:75]
	v_mfma_f32_16x16x32_bf16 v[116:119], v[158:161], v[174:177], v[116:119]
	v_mfma_f32_16x16x32_bf16 v[108:111], v[166:169], v[174:177], v[108:111]
	v_mfma_f32_16x16x32_bf16 v[100:103], v[158:161], v[182:185], v[100:103]
	v_mfma_f32_16x16x32_bf16 v[92:95], v[166:169], v[182:185], v[92:95]
	v_mfma_f32_16x16x32_bf16 v[84:87], v[158:161], v[190:193], v[84:87]
	v_mfma_f32_16x16x32_bf16 v[76:79], v[166:169], v[190:193], v[76:79]
	v_mfma_f32_16x16x32_bf16 v[68:71], v[158:161], v[198:201], v[68:71]
	v_mfma_f32_16x16x32_bf16 v[64:67], v[166:169], v[198:201], v[64:67]
	v_mfma_f32_16x16x32_bf16 v[116:119], v[162:165], v[178:181], v[116:119]
	v_mfma_f32_16x16x32_bf16 v[108:111], v[170:173], v[178:181], v[108:111]
	v_mfma_f32_16x16x32_bf16 v[100:103], v[162:165], v[186:189], v[100:103]
	v_mfma_f32_16x16x32_bf16 v[92:95], v[170:173], v[186:189], v[92:95]
	v_mfma_f32_16x16x32_bf16 v[84:87], v[162:165], v[194:197], v[84:87]
	v_mfma_f32_16x16x32_bf16 v[76:79], v[170:173], v[194:197], v[76:79]
	v_mfma_f32_16x16x32_bf16 v[68:71], v[162:165], v[202:205], v[68:71]
	v_mfma_f32_16x16x32_bf16 v[64:67], v[170:173], v[202:205], v[64:67]
	s_setprio 0
	s_barrier
	s_add_i32 s51, s51, s36
	v_lshl_add_u64 v[142:143], s[24:25], 0, v[232:233]
	s_mov_b32 m0, s51
	ds_read_b128 v[174:177], v145 offset:16384
	ds_read_b128 v[178:181], v145 offset:17408
	ds_read_b128 v[182:185], v145 offset:18432
	ds_read_b128 v[186:189], v145 offset:19456
	ds_read_b128 v[190:193], v145 offset:20480
	ds_read_b128 v[194:197], v145 offset:21504
	ds_read_b128 v[198:201], v145 offset:22528
	ds_read_b128 v[202:205], v145 offset:23552
	global_load_lds_dwordx4 v[142:143], off
	s_add_i32 m0, s51, 0x2000
	s_add_u32 s52, s24, 0x40000
	v_lshl_add_u64 v[206:207], s[24:25], 0, v[132:133]
	s_addc_u32 s53, s25, 0
	s_add_i32 s51, s54, s36
	global_load_lds_dwordx4 v[206:207], off
	v_lshl_add_u64 v[208:209], s[52:53], 0, v[232:233]
	s_mov_b32 m0, s51
	v_lshl_add_u64 v[210:211], s[26:27], 0, v[130:131]
	global_load_lds_dwordx4 v[208:209], off
	v_lshl_add_u64 v[208:209], s[52:53], 0, v[132:133]
	s_add_i32 m0, s51, 0x2000
	s_nop 0
	global_load_lds_dwordx4 v[208:209], off
	v_lshl_add_u64 v[208:209], s[26:27], 0, v[128:129]
	s_waitcnt vmcnt(6)
	s_waitcnt lgkmcnt(0)
	s_barrier
	s_setprio 1
	s_waitcnt lgkmcnt(0)
	v_mfma_f32_16x16x32_bf16 v[60:63], v[138:141], v[174:177], v[60:63]
	v_mfma_f32_16x16x32_bf16 v[56:59], v[150:153], v[174:177], v[56:59]
	v_mfma_f32_16x16x32_bf16 v[48:51], v[138:141], v[182:185], v[48:51]
	v_mfma_f32_16x16x32_bf16 v[40:43], v[150:153], v[182:185], v[40:43]
	v_mfma_f32_16x16x32_bf16 v[32:35], v[138:141], v[190:193], v[32:35]
	v_mfma_f32_16x16x32_bf16 v[24:27], v[150:153], v[190:193], v[24:27]
	v_mfma_f32_16x16x32_bf16 v[16:19], v[138:141], v[198:201], v[16:19]
	v_mfma_f32_16x16x32_bf16 v[8:11], v[150:153], v[198:201], v[8:11]
	v_mfma_f32_16x16x32_bf16 v[60:63], v[146:149], v[178:181], v[60:63]
	v_mfma_f32_16x16x32_bf16 v[56:59], v[154:157], v[178:181], v[56:59]
	v_mfma_f32_16x16x32_bf16 v[48:51], v[146:149], v[186:189], v[48:51]
	v_mfma_f32_16x16x32_bf16 v[40:43], v[154:157], v[186:189], v[40:43]
	v_mfma_f32_16x16x32_bf16 v[32:35], v[146:149], v[194:197], v[32:35]
	v_mfma_f32_16x16x32_bf16 v[24:27], v[154:157], v[194:197], v[24:27]
	v_mfma_f32_16x16x32_bf16 v[16:19], v[146:149], v[202:205], v[16:19]
	v_mfma_f32_16x16x32_bf16 v[8:11], v[154:157], v[202:205], v[8:11]
	v_mfma_f32_16x16x32_bf16 v[52:55], v[158:161], v[174:177], v[52:55]
	v_mfma_f32_16x16x32_bf16 v[44:47], v[166:169], v[174:177], v[44:47]
	v_mfma_f32_16x16x32_bf16 v[36:39], v[158:161], v[182:185], v[36:39]
	v_mfma_f32_16x16x32_bf16 v[28:31], v[166:169], v[182:185], v[28:31]
	v_mfma_f32_16x16x32_bf16 v[20:23], v[158:161], v[190:193], v[20:23]
	v_mfma_f32_16x16x32_bf16 v[12:15], v[166:169], v[190:193], v[12:15]
	v_mfma_f32_16x16x32_bf16 v[4:7], v[158:161], v[198:201], v[4:7]
	v_mfma_f32_16x16x32_bf16 v[0:3], v[166:169], v[198:201], v[0:3]
	v_mfma_f32_16x16x32_bf16 v[52:55], v[162:165], v[178:181], v[52:55]
	v_mfma_f32_16x16x32_bf16 v[44:47], v[170:173], v[178:181], v[44:47]
	v_mfma_f32_16x16x32_bf16 v[36:39], v[162:165], v[186:189], v[36:39]
	v_mfma_f32_16x16x32_bf16 v[28:31], v[170:173], v[186:189], v[28:31]
	v_mfma_f32_16x16x32_bf16 v[20:23], v[162:165], v[194:197], v[20:23]
	v_mfma_f32_16x16x32_bf16 v[12:15], v[170:173], v[194:197], v[12:15]
	v_mfma_f32_16x16x32_bf16 v[4:7], v[162:165], v[202:205], v[4:7]
	v_mfma_f32_16x16x32_bf16 v[0:3], v[170:173], v[202:205], v[0:3]
	s_setprio 0
	s_barrier
.Lzmid_1:
	s_add_i32 s51, 0, 0x18000
	s_add_i32 s52, 0, 0x1c000
	v_add_u32_e32 v154, s51, v144
	v_add_u32_e32 v170, s52, v144
	ds_read_b128 v[138:141], v154
	ds_read_b128 v[146:149], v154 offset:1024
	ds_read_b128 v[150:153], v154 offset:2048
	ds_read_b128 v[154:157], v154 offset:3072
	ds_read_b128 v[158:161], v170
	ds_read_b128 v[162:165], v170 offset:1024
	ds_read_b128 v[166:169], v170 offset:2048
	ds_read_b128 v[170:173], v170 offset:3072
	s_add_u32 s26, s26, 0x40000
	s_addc_u32 s27, s27, 0
	s_mov_b32 m0, s37
	s_nop 0
	global_load_lds_dwordx4 v[208:209], off
	s_mov_b32 m0, s38
	s_nop 0
	global_load_lds_dwordx4 v[210:211], off
	s_mov_b32 m0, s39
	v_lshl_add_u64 v[212:213], s[26:27], 0, v[128:129]
	ds_read_b128 v[174:177], v145 offset:32768
	ds_read_b128 v[178:181], v145 offset:33792
	ds_read_b128 v[182:185], v145 offset:34816
	ds_read_b128 v[186:189], v145 offset:35840
	ds_read_b128 v[190:193], v145 offset:36864
	ds_read_b128 v[194:197], v145 offset:37888
	ds_read_b128 v[198:201], v145 offset:38912
	ds_read_b128 v[202:205], v145 offset:39936
	global_load_lds_dwordx4 v[212:213], off
	v_lshl_add_u64 v[212:213], s[26:27], 0, v[130:131]
	s_mov_b32 m0, s40
	s_nop 0
	global_load_lds_dwordx4 v[212:213], off
	s_waitcnt vmcnt(8)
	s_waitcnt lgkmcnt(0)
	s_barrier
	s_setprio 1
	s_waitcnt lgkmcnt(0)
	v_mfma_f32_16x16x32_bf16 v[124:127], v[138:141], v[174:177], v[124:127]
	v_mfma_f32_16x16x32_bf16 v[120:123], v[150:153], v[174:177], v[120:123]
	v_mfma_f32_16x16x32_bf16 v[112:115], v[138:141], v[182:185], v[112:115]
	v_mfma_f32_16x16x32_bf16 v[104:107], v[150:153], v[182:185], v[104:107]
	v_mfma_f32_16x16x32_bf16 v[96:99], v[138:141], v[190:193], v[96:99]
	v_mfma_f32_16x16x32_bf16 v[88:91], v[150:153], v[190:193], v[88:91]
	v_mfma_f32_16x16x32_bf16 v[80:83], v[138:141], v[198:201], v[80:83]
	v_mfma_f32_16x16x32_bf16 v[72:75], v[150:153], v[198:201], v[72:75]
	v_mfma_f32_16x16x32_bf16 v[124:127], v[146:149], v[178:181], v[124:127]
	v_mfma_f32_16x16x32_bf16 v[120:123], v[154:157], v[178:181], v[120:123]
	v_mfma_f32_16x16x32_bf16 v[112:115], v[146:149], v[186:189], v[112:115]
	v_mfma_f32_16x16x32_bf16 v[104:107], v[154:157], v[186:189], v[104:107]
	v_mfma_f32_16x16x32_bf16 v[96:99], v[146:149], v[194:197], v[96:99]
	v_mfma_f32_16x16x32_bf16 v[88:91], v[154:157], v[194:197], v[88:91]
	v_mfma_f32_16x16x32_bf16 v[80:83], v[146:149], v[202:205], v[80:83]
	v_mfma_f32_16x16x32_bf16 v[72:75], v[154:157], v[202:205], v[72:75]
	v_mfma_f32_16x16x32_bf16 v[116:119], v[158:161], v[174:177], v[116:119]
	v_mfma_f32_16x16x32_bf16 v[108:111], v[166:169], v[174:177], v[108:111]
	v_mfma_f32_16x16x32_bf16 v[100:103], v[158:161], v[182:185], v[100:103]
	v_mfma_f32_16x16x32_bf16 v[92:95], v[166:169], v[182:185], v[92:95]
	v_mfma_f32_16x16x32_bf16 v[84:87], v[158:161], v[190:193], v[84:87]
	v_mfma_f32_16x16x32_bf16 v[76:79], v[166:169], v[190:193], v[76:79]
	v_mfma_f32_16x16x32_bf16 v[68:71], v[158:161], v[198:201], v[68:71]
	v_mfma_f32_16x16x32_bf16 v[64:67], v[166:169], v[198:201], v[64:67]
	v_mfma_f32_16x16x32_bf16 v[116:119], v[162:165], v[178:181], v[116:119]
	v_mfma_f32_16x16x32_bf16 v[108:111], v[170:173], v[178:181], v[108:111]
	v_mfma_f32_16x16x32_bf16 v[100:103], v[162:165], v[186:189], v[100:103]
	v_mfma_f32_16x16x32_bf16 v[92:95], v[170:173], v[186:189], v[92:95]
	v_mfma_f32_16x16x32_bf16 v[84:87], v[162:165], v[194:197], v[84:87]
	v_mfma_f32_16x16x32_bf16 v[76:79], v[170:173], v[194:197], v[76:79]
	v_mfma_f32_16x16x32_bf16 v[68:71], v[162:165], v[202:205], v[68:71]
	v_mfma_f32_16x16x32_bf16 v[64:67], v[170:173], v[202:205], v[64:67]
	s_setprio 0
	s_barrier
	s_add_i32 s26, s51, s36
	v_lshl_add_u64 v[142:143], v[142:143], 0, s[94:95]
	s_mov_b32 m0, s26
	ds_read_b128 v[174:177], v145 offset:49152
	ds_read_b128 v[178:181], v145 offset:50176
	ds_read_b128 v[182:185], v145 offset:51200
	ds_read_b128 v[186:189], v145 offset:52224
	ds_read_b128 v[190:193], v145 offset:53248
	ds_read_b128 v[194:197], v145 offset:54272
	ds_read_b128 v[198:201], v145 offset:55296
	ds_read_b128 v[202:205], v145 offset:56320
	global_load_lds_dwordx4 v[142:143], off
	s_add_i32 m0, s26, 0x2000
	s_add_u32 s24, s24, 0x40080
	v_lshl_add_u64 v[142:143], v[206:207], 0, s[94:95]
	s_addc_u32 s25, s25, 0
	s_add_i32 s26, s52, s36
	global_load_lds_dwordx4 v[142:143], off
	v_lshl_add_u64 v[142:143], s[24:25], 0, v[232:233]
	s_mov_b32 m0, s26
	s_nop 0
	global_load_lds_dwordx4 v[142:143], off
	v_lshl_add_u64 v[142:143], s[24:25], 0, v[132:133]
	s_add_i32 m0, s26, 0x2000
	s_nop 0
	global_load_lds_dwordx4 v[142:143], off
	v_lshl_add_u64 v[142:143], v[208:209], 0, s[94:95]
	s_mov_b32 m0, s43
	s_nop 0
	global_load_lds_dwordx4 v[142:143], off
	v_lshl_add_u64 v[142:143], v[210:211], 0, s[94:95]
	s_mov_b32 m0, s44
	s_nop 0
	global_load_lds_dwordx4 v[142:143], off
	s_waitcnt vmcnt(8)
	s_waitcnt lgkmcnt(0)
	s_barrier
	s_setprio 1
	s_waitcnt lgkmcnt(0)
	v_mfma_f32_16x16x32_bf16 v[60:63], v[138:141], v[174:177], v[60:63]
	v_mfma_f32_16x16x32_bf16 v[56:59], v[150:153], v[174:177], v[56:59]
	v_mfma_f32_16x16x32_bf16 v[48:51], v[138:141], v[182:185], v[48:51]
	v_mfma_f32_16x16x32_bf16 v[40:43], v[150:153], v[182:185], v[40:43]
	v_mfma_f32_16x16x32_bf16 v[32:35], v[138:141], v[190:193], v[32:35]
	v_mfma_f32_16x16x32_bf16 v[24:27], v[150:153], v[190:193], v[24:27]
	v_mfma_f32_16x16x32_bf16 v[16:19], v[138:141], v[198:201], v[16:19]
	v_mfma_f32_16x16x32_bf16 v[8:11], v[150:153], v[198:201], v[8:11]
	v_mfma_f32_16x16x32_bf16 v[60:63], v[146:149], v[178:181], v[60:63]
	v_mfma_f32_16x16x32_bf16 v[56:59], v[154:157], v[178:181], v[56:59]
	v_mfma_f32_16x16x32_bf16 v[48:51], v[146:149], v[186:189], v[48:51]
	v_mfma_f32_16x16x32_bf16 v[40:43], v[154:157], v[186:189], v[40:43]
	v_mfma_f32_16x16x32_bf16 v[32:35], v[146:149], v[194:197], v[32:35]
	v_mfma_f32_16x16x32_bf16 v[24:27], v[154:157], v[194:197], v[24:27]
	v_mfma_f32_16x16x32_bf16 v[16:19], v[146:149], v[202:205], v[16:19]
	v_mfma_f32_16x16x32_bf16 v[8:11], v[154:157], v[202:205], v[8:11]
	v_mfma_f32_16x16x32_bf16 v[52:55], v[158:161], v[174:177], v[52:55]
	v_mfma_f32_16x16x32_bf16 v[44:47], v[166:169], v[174:177], v[44:47]
	v_mfma_f32_16x16x32_bf16 v[36:39], v[158:161], v[182:185], v[36:39]
	v_mfma_f32_16x16x32_bf16 v[28:31], v[166:169], v[182:185], v[28:31]
	v_mfma_f32_16x16x32_bf16 v[20:23], v[158:161], v[190:193], v[20:23]
	v_mfma_f32_16x16x32_bf16 v[12:15], v[166:169], v[190:193], v[12:15]
	v_mfma_f32_16x16x32_bf16 v[4:7], v[158:161], v[198:201], v[4:7]
	v_mfma_f32_16x16x32_bf16 v[0:3], v[166:169], v[198:201], v[0:3]
	v_mfma_f32_16x16x32_bf16 v[52:55], v[162:165], v[178:181], v[52:55]
	v_mfma_f32_16x16x32_bf16 v[44:47], v[170:173], v[178:181], v[44:47]
	v_mfma_f32_16x16x32_bf16 v[36:39], v[162:165], v[186:189], v[36:39]
	v_mfma_f32_16x16x32_bf16 v[28:31], v[170:173], v[186:189], v[28:31]
	v_mfma_f32_16x16x32_bf16 v[20:23], v[162:165], v[194:197], v[20:23]
	v_mfma_f32_16x16x32_bf16 v[12:15], v[170:173], v[194:197], v[12:15]
	v_mfma_f32_16x16x32_bf16 v[4:7], v[162:165], v[202:205], v[4:7]
	v_mfma_f32_16x16x32_bf16 v[0:3], v[170:173], v[202:205], v[0:3]
	s_setprio 0
	s_barrier
	s_add_i32 s50, s50, 2
	s_add_u32 s48, s48, 0x100
	s_addc_u32 s49, s49, 0
	s_add_u32 s22, s22, 0x100
	s_addc_u32 s23, s23, 0
	s_cmp_gt_u32 s50, 13
	s_cbranch_scc0 .LBB0_188
	s_and_b64 vcc, exec, s[10:11]
	s_cbranch_vccz .LBB0_191
	s_barrier

.LBB0_311:
	s_add_u32 s35, s26, s34
	s_addc_u32 s40, s27, 0
	s_add_u32 s38, s35, 0x100
	s_addc_u32 s39, s40, 0
	s_and_b64 s[36:37], s[30:31], exec
	s_cselect_b32 s37, s5, s39
	s_cselect_b32 s36, s17, s38
	s_add_u32 s34, s24, s34
	s_addc_u32 s38, s25, 0
	s_add_u32 s34, s34, 0x100
	s_addc_u32 s38, s38, 0
	s_add_i32 s70, 0, 0x10000
	s_and_b64 s[30:31], s[30:31], exec
	s_cselect_b32 s39, s15, s38
	s_cselect_b32 s38, s23, s34
	s_add_i32 s31, 0, 0x14000
	s_add_u32 s42, s35, 0x100080
	s_addc_u32 s43, s40, 0
	s_add_i32 s69, s70, s50
	s_add_i32 m0, s51, 0xc000
	s_add_i32 s72, s51, 0xe000
	s_add_i32 s66, s69, 0x2000
	s_add_u32 s40, s38, 0x10000
	v_add_u32_e32 v146, s70, v154
	v_add_u32_e32 v164, s31, v154
	s_addc_u32 s41, s39, 0
	s_add_i32 s68, s31, s50
	ds_read_b128 v[134:137], v146
	ds_read_b128 v[138:141], v146 offset:1024
	ds_read_b128 v[142:145], v146 offset:2048
	ds_read_b128 v[146:149], v146 offset:3072
	ds_read_b128 v[150:153], v164
	ds_read_b128 v[156:159], v164 offset:1024
	ds_read_b128 v[160:163], v164 offset:2048
	ds_read_b128 v[164:167], v164 offset:3072
	s_add_i32 s67, s68, 0x2000
	s_add_i32 s65, 0, 0x18000
	s_add_i32 s64, 0, 0x1c000
	s_add_u32 s34, s36, 0x100000
	s_addc_u32 s35, s37, 0
	s_add_i32 s63, s65, s50
	s_add_i32 s62, s63, 0x2000
	s_add_u32 s30, s38, 0x10080
	s_addc_u32 s31, s39, 0
	s_add_i32 s71, s64, s50
	s_add_i32 s70, s71, 0x2000
	v_lshl_add_u64 v[200:201], s[42:43], 0, v[128:129]
	ds_read_b128 v[168:171], v155
	ds_read_b128 v[172:175], v155 offset:1024
	ds_read_b128 v[176:179], v155 offset:2048
	ds_read_b128 v[180:183], v155 offset:3072
	ds_read_b128 v[184:187], v155 offset:4096
	ds_read_b128 v[188:191], v155 offset:5120
	ds_read_b128 v[192:195], v155 offset:6144
	ds_read_b128 v[196:199], v155 offset:7168
	global_load_lds_dwordx4 v[200:201], off
	v_lshl_add_u64 v[200:201], s[42:43], 0, v[130:131]
	s_mov_b32 m0, s72
	s_nop 0
	global_load_lds_dwordx4 v[200:201], off
	s_waitcnt vmcnt(8)
	s_waitcnt lgkmcnt(0)
	s_barrier
	s_setprio 1
	s_waitcnt lgkmcnt(0)
	v_mfma_f32_16x16x32_bf16 v[124:127], v[134:137], v[168:171], v[124:127]
	v_mfma_f32_16x16x32_bf16 v[120:123], v[142:145], v[168:171], v[120:123]
	v_mfma_f32_16x16x32_bf16 v[108:111], v[134:137], v[176:179], v[108:111]
	v_mfma_f32_16x16x32_bf16 v[104:107], v[142:145], v[176:179], v[104:107]
	v_mfma_f32_16x16x32_bf16 v[92:95], v[134:137], v[184:187], v[92:95]
	v_mfma_f32_16x16x32_bf16 v[88:91], v[142:145], v[184:187], v[88:91]
	v_mfma_f32_16x16x32_bf16 v[76:79], v[134:137], v[192:195], v[76:79]
	v_mfma_f32_16x16x32_bf16 v[72:75], v[142:145], v[192:195], v[72:75]
	v_mfma_f32_16x16x32_bf16 v[124:127], v[138:141], v[172:175], v[124:127]
	v_mfma_f32_16x16x32_bf16 v[120:123], v[146:149], v[172:175], v[120:123]
	v_mfma_f32_16x16x32_bf16 v[108:111], v[138:141], v[180:183], v[108:111]
	v_mfma_f32_16x16x32_bf16 v[104:107], v[146:149], v[180:183], v[104:107]
	v_mfma_f32_16x16x32_bf16 v[92:95], v[138:141], v[188:191], v[92:95]
	v_mfma_f32_16x16x32_bf16 v[88:91], v[146:149], v[188:191], v[88:91]
	v_mfma_f32_16x16x32_bf16 v[76:79], v[138:141], v[196:199], v[76:79]
	v_mfma_f32_16x16x32_bf16 v[72:75], v[146:149], v[196:199], v[72:75]
	v_mfma_f32_16x16x32_bf16 v[116:119], v[150:153], v[168:171], v[116:119]
	v_mfma_f32_16x16x32_bf16 v[112:115], v[160:163], v[168:171], v[112:115]
	v_mfma_f32_16x16x32_bf16 v[100:103], v[150:153], v[176:179], v[100:103]
	v_mfma_f32_16x16x32_bf16 v[96:99], v[160:163], v[176:179], v[96:99]
	v_mfma_f32_16x16x32_bf16 v[84:87], v[150:153], v[184:187], v[84:87]
	v_mfma_f32_16x16x32_bf16 v[80:83], v[160:163], v[184:187], v[80:83]
	v_mfma_f32_16x16x32_bf16 v[68:71], v[150:153], v[192:195], v[68:71]
	v_mfma_f32_16x16x32_bf16 v[64:67], v[160:163], v[192:195], v[64:67]
	v_mfma_f32_16x16x32_bf16 v[116:119], v[156:159], v[172:175], v[116:119]
	v_mfma_f32_16x16x32_bf16 v[112:115], v[164:167], v[172:175], v[112:115]
	v_mfma_f32_16x16x32_bf16 v[100:103], v[156:159], v[180:183], v[100:103]
	v_mfma_f32_16x16x32_bf16 v[96:99], v[164:167], v[180:183], v[96:99]
	v_mfma_f32_16x16x32_bf16 v[84:87], v[156:159], v[188:191], v[84:87]
	v_mfma_f32_16x16x32_bf16 v[80:83], v[164:167], v[188:191], v[80:83]
	v_mfma_f32_16x16x32_bf16 v[68:71], v[156:159], v[196:199], v[68:71]
	v_mfma_f32_16x16x32_bf16 v[64:67], v[164:167], v[196:199], v[64:67]
	s_setprio 0
	s_barrier
	s_mov_b32 m0, s69
	v_lshl_add_u64 v[200:201], s[38:39], 0, v[232:233]
	ds_read_b128 v[168:171], v155 offset:16384
	ds_read_b128 v[172:175], v155 offset:17408
	ds_read_b128 v[176:179], v155 offset:18432
	ds_read_b128 v[180:183], v155 offset:19456
	ds_read_b128 v[184:187], v155 offset:20480
	ds_read_b128 v[188:191], v155 offset:21504
	ds_read_b128 v[192:195], v155 offset:22528
	ds_read_b128 v[196:199], v155 offset:23552
	global_load_lds_dwordx4 v[200:201], off
	v_lshl_add_u64 v[202:203], s[38:39], 0, v[132:133]
	s_mov_b32 m0, s66
	v_lshl_add_u64 v[204:205], s[40:41], 0, v[232:233]
	global_load_lds_dwordx4 v[202:203], off
	s_mov_b32 m0, s68
	v_lshl_add_u64 v[206:207], s[36:37], 0, v[130:131]
	global_load_lds_dwordx4 v[204:205], off
	v_lshl_add_u64 v[204:205], s[40:41], 0, v[132:133]
	s_mov_b32 m0, s67
	s_nop 0
	global_load_lds_dwordx4 v[204:205], off
	v_lshl_add_u64 v[204:205], s[36:37], 0, v[128:129]
	s_mov_b32 m0, s51
	s_nop 0
	global_load_lds_dwordx4 v[204:205], off
	s_mov_b32 m0, s52
	s_nop 0
	global_load_lds_dwordx4 v[206:207], off
	s_waitcnt vmcnt(8)
	s_waitcnt lgkmcnt(0)
	s_barrier
	s_setprio 1
	s_waitcnt lgkmcnt(0)
	v_mfma_f32_16x16x32_bf16 v[60:63], v[134:137], v[168:171], v[60:63]
	v_mfma_f32_16x16x32_bf16 v[56:59], v[142:145], v[168:171], v[56:59]
	v_mfma_f32_16x16x32_bf16 v[44:47], v[134:137], v[176:179], v[44:47]
	v_mfma_f32_16x16x32_bf16 v[40:43], v[142:145], v[176:179], v[40:43]
	v_mfma_f32_16x16x32_bf16 v[28:31], v[134:137], v[184:187], v[28:31]
	v_mfma_f32_16x16x32_bf16 v[24:27], v[142:145], v[184:187], v[24:27]
	v_mfma_f32_16x16x32_bf16 v[12:15], v[134:137], v[192:195], v[12:15]
	v_mfma_f32_16x16x32_bf16 v[8:11], v[142:145], v[192:195], v[8:11]
	v_mfma_f32_16x16x32_bf16 v[60:63], v[138:141], v[172:175], v[60:63]
	v_mfma_f32_16x16x32_bf16 v[56:59], v[146:149], v[172:175], v[56:59]
	v_mfma_f32_16x16x32_bf16 v[44:47], v[138:141], v[180:183], v[44:47]
	v_mfma_f32_16x16x32_bf16 v[40:43], v[146:149], v[180:183], v[40:43]
	v_mfma_f32_16x16x32_bf16 v[28:31], v[138:141], v[188:191], v[28:31]
	v_mfma_f32_16x16x32_bf16 v[24:27], v[146:149], v[188:191], v[24:27]
	v_mfma_f32_16x16x32_bf16 v[12:15], v[138:141], v[196:199], v[12:15]
	v_mfma_f32_16x16x32_bf16 v[8:11], v[146:149], v[196:199], v[8:11]
	v_mfma_f32_16x16x32_bf16 v[52:55], v[150:153], v[168:171], v[52:55]
	v_mfma_f32_16x16x32_bf16 v[48:51], v[160:163], v[168:171], v[48:51]
	v_mfma_f32_16x16x32_bf16 v[36:39], v[150:153], v[176:179], v[36:39]
	v_mfma_f32_16x16x32_bf16 v[32:35], v[160:163], v[176:179], v[32:35]
	v_mfma_f32_16x16x32_bf16 v[20:23], v[150:153], v[184:187], v[20:23]
	v_mfma_f32_16x16x32_bf16 v[16:19], v[160:163], v[184:187], v[16:19]
	v_mfma_f32_16x16x32_bf16 v[4:7], v[150:153], v[192:195], v[4:7]
	v_mfma_f32_16x16x32_bf16 v[0:3], v[160:163], v[192:195], v[0:3]
	v_mfma_f32_16x16x32_bf16 v[52:55], v[156:159], v[172:175], v[52:55]
	v_mfma_f32_16x16x32_bf16 v[48:51], v[164:167], v[172:175], v[48:51]
	v_mfma_f32_16x16x32_bf16 v[36:39], v[156:159], v[180:183], v[36:39]
	v_mfma_f32_16x16x32_bf16 v[32:35], v[164:167], v[180:183], v[32:35]
	v_mfma_f32_16x16x32_bf16 v[20:23], v[156:159], v[188:191], v[20:23]
	v_mfma_f32_16x16x32_bf16 v[16:19], v[164:167], v[188:191], v[16:19]
	v_mfma_f32_16x16x32_bf16 v[4:7], v[156:159], v[196:199], v[4:7]
	v_mfma_f32_16x16x32_bf16 v[0:3], v[164:167], v[196:199], v[0:3]
	s_setprio 0
	s_barrier
	v_add_u32_e32 v146, s65, v154
	v_add_u32_e32 v164, s64, v154
	ds_read_b128 v[134:137], v146
	ds_read_b128 v[138:141], v146 offset:1024
	ds_read_b128 v[142:145], v146 offset:2048
	ds_read_b128 v[146:149], v146 offset:3072
	ds_read_b128 v[150:153], v164
	ds_read_b128 v[156:159], v164 offset:1024
	ds_read_b128 v[160:163], v164 offset:2048
	ds_read_b128 v[164:167], v164 offset:3072
	s_mov_b32 m0, s53
	v_lshl_add_u64 v[208:209], s[34:35], 0, v[128:129]
	ds_read_b128 v[168:171], v155 offset:32768
	ds_read_b128 v[172:175], v155 offset:33792
	ds_read_b128 v[176:179], v155 offset:34816
	ds_read_b128 v[180:183], v155 offset:35840
	ds_read_b128 v[184:187], v155 offset:36864
	ds_read_b128 v[188:191], v155 offset:37888
	ds_read_b128 v[192:195], v155 offset:38912
	ds_read_b128 v[196:199], v155 offset:39936
	global_load_lds_dwordx4 v[208:209], off
	v_lshl_add_u64 v[208:209], s[34:35], 0, v[130:131]
	s_mov_b32 m0, s54
	s_nop 0
	global_load_lds_dwordx4 v[208:209], off
	s_waitcnt vmcnt(8)
	s_waitcnt lgkmcnt(0)
	s_barrier
	s_setprio 1
	s_waitcnt lgkmcnt(0)
	v_mfma_f32_16x16x32_bf16 v[124:127], v[134:137], v[168:171], v[124:127]
	v_mfma_f32_16x16x32_bf16 v[120:123], v[142:145], v[168:171], v[120:123]
	v_mfma_f32_16x16x32_bf16 v[108:111], v[134:137], v[176:179], v[108:111]
	v_mfma_f32_16x16x32_bf16 v[104:107], v[142:145], v[176:179], v[104:107]
	v_mfma_f32_16x16x32_bf16 v[92:95], v[134:137], v[184:187], v[92:95]
	v_mfma_f32_16x16x32_bf16 v[88:91], v[142:145], v[184:187], v[88:91]
	v_mfma_f32_16x16x32_bf16 v[76:79], v[134:137], v[192:195], v[76:79]
	v_mfma_f32_16x16x32_bf16 v[72:75], v[142:145], v[192:195], v[72:75]
	v_mfma_f32_16x16x32_bf16 v[124:127], v[138:141], v[172:175], v[124:127]
	v_mfma_f32_16x16x32_bf16 v[120:123], v[146:149], v[172:175], v[120:123]
	v_mfma_f32_16x16x32_bf16 v[108:111], v[138:141], v[180:183], v[108:111]
	v_mfma_f32_16x16x32_bf16 v[104:107], v[146:149], v[180:183], v[104:107]
	v_mfma_f32_16x16x32_bf16 v[92:95], v[138:141], v[188:191], v[92:95]
	v_mfma_f32_16x16x32_bf16 v[88:91], v[146:149], v[188:191], v[88:91]
	v_mfma_f32_16x16x32_bf16 v[76:79], v[138:141], v[196:199], v[76:79]
	v_mfma_f32_16x16x32_bf16 v[72:75], v[146:149], v[196:199], v[72:75]
	v_mfma_f32_16x16x32_bf16 v[116:119], v[150:153], v[168:171], v[116:119]
	v_mfma_f32_16x16x32_bf16 v[112:115], v[160:163], v[168:171], v[112:115]
	v_mfma_f32_16x16x32_bf16 v[100:103], v[150:153], v[176:179], v[100:103]
	v_mfma_f32_16x16x32_bf16 v[96:99], v[160:163], v[176:179], v[96:99]
	v_mfma_f32_16x16x32_bf16 v[84:87], v[150:153], v[184:187], v[84:87]
	v_mfma_f32_16x16x32_bf16 v[80:83], v[160:163], v[184:187], v[80:83]
	v_mfma_f32_16x16x32_bf16 v[68:71], v[150:153], v[192:195], v[68:71]
	v_mfma_f32_16x16x32_bf16 v[64:67], v[160:163], v[192:195], v[64:67]
	v_mfma_f32_16x16x32_bf16 v[116:119], v[156:159], v[172:175], v[116:119]
	v_mfma_f32_16x16x32_bf16 v[112:115], v[164:167], v[172:175], v[112:115]
	v_mfma_f32_16x16x32_bf16 v[100:103], v[156:159], v[180:183], v[100:103]
	v_mfma_f32_16x16x32_bf16 v[96:99], v[164:167], v[180:183], v[96:99]
	v_mfma_f32_16x16x32_bf16 v[84:87], v[156:159], v[188:191], v[84:87]
	v_mfma_f32_16x16x32_bf16 v[80:83], v[164:167], v[188:191], v[80:83]
	v_mfma_f32_16x16x32_bf16 v[68:71], v[156:159], v[196:199], v[68:71]
	v_mfma_f32_16x16x32_bf16 v[64:67], v[164:167], v[196:199], v[64:67]
	s_setprio 0
	s_barrier
	s_mov_b32 m0, s63
	v_lshl_add_u64 v[200:201], v[200:201], 0, s[94:95]
	ds_read_b128 v[168:171], v155 offset:49152
	ds_read_b128 v[172:175], v155 offset:50176
	ds_read_b128 v[176:179], v155 offset:51200
	ds_read_b128 v[180:183], v155 offset:52224
	ds_read_b128 v[184:187], v155 offset:53248
	ds_read_b128 v[188:191], v155 offset:54272
	ds_read_b128 v[192:195], v155 offset:55296
	ds_read_b128 v[196:199], v155 offset:56320
	global_load_lds_dwordx4 v[200:201], off
	v_lshl_add_u64 v[200:201], v[202:203], 0, s[94:95]
	s_mov_b32 m0, s62
	s_nop 0
	global_load_lds_dwordx4 v[200:201], off
	v_lshl_add_u64 v[200:201], s[30:31], 0, v[232:233]
	s_mov_b32 m0, s71
	s_nop 0
	global_load_lds_dwordx4 v[200:201], off
	v_lshl_add_u64 v[200:201], s[30:31], 0, v[132:133]
	s_mov_b32 m0, s70
	s_nop 0
	global_load_lds_dwordx4 v[200:201], off
	v_lshl_add_u64 v[200:201], v[204:205], 0, s[94:95]
	s_mov_b32 m0, s57
	s_nop 0
	global_load_lds_dwordx4 v[200:201], off
	v_lshl_add_u64 v[200:201], v[206:207], 0, s[94:95]
	s_mov_b32 m0, s58
	s_nop 0
	global_load_lds_dwordx4 v[200:201], off
	s_waitcnt vmcnt(8)
	s_waitcnt lgkmcnt(0)
	s_barrier
	s_setprio 1
	s_waitcnt lgkmcnt(0)
	v_mfma_f32_16x16x32_bf16 v[60:63], v[134:137], v[168:171], v[60:63]
	v_mfma_f32_16x16x32_bf16 v[56:59], v[142:145], v[168:171], v[56:59]
	v_mfma_f32_16x16x32_bf16 v[44:47], v[134:137], v[176:179], v[44:47]
	v_mfma_f32_16x16x32_bf16 v[40:43], v[142:145], v[176:179], v[40:43]
	v_mfma_f32_16x16x32_bf16 v[28:31], v[134:137], v[184:187], v[28:31]
	v_mfma_f32_16x16x32_bf16 v[24:27], v[142:145], v[184:187], v[24:27]
	v_mfma_f32_16x16x32_bf16 v[12:15], v[134:137], v[192:195], v[12:15]
	v_mfma_f32_16x16x32_bf16 v[8:11], v[142:145], v[192:195], v[8:11]
	v_mfma_f32_16x16x32_bf16 v[60:63], v[138:141], v[172:175], v[60:63]
	v_mfma_f32_16x16x32_bf16 v[56:59], v[146:149], v[172:175], v[56:59]
	v_mfma_f32_16x16x32_bf16 v[44:47], v[138:141], v[180:183], v[44:47]
	v_mfma_f32_16x16x32_bf16 v[40:43], v[146:149], v[180:183], v[40:43]
	v_mfma_f32_16x16x32_bf16 v[28:31], v[138:141], v[188:191], v[28:31]
	v_mfma_f32_16x16x32_bf16 v[24:27], v[146:149], v[188:191], v[24:27]
	v_mfma_f32_16x16x32_bf16 v[12:15], v[138:141], v[196:199], v[12:15]
	v_mfma_f32_16x16x32_bf16 v[8:11], v[146:149], v[196:199], v[8:11]
	v_mfma_f32_16x16x32_bf16 v[52:55], v[150:153], v[168:171], v[52:55]
	v_mfma_f32_16x16x32_bf16 v[48:51], v[160:163], v[168:171], v[48:51]
	v_mfma_f32_16x16x32_bf16 v[36:39], v[150:153], v[176:179], v[36:39]
	v_mfma_f32_16x16x32_bf16 v[32:35], v[160:163], v[176:179], v[32:35]
	v_mfma_f32_16x16x32_bf16 v[20:23], v[150:153], v[184:187], v[20:23]
	v_mfma_f32_16x16x32_bf16 v[16:19], v[160:163], v[184:187], v[16:19]
	v_mfma_f32_16x16x32_bf16 v[4:7], v[150:153], v[192:195], v[4:7]
	v_mfma_f32_16x16x32_bf16 v[0:3], v[160:163], v[192:195], v[0:3]
	v_mfma_f32_16x16x32_bf16 v[52:55], v[156:159], v[172:175], v[52:55]
	v_mfma_f32_16x16x32_bf16 v[48:51], v[164:167], v[172:175], v[48:51]
	v_mfma_f32_16x16x32_bf16 v[36:39], v[156:159], v[180:183], v[36:39]
	v_mfma_f32_16x16x32_bf16 v[32:35], v[164:167], v[180:183], v[32:35]
	v_mfma_f32_16x16x32_bf16 v[20:23], v[156:159], v[188:191], v[20:23]
	v_mfma_f32_16x16x32_bf16 v[16:19], v[164:167], v[188:191], v[16:19]
	v_mfma_f32_16x16x32_bf16 v[4:7], v[156:159], v[196:199], v[4:7]
	v_mfma_f32_16x16x32_bf16 v[0:3], v[164:167], v[196:199], v[0:3]
	s_setprio 0
	s_barrier
	s_movk_i32 s34, 0x100
	s_andn2_b64 vcc, exec, s[28:29]
	s_mov_b64 s[30:31], -1
	s_mov_b64 s[28:29], 0
	s_cbranch_vccz .LBB0_311
	s_and_b64 vcc, exec, s[12:13]
	s_cbranch_vccz .LBB0_314
	s_barrier

.LBB0_369:
	s_add_u32 s35, s26, s34
	s_addc_u32 s40, s27, 0
	s_add_u32 s38, s35, 0x100
	s_addc_u32 s39, s40, 0
	s_and_b64 s[36:37], s[30:31], exec
	s_cselect_b32 s37, s5, s39
	s_cselect_b32 s36, s17, s38
	s_add_u32 s34, s24, s34
	s_addc_u32 s38, s25, 0
	s_add_u32 s34, s34, 0x100
	s_addc_u32 s38, s38, 0
	s_add_i32 s70, 0, 0x10000
	s_and_b64 s[30:31], s[30:31], exec
	s_cselect_b32 s39, s15, s38
	s_cselect_b32 s38, s23, s34
	s_add_i32 s31, 0, 0x14000
	s_add_u32 s42, s35, 0x100080
	s_addc_u32 s43, s40, 0
	s_add_i32 s69, s70, s50
	s_add_i32 m0, s51, 0xc000
	s_add_i32 s72, s51, 0xe000
	s_add_i32 s66, s69, 0x2000
	s_add_u32 s40, s38, 0x10000
	v_add_u32_e32 v146, s70, v168
	v_add_u32_e32 v162, s31, v168
	s_addc_u32 s41, s39, 0
	s_add_i32 s68, s31, s50
	ds_read_b128 v[134:137], v146
	ds_read_b128 v[138:141], v146 offset:1024
	ds_read_b128 v[142:145], v146 offset:2048
	ds_read_b128 v[146:149], v146 offset:3072
	ds_read_b128 v[150:153], v162
	ds_read_b128 v[154:157], v162 offset:1024
	ds_read_b128 v[158:161], v162 offset:2048
	ds_read_b128 v[162:165], v162 offset:3072
	s_add_i32 s67, s68, 0x2000
	s_add_i32 s65, 0, 0x18000
	s_add_i32 s64, 0, 0x1c000
	s_add_u32 s34, s36, 0x100000
	s_addc_u32 s35, s37, 0
	s_add_i32 s63, s65, s50
	s_add_i32 s62, s63, 0x2000
	s_add_u32 s30, s38, 0x10080
	s_addc_u32 s31, s39, 0
	s_add_i32 s71, s64, s50
	s_add_i32 s70, s71, 0x2000
	v_lshl_add_u64 v[166:167], s[42:43], 0, v[128:129]
	ds_read_b128 v[170:173], v169
	ds_read_b128 v[174:177], v169 offset:1024
	ds_read_b128 v[178:181], v169 offset:2048
	ds_read_b128 v[182:185], v169 offset:3072
	ds_read_b128 v[186:189], v169 offset:4096
	ds_read_b128 v[190:193], v169 offset:5120
	ds_read_b128 v[194:197], v169 offset:6144
	ds_read_b128 v[198:201], v169 offset:7168
	global_load_lds_dwordx4 v[166:167], off
	v_lshl_add_u64 v[166:167], s[42:43], 0, v[130:131]
	s_mov_b32 m0, s72
	s_nop 0
	global_load_lds_dwordx4 v[166:167], off
	s_waitcnt vmcnt(8)
	s_waitcnt lgkmcnt(0)
	s_barrier
	s_setprio 1
	s_waitcnt lgkmcnt(0)
	v_mfma_f32_16x16x32_bf16 v[124:127], v[134:137], v[170:173], v[124:127]
	v_mfma_f32_16x16x32_bf16 v[120:123], v[142:145], v[170:173], v[120:123]
	v_mfma_f32_16x16x32_bf16 v[108:111], v[134:137], v[178:181], v[108:111]
	v_mfma_f32_16x16x32_bf16 v[104:107], v[142:145], v[178:181], v[104:107]
	v_mfma_f32_16x16x32_bf16 v[92:95], v[134:137], v[186:189], v[92:95]
	v_mfma_f32_16x16x32_bf16 v[88:91], v[142:145], v[186:189], v[88:91]
	v_mfma_f32_16x16x32_bf16 v[76:79], v[134:137], v[194:197], v[76:79]
	v_mfma_f32_16x16x32_bf16 v[72:75], v[142:145], v[194:197], v[72:75]
	v_mfma_f32_16x16x32_bf16 v[124:127], v[138:141], v[174:177], v[124:127]
	v_mfma_f32_16x16x32_bf16 v[120:123], v[146:149], v[174:177], v[120:123]
	v_mfma_f32_16x16x32_bf16 v[108:111], v[138:141], v[182:185], v[108:111]
	v_mfma_f32_16x16x32_bf16 v[104:107], v[146:149], v[182:185], v[104:107]
	v_mfma_f32_16x16x32_bf16 v[92:95], v[138:141], v[190:193], v[92:95]
	v_mfma_f32_16x16x32_bf16 v[88:91], v[146:149], v[190:193], v[88:91]
	v_mfma_f32_16x16x32_bf16 v[76:79], v[138:141], v[198:201], v[76:79]
	v_mfma_f32_16x16x32_bf16 v[72:75], v[146:149], v[198:201], v[72:75]
	v_mfma_f32_16x16x32_bf16 v[116:119], v[150:153], v[170:173], v[116:119]
	v_mfma_f32_16x16x32_bf16 v[112:115], v[158:161], v[170:173], v[112:115]
	v_mfma_f32_16x16x32_bf16 v[100:103], v[150:153], v[178:181], v[100:103]
	v_mfma_f32_16x16x32_bf16 v[96:99], v[158:161], v[178:181], v[96:99]
	v_mfma_f32_16x16x32_bf16 v[84:87], v[150:153], v[186:189], v[84:87]
	v_mfma_f32_16x16x32_bf16 v[80:83], v[158:161], v[186:189], v[80:83]
	v_mfma_f32_16x16x32_bf16 v[68:71], v[150:153], v[194:197], v[68:71]
	v_mfma_f32_16x16x32_bf16 v[64:67], v[158:161], v[194:197], v[64:67]
	v_mfma_f32_16x16x32_bf16 v[116:119], v[154:157], v[174:177], v[116:119]
	v_mfma_f32_16x16x32_bf16 v[112:115], v[162:165], v[174:177], v[112:115]
	v_mfma_f32_16x16x32_bf16 v[100:103], v[154:157], v[182:185], v[100:103]
	v_mfma_f32_16x16x32_bf16 v[96:99], v[162:165], v[182:185], v[96:99]
	v_mfma_f32_16x16x32_bf16 v[84:87], v[154:157], v[190:193], v[84:87]
	v_mfma_f32_16x16x32_bf16 v[80:83], v[162:165], v[190:193], v[80:83]
	v_mfma_f32_16x16x32_bf16 v[68:71], v[154:157], v[198:201], v[68:71]
	v_mfma_f32_16x16x32_bf16 v[64:67], v[162:165], v[198:201], v[64:67]
	s_setprio 0
	s_barrier
	s_mov_b32 m0, s69
	v_lshl_add_u64 v[166:167], s[38:39], 0, v[232:233]
	ds_read_b128 v[170:173], v169 offset:16384
	ds_read_b128 v[174:177], v169 offset:17408
	ds_read_b128 v[178:181], v169 offset:18432
	ds_read_b128 v[182:185], v169 offset:19456
	ds_read_b128 v[186:189], v169 offset:20480
	ds_read_b128 v[190:193], v169 offset:21504
	ds_read_b128 v[194:197], v169 offset:22528
	ds_read_b128 v[198:201], v169 offset:23552
	global_load_lds_dwordx4 v[166:167], off
	v_lshl_add_u64 v[202:203], s[38:39], 0, v[132:133]
	s_mov_b32 m0, s66
	v_lshl_add_u64 v[204:205], s[40:41], 0, v[232:233]
	global_load_lds_dwordx4 v[202:203], off
	s_mov_b32 m0, s68
	v_lshl_add_u64 v[206:207], s[36:37], 0, v[130:131]
	global_load_lds_dwordx4 v[204:205], off
	v_lshl_add_u64 v[204:205], s[40:41], 0, v[132:133]
	s_mov_b32 m0, s67
	s_nop 0
	global_load_lds_dwordx4 v[204:205], off
	v_lshl_add_u64 v[204:205], s[36:37], 0, v[128:129]
	s_mov_b32 m0, s51
	s_nop 0
	global_load_lds_dwordx4 v[204:205], off
	s_mov_b32 m0, s52
	s_nop 0
	global_load_lds_dwordx4 v[206:207], off
	s_waitcnt vmcnt(8)
	s_waitcnt lgkmcnt(0)
	s_barrier
	s_setprio 1
	s_waitcnt lgkmcnt(0)
	v_mfma_f32_16x16x32_bf16 v[60:63], v[134:137], v[170:173], v[60:63]
	v_mfma_f32_16x16x32_bf16 v[56:59], v[142:145], v[170:173], v[56:59]
	v_mfma_f32_16x16x32_bf16 v[44:47], v[134:137], v[178:181], v[44:47]
	v_mfma_f32_16x16x32_bf16 v[40:43], v[142:145], v[178:181], v[40:43]
	v_mfma_f32_16x16x32_bf16 v[28:31], v[134:137], v[186:189], v[28:31]
	v_mfma_f32_16x16x32_bf16 v[24:27], v[142:145], v[186:189], v[24:27]
	v_mfma_f32_16x16x32_bf16 v[12:15], v[134:137], v[194:197], v[12:15]
	v_mfma_f32_16x16x32_bf16 v[8:11], v[142:145], v[194:197], v[8:11]
	v_mfma_f32_16x16x32_bf16 v[60:63], v[138:141], v[174:177], v[60:63]
	v_mfma_f32_16x16x32_bf16 v[56:59], v[146:149], v[174:177], v[56:59]
	v_mfma_f32_16x16x32_bf16 v[44:47], v[138:141], v[182:185], v[44:47]
	v_mfma_f32_16x16x32_bf16 v[40:43], v[146:149], v[182:185], v[40:43]
	v_mfma_f32_16x16x32_bf16 v[28:31], v[138:141], v[190:193], v[28:31]
	v_mfma_f32_16x16x32_bf16 v[24:27], v[146:149], v[190:193], v[24:27]
	v_mfma_f32_16x16x32_bf16 v[12:15], v[138:141], v[198:201], v[12:15]
	v_mfma_f32_16x16x32_bf16 v[8:11], v[146:149], v[198:201], v[8:11]
	v_mfma_f32_16x16x32_bf16 v[52:55], v[150:153], v[170:173], v[52:55]
	v_mfma_f32_16x16x32_bf16 v[48:51], v[158:161], v[170:173], v[48:51]
	v_mfma_f32_16x16x32_bf16 v[36:39], v[150:153], v[178:181], v[36:39]
	v_mfma_f32_16x16x32_bf16 v[32:35], v[158:161], v[178:181], v[32:35]
	v_mfma_f32_16x16x32_bf16 v[20:23], v[150:153], v[186:189], v[20:23]
	v_mfma_f32_16x16x32_bf16 v[16:19], v[158:161], v[186:189], v[16:19]
	v_mfma_f32_16x16x32_bf16 v[4:7], v[150:153], v[194:197], v[4:7]
	v_mfma_f32_16x16x32_bf16 v[0:3], v[158:161], v[194:197], v[0:3]
	v_mfma_f32_16x16x32_bf16 v[52:55], v[154:157], v[174:177], v[52:55]
	v_mfma_f32_16x16x32_bf16 v[48:51], v[162:165], v[174:177], v[48:51]
	v_mfma_f32_16x16x32_bf16 v[36:39], v[154:157], v[182:185], v[36:39]
	v_mfma_f32_16x16x32_bf16 v[32:35], v[162:165], v[182:185], v[32:35]
	v_mfma_f32_16x16x32_bf16 v[20:23], v[154:157], v[190:193], v[20:23]
	v_mfma_f32_16x16x32_bf16 v[16:19], v[162:165], v[190:193], v[16:19]
	v_mfma_f32_16x16x32_bf16 v[4:7], v[154:157], v[198:201], v[4:7]
	v_mfma_f32_16x16x32_bf16 v[0:3], v[162:165], v[198:201], v[0:3]
	s_setprio 0
	s_barrier
	v_add_u32_e32 v146, s65, v168
	v_add_u32_e32 v162, s64, v168
	ds_read_b128 v[134:137], v146
	ds_read_b128 v[138:141], v146 offset:1024
	ds_read_b128 v[142:145], v146 offset:2048
	ds_read_b128 v[146:149], v146 offset:3072
	ds_read_b128 v[150:153], v162
	ds_read_b128 v[154:157], v162 offset:1024
	ds_read_b128 v[158:161], v162 offset:2048
	ds_read_b128 v[162:165], v162 offset:3072
	s_mov_b32 m0, s53
	v_lshl_add_u64 v[208:209], s[34:35], 0, v[128:129]
	ds_read_b128 v[170:173], v169 offset:32768
	ds_read_b128 v[174:177], v169 offset:33792
	ds_read_b128 v[178:181], v169 offset:34816
	ds_read_b128 v[182:185], v169 offset:35840
	ds_read_b128 v[186:189], v169 offset:36864
	ds_read_b128 v[190:193], v169 offset:37888
	ds_read_b128 v[194:197], v169 offset:38912
	ds_read_b128 v[198:201], v169 offset:39936
	global_load_lds_dwordx4 v[208:209], off
	v_lshl_add_u64 v[208:209], s[34:35], 0, v[130:131]
	s_mov_b32 m0, s54
	s_nop 0
	global_load_lds_dwordx4 v[208:209], off
	s_waitcnt vmcnt(8)
	s_waitcnt lgkmcnt(0)
	s_barrier
	s_setprio 1
	s_waitcnt lgkmcnt(0)
	v_mfma_f32_16x16x32_bf16 v[124:127], v[134:137], v[170:173], v[124:127]
	v_mfma_f32_16x16x32_bf16 v[120:123], v[142:145], v[170:173], v[120:123]
	v_mfma_f32_16x16x32_bf16 v[108:111], v[134:137], v[178:181], v[108:111]
	v_mfma_f32_16x16x32_bf16 v[104:107], v[142:145], v[178:181], v[104:107]
	v_mfma_f32_16x16x32_bf16 v[92:95], v[134:137], v[186:189], v[92:95]
	v_mfma_f32_16x16x32_bf16 v[88:91], v[142:145], v[186:189], v[88:91]
	v_mfma_f32_16x16x32_bf16 v[76:79], v[134:137], v[194:197], v[76:79]
	v_mfma_f32_16x16x32_bf16 v[72:75], v[142:145], v[194:197], v[72:75]
	v_mfma_f32_16x16x32_bf16 v[124:127], v[138:141], v[174:177], v[124:127]
	v_mfma_f32_16x16x32_bf16 v[120:123], v[146:149], v[174:177], v[120:123]
	v_mfma_f32_16x16x32_bf16 v[108:111], v[138:141], v[182:185], v[108:111]
	v_mfma_f32_16x16x32_bf16 v[104:107], v[146:149], v[182:185], v[104:107]
	v_mfma_f32_16x16x32_bf16 v[92:95], v[138:141], v[190:193], v[92:95]
	v_mfma_f32_16x16x32_bf16 v[88:91], v[146:149], v[190:193], v[88:91]
	v_mfma_f32_16x16x32_bf16 v[76:79], v[138:141], v[198:201], v[76:79]
	v_mfma_f32_16x16x32_bf16 v[72:75], v[146:149], v[198:201], v[72:75]
	v_mfma_f32_16x16x32_bf16 v[116:119], v[150:153], v[170:173], v[116:119]
	v_mfma_f32_16x16x32_bf16 v[112:115], v[158:161], v[170:173], v[112:115]
	v_mfma_f32_16x16x32_bf16 v[100:103], v[150:153], v[178:181], v[100:103]
	v_mfma_f32_16x16x32_bf16 v[96:99], v[158:161], v[178:181], v[96:99]
	v_mfma_f32_16x16x32_bf16 v[84:87], v[150:153], v[186:189], v[84:87]
	v_mfma_f32_16x16x32_bf16 v[80:83], v[158:161], v[186:189], v[80:83]
	v_mfma_f32_16x16x32_bf16 v[68:71], v[150:153], v[194:197], v[68:71]
	v_mfma_f32_16x16x32_bf16 v[64:67], v[158:161], v[194:197], v[64:67]
	v_mfma_f32_16x16x32_bf16 v[116:119], v[154:157], v[174:177], v[116:119]
	v_mfma_f32_16x16x32_bf16 v[112:115], v[162:165], v[174:177], v[112:115]
	v_mfma_f32_16x16x32_bf16 v[100:103], v[154:157], v[182:185], v[100:103]
	v_mfma_f32_16x16x32_bf16 v[96:99], v[162:165], v[182:185], v[96:99]
	v_mfma_f32_16x16x32_bf16 v[84:87], v[154:157], v[190:193], v[84:87]
	v_mfma_f32_16x16x32_bf16 v[80:83], v[162:165], v[190:193], v[80:83]
	v_mfma_f32_16x16x32_bf16 v[68:71], v[154:157], v[198:201], v[68:71]
	v_mfma_f32_16x16x32_bf16 v[64:67], v[162:165], v[198:201], v[64:67]
	s_setprio 0
	s_barrier
	s_mov_b32 m0, s63
	v_lshl_add_u64 v[166:167], v[166:167], 0, s[94:95]
	ds_read_b128 v[170:173], v169 offset:49152
	ds_read_b128 v[174:177], v169 offset:50176
	ds_read_b128 v[178:181], v169 offset:51200
	ds_read_b128 v[182:185], v169 offset:52224
	ds_read_b128 v[186:189], v169 offset:53248
	ds_read_b128 v[190:193], v169 offset:54272
	ds_read_b128 v[194:197], v169 offset:55296
	ds_read_b128 v[198:201], v169 offset:56320
	global_load_lds_dwordx4 v[166:167], off
	v_lshl_add_u64 v[166:167], v[202:203], 0, s[94:95]
	s_mov_b32 m0, s62
	s_nop 0
	global_load_lds_dwordx4 v[166:167], off
	v_lshl_add_u64 v[166:167], s[30:31], 0, v[232:233]
	s_mov_b32 m0, s71
	s_nop 0
	global_load_lds_dwordx4 v[166:167], off
	v_lshl_add_u64 v[166:167], s[30:31], 0, v[132:133]
	s_mov_b32 m0, s70
	s_nop 0
	global_load_lds_dwordx4 v[166:167], off
	v_lshl_add_u64 v[166:167], v[204:205], 0, s[94:95]
	s_mov_b32 m0, s57
	s_nop 0
	global_load_lds_dwordx4 v[166:167], off
	v_lshl_add_u64 v[166:167], v[206:207], 0, s[94:95]
	s_mov_b32 m0, s58
	s_nop 0
	global_load_lds_dwordx4 v[166:167], off
	s_waitcnt vmcnt(8)
	s_waitcnt lgkmcnt(0)
	s_barrier
	s_setprio 1
	s_waitcnt lgkmcnt(0)
	v_mfma_f32_16x16x32_bf16 v[60:63], v[134:137], v[170:173], v[60:63]
	v_mfma_f32_16x16x32_bf16 v[56:59], v[142:145], v[170:173], v[56:59]
	v_mfma_f32_16x16x32_bf16 v[44:47], v[134:137], v[178:181], v[44:47]
	v_mfma_f32_16x16x32_bf16 v[40:43], v[142:145], v[178:181], v[40:43]
	v_mfma_f32_16x16x32_bf16 v[28:31], v[134:137], v[186:189], v[28:31]
	v_mfma_f32_16x16x32_bf16 v[24:27], v[142:145], v[186:189], v[24:27]
	v_mfma_f32_16x16x32_bf16 v[12:15], v[134:137], v[194:197], v[12:15]
	v_mfma_f32_16x16x32_bf16 v[8:11], v[142:145], v[194:197], v[8:11]
	v_mfma_f32_16x16x32_bf16 v[60:63], v[138:141], v[174:177], v[60:63]
	v_mfma_f32_16x16x32_bf16 v[56:59], v[146:149], v[174:177], v[56:59]
	v_mfma_f32_16x16x32_bf16 v[44:47], v[138:141], v[182:185], v[44:47]
	v_mfma_f32_16x16x32_bf16 v[40:43], v[146:149], v[182:185], v[40:43]
	v_mfma_f32_16x16x32_bf16 v[28:31], v[138:141], v[190:193], v[28:31]
	v_mfma_f32_16x16x32_bf16 v[24:27], v[146:149], v[190:193], v[24:27]
	v_mfma_f32_16x16x32_bf16 v[12:15], v[138:141], v[198:201], v[12:15]
	v_mfma_f32_16x16x32_bf16 v[8:11], v[146:149], v[198:201], v[8:11]
	v_mfma_f32_16x16x32_bf16 v[52:55], v[150:153], v[170:173], v[52:55]
	v_mfma_f32_16x16x32_bf16 v[48:51], v[158:161], v[170:173], v[48:51]
	v_mfma_f32_16x16x32_bf16 v[36:39], v[150:153], v[178:181], v[36:39]
	v_mfma_f32_16x16x32_bf16 v[32:35], v[158:161], v[178:181], v[32:35]
	v_mfma_f32_16x16x32_bf16 v[20:23], v[150:153], v[186:189], v[20:23]
	v_mfma_f32_16x16x32_bf16 v[16:19], v[158:161], v[186:189], v[16:19]
	v_mfma_f32_16x16x32_bf16 v[4:7], v[150:153], v[194:197], v[4:7]
	v_mfma_f32_16x16x32_bf16 v[0:3], v[158:161], v[194:197], v[0:3]
	v_mfma_f32_16x16x32_bf16 v[52:55], v[154:157], v[174:177], v[52:55]
	v_mfma_f32_16x16x32_bf16 v[48:51], v[162:165], v[174:177], v[48:51]
	v_mfma_f32_16x16x32_bf16 v[36:39], v[154:157], v[182:185], v[36:39]
	v_mfma_f32_16x16x32_bf16 v[32:35], v[162:165], v[182:185], v[32:35]
	v_mfma_f32_16x16x32_bf16 v[20:23], v[154:157], v[190:193], v[20:23]
	v_mfma_f32_16x16x32_bf16 v[16:19], v[162:165], v[190:193], v[16:19]
	v_mfma_f32_16x16x32_bf16 v[4:7], v[154:157], v[198:201], v[4:7]
	v_mfma_f32_16x16x32_bf16 v[0:3], v[162:165], v[198:201], v[0:3]
	s_setprio 0
	s_barrier
	s_movk_i32 s34, 0x100
	s_andn2_b64 vcc, exec, s[28:29]
	s_mov_b64 s[30:31], -1
	s_mov_b64 s[28:29], 0
	s_cbranch_vccz .LBB0_369
	s_and_b64 vcc, exec, s[12:13]
	s_cbranch_vccz .LBB0_372
	s_barrier

.LBB0_911:
	s_ashr_i32 s15, s14, 31
	s_lshl_b64 s[16:17], s[14:15], 19
	s_add_u32 s16, s30, s16
	s_addc_u32 s17, s31, s17
	s_and_b64 s[18:19], s[2:3], exec
	s_cselect_b32 s5, s17, s25
	s_cselect_b32 s15, s16, s24
	s_ashr_i32 s13, s12, 31
	s_lshl_b64 s[18:19], s[12:13], 19
	s_add_u32 s18, s34, s18
	s_addc_u32 s19, s35, s19
	s_and_b64 s[26:27], s[2:3], exec
	s_cselect_b32 s13, s19, s23
	s_cselect_b32 s21, s18, s22
	s_add_u32 s48, s22, 0x100
	s_addc_u32 s49, s23, 0
	s_add_u32 s22, s24, 0x40080
	s_addc_u32 s23, s25, 0
	s_mov_b32 s50, -2
	s_add_u32 s24, s22, 0xfffc0080
	s_addc_u32 s25, s23, -1
	s_add_i32 s51, 0, 0x10000
	s_cmp_eq_u32 s50, 12
	s_cselect_b32 s27, s5, s25
	s_cselect_b32 s26, s15, s24
	v_add_u32_e32 v142, s51, v144
	s_cselect_b32 s25, s13, s49
	s_cselect_b32 s24, s21, s48
	s_add_i32 s54, 0, 0x14000
	ds_read_b128 v[138:141], v142
	ds_read_b128 v[146:149], v142 offset:1024
	ds_read_b128 v[150:153], v142 offset:2048
	ds_read_b128 v[154:157], v142 offset:3072
	v_add_u32_e32 v142, s54, v144
	ds_read_b128 v[158:161], v142
	ds_read_b128 v[162:165], v142 offset:1024
	ds_read_b128 v[166:169], v142 offset:2048
	ds_read_b128 v[170:173], v142 offset:3072
	v_lshl_add_u64 v[142:143], s[22:23], 0, v[136:137]
	s_add_i32 m0, s37, 0xc000
	ds_read_b128 v[174:177], v145
	ds_read_b128 v[178:181], v145 offset:1024
	ds_read_b128 v[182:185], v145 offset:2048
	ds_read_b128 v[186:189], v145 offset:3072
	ds_read_b128 v[190:193], v145 offset:4096
	ds_read_b128 v[194:197], v145 offset:5120
	ds_read_b128 v[198:201], v145 offset:6144
	ds_read_b128 v[202:205], v145 offset:7168
	global_load_lds_dwordx4 v[142:143], off
	v_lshl_add_u64 v[142:143], s[22:23], 0, v[134:135]
	s_add_i32 m0, s37, 0xe000
	s_nop 0
	global_load_lds_dwordx4 v[142:143], off
	s_waitcnt vmcnt(8)
	s_waitcnt lgkmcnt(0)
	s_barrier
	s_setprio 1
	s_waitcnt lgkmcnt(0)
	v_mfma_f32_16x16x32_bf16 v[124:127], v[138:141], v[174:177], 0
	v_mfma_f32_16x16x32_bf16 v[120:123], v[150:153], v[174:177], 0
	v_mfma_f32_16x16x32_bf16 v[108:111], v[138:141], v[182:185], 0
	v_mfma_f32_16x16x32_bf16 v[104:107], v[150:153], v[182:185], 0
	v_mfma_f32_16x16x32_bf16 v[92:95], v[138:141], v[190:193], 0
	v_mfma_f32_16x16x32_bf16 v[88:91], v[150:153], v[190:193], 0
	v_mfma_f32_16x16x32_bf16 v[76:79], v[138:141], v[198:201], 0
	v_mfma_f32_16x16x32_bf16 v[72:75], v[150:153], v[198:201], 0
	v_mfma_f32_16x16x32_bf16 v[124:127], v[146:149], v[178:181], v[124:127]
	v_mfma_f32_16x16x32_bf16 v[120:123], v[154:157], v[178:181], v[120:123]
	v_mfma_f32_16x16x32_bf16 v[108:111], v[146:149], v[186:189], v[108:111]
	v_mfma_f32_16x16x32_bf16 v[104:107], v[154:157], v[186:189], v[104:107]
	v_mfma_f32_16x16x32_bf16 v[92:95], v[146:149], v[194:197], v[92:95]
	v_mfma_f32_16x16x32_bf16 v[88:91], v[154:157], v[194:197], v[88:91]
	v_mfma_f32_16x16x32_bf16 v[76:79], v[146:149], v[202:205], v[76:79]
	v_mfma_f32_16x16x32_bf16 v[72:75], v[154:157], v[202:205], v[72:75]
	v_mfma_f32_16x16x32_bf16 v[116:119], v[158:161], v[174:177], 0
	v_mfma_f32_16x16x32_bf16 v[112:115], v[166:169], v[174:177], 0
	v_mfma_f32_16x16x32_bf16 v[100:103], v[158:161], v[182:185], 0
	v_mfma_f32_16x16x32_bf16 v[96:99], v[166:169], v[182:185], 0
	v_mfma_f32_16x16x32_bf16 v[84:87], v[158:161], v[190:193], 0
	v_mfma_f32_16x16x32_bf16 v[80:83], v[166:169], v[190:193], 0
	v_mfma_f32_16x16x32_bf16 v[68:71], v[158:161], v[198:201], 0
	v_mfma_f32_16x16x32_bf16 v[64:67], v[166:169], v[198:201], 0
	v_mfma_f32_16x16x32_bf16 v[116:119], v[162:165], v[178:181], v[116:119]
	v_mfma_f32_16x16x32_bf16 v[112:115], v[170:173], v[178:181], v[112:115]
	v_mfma_f32_16x16x32_bf16 v[100:103], v[162:165], v[186:189], v[100:103]
	v_mfma_f32_16x16x32_bf16 v[96:99], v[170:173], v[186:189], v[96:99]
	v_mfma_f32_16x16x32_bf16 v[84:87], v[162:165], v[194:197], v[84:87]
	v_mfma_f32_16x16x32_bf16 v[80:83], v[170:173], v[194:197], v[80:83]
	v_mfma_f32_16x16x32_bf16 v[68:71], v[162:165], v[202:205], v[68:71]
	v_mfma_f32_16x16x32_bf16 v[64:67], v[170:173], v[202:205], v[64:67]
	s_setprio 0
	s_barrier
	s_add_i32 s51, s51, s36
	v_lshl_add_u64 v[142:143], s[24:25], 0, v[232:233]
	s_mov_b32 m0, s51
	ds_read_b128 v[174:177], v145 offset:16384
	ds_read_b128 v[178:181], v145 offset:17408
	ds_read_b128 v[182:185], v145 offset:18432
	ds_read_b128 v[186:189], v145 offset:19456
	ds_read_b128 v[190:193], v145 offset:20480
	ds_read_b128 v[194:197], v145 offset:21504
	ds_read_b128 v[198:201], v145 offset:22528
	ds_read_b128 v[202:205], v145 offset:23552
	global_load_lds_dwordx4 v[142:143], off
	s_add_i32 m0, s51, 0x2000
	s_add_u32 s52, s24, 0x40000
	v_lshl_add_u64 v[206:207], s[24:25], 0, v[132:133]
	s_addc_u32 s53, s25, 0
	s_add_i32 s51, s54, s36
	global_load_lds_dwordx4 v[206:207], off
	v_lshl_add_u64 v[208:209], s[52:53], 0, v[232:233]
	s_mov_b32 m0, s51
	v_lshl_add_u64 v[210:211], s[26:27], 0, v[130:131]
	global_load_lds_dwordx4 v[208:209], off
	v_lshl_add_u64 v[208:209], s[52:53], 0, v[132:133]
	s_add_i32 m0, s51, 0x2000
	s_nop 0
	global_load_lds_dwordx4 v[208:209], off
	v_lshl_add_u64 v[208:209], s[26:27], 0, v[128:129]
	s_waitcnt vmcnt(6)
	s_waitcnt lgkmcnt(0)
	s_barrier
	s_setprio 1
	s_waitcnt lgkmcnt(0)
	v_mfma_f32_16x16x32_bf16 v[60:63], v[138:141], v[174:177], 0
	v_mfma_f32_16x16x32_bf16 v[56:59], v[150:153], v[174:177], 0
	v_mfma_f32_16x16x32_bf16 v[44:47], v[138:141], v[182:185], 0
	v_mfma_f32_16x16x32_bf16 v[40:43], v[150:153], v[182:185], 0
	v_mfma_f32_16x16x32_bf16 v[28:31], v[138:141], v[190:193], 0
	v_mfma_f32_16x16x32_bf16 v[24:27], v[150:153], v[190:193], 0
	v_mfma_f32_16x16x32_bf16 v[12:15], v[138:141], v[198:201], 0
	v_mfma_f32_16x16x32_bf16 v[8:11], v[150:153], v[198:201], 0
	v_mfma_f32_16x16x32_bf16 v[60:63], v[146:149], v[178:181], v[60:63]
	v_mfma_f32_16x16x32_bf16 v[56:59], v[154:157], v[178:181], v[56:59]
	v_mfma_f32_16x16x32_bf16 v[44:47], v[146:149], v[186:189], v[44:47]
	v_mfma_f32_16x16x32_bf16 v[40:43], v[154:157], v[186:189], v[40:43]
	v_mfma_f32_16x16x32_bf16 v[28:31], v[146:149], v[194:197], v[28:31]
	v_mfma_f32_16x16x32_bf16 v[24:27], v[154:157], v[194:197], v[24:27]
	v_mfma_f32_16x16x32_bf16 v[12:15], v[146:149], v[202:205], v[12:15]
	v_mfma_f32_16x16x32_bf16 v[8:11], v[154:157], v[202:205], v[8:11]
	v_mfma_f32_16x16x32_bf16 v[52:55], v[158:161], v[174:177], 0
	v_mfma_f32_16x16x32_bf16 v[48:51], v[166:169], v[174:177], 0
	v_mfma_f32_16x16x32_bf16 v[36:39], v[158:161], v[182:185], 0
	v_mfma_f32_16x16x32_bf16 v[32:35], v[166:169], v[182:185], 0
	v_mfma_f32_16x16x32_bf16 v[20:23], v[158:161], v[190:193], 0
	v_mfma_f32_16x16x32_bf16 v[16:19], v[166:169], v[190:193], 0
	v_mfma_f32_16x16x32_bf16 v[4:7], v[158:161], v[198:201], 0
	v_mfma_f32_16x16x32_bf16 v[0:3], v[166:169], v[198:201], 0
	v_mfma_f32_16x16x32_bf16 v[52:55], v[162:165], v[178:181], v[52:55]
	v_mfma_f32_16x16x32_bf16 v[48:51], v[170:173], v[178:181], v[48:51]
	v_mfma_f32_16x16x32_bf16 v[36:39], v[162:165], v[186:189], v[36:39]
	v_mfma_f32_16x16x32_bf16 v[32:35], v[170:173], v[186:189], v[32:35]
	v_mfma_f32_16x16x32_bf16 v[20:23], v[162:165], v[194:197], v[20:23]
	v_mfma_f32_16x16x32_bf16 v[16:19], v[170:173], v[194:197], v[16:19]
	v_mfma_f32_16x16x32_bf16 v[4:7], v[162:165], v[202:205], v[4:7]
	v_mfma_f32_16x16x32_bf16 v[0:3], v[170:173], v[202:205], v[0:3]
	s_setprio 0
	s_barrier
	s_branch .Lzmid_2
.LBB0_912:
	s_add_u32 s24, s22, 0xfffc0080
	s_addc_u32 s25, s23, -1
	s_add_i32 s51, 0, 0x10000
	s_cmp_eq_u32 s50, 12
	s_cselect_b32 s27, s5, s25
	s_cselect_b32 s26, s15, s24
	v_add_u32_e32 v142, s51, v144
	s_cselect_b32 s25, s13, s49
	s_cselect_b32 s24, s21, s48
	s_add_i32 s54, 0, 0x14000
	ds_read_b128 v[138:141], v142
	ds_read_b128 v[146:149], v142 offset:1024
	ds_read_b128 v[150:153], v142 offset:2048
	ds_read_b128 v[154:157], v142 offset:3072
	v_add_u32_e32 v142, s54, v144
	ds_read_b128 v[158:161], v142
	ds_read_b128 v[162:165], v142 offset:1024
	ds_read_b128 v[166:169], v142 offset:2048
	ds_read_b128 v[170:173], v142 offset:3072
	v_lshl_add_u64 v[142:143], s[22:23], 0, v[136:137]
	s_add_i32 m0, s37, 0xc000
	ds_read_b128 v[174:177], v145
	ds_read_b128 v[178:181], v145 offset:1024
	ds_read_b128 v[182:185], v145 offset:2048
	ds_read_b128 v[186:189], v145 offset:3072
	ds_read_b128 v[190:193], v145 offset:4096
	ds_read_b128 v[194:197], v145 offset:5120
	ds_read_b128 v[198:201], v145 offset:6144
	ds_read_b128 v[202:205], v145 offset:7168
	global_load_lds_dwordx4 v[142:143], off
	v_lshl_add_u64 v[142:143], s[22:23], 0, v[134:135]
	s_add_i32 m0, s37, 0xe000
	s_nop 0
	global_load_lds_dwordx4 v[142:143], off
	s_waitcnt vmcnt(8)
	s_waitcnt lgkmcnt(0)
	s_barrier
	s_setprio 1
	s_waitcnt lgkmcnt(0)
	v_mfma_f32_16x16x32_bf16 v[124:127], v[138:141], v[174:177], v[124:127]
	v_mfma_f32_16x16x32_bf16 v[120:123], v[150:153], v[174:177], v[120:123]
	v_mfma_f32_16x16x32_bf16 v[108:111], v[138:141], v[182:185], v[108:111]
	v_mfma_f32_16x16x32_bf16 v[104:107], v[150:153], v[182:185], v[104:107]
	v_mfma_f32_16x16x32_bf16 v[92:95], v[138:141], v[190:193], v[92:95]
	v_mfma_f32_16x16x32_bf16 v[88:91], v[150:153], v[190:193], v[88:91]
	v_mfma_f32_16x16x32_bf16 v[76:79], v[138:141], v[198:201], v[76:79]
	v_mfma_f32_16x16x32_bf16 v[72:75], v[150:153], v[198:201], v[72:75]
	v_mfma_f32_16x16x32_bf16 v[124:127], v[146:149], v[178:181], v[124:127]
	v_mfma_f32_16x16x32_bf16 v[120:123], v[154:157], v[178:181], v[120:123]
	v_mfma_f32_16x16x32_bf16 v[108:111], v[146:149], v[186:189], v[108:111]
	v_mfma_f32_16x16x32_bf16 v[104:107], v[154:157], v[186:189], v[104:107]
	v_mfma_f32_16x16x32_bf16 v[92:95], v[146:149], v[194:197], v[92:95]
	v_mfma_f32_16x16x32_bf16 v[88:91], v[154:157], v[194:197], v[88:91]
	v_mfma_f32_16x16x32_bf16 v[76:79], v[146:149], v[202:205], v[76:79]
	v_mfma_f32_16x16x32_bf16 v[72:75], v[154:157], v[202:205], v[72:75]
	v_mfma_f32_16x16x32_bf16 v[116:119], v[158:161], v[174:177], v[116:119]
	v_mfma_f32_16x16x32_bf16 v[112:115], v[166:169], v[174:177], v[112:115]
	v_mfma_f32_16x16x32_bf16 v[100:103], v[158:161], v[182:185], v[100:103]
	v_mfma_f32_16x16x32_bf16 v[96:99], v[166:169], v[182:185], v[96:99]
	v_mfma_f32_16x16x32_bf16 v[84:87], v[158:161], v[190:193], v[84:87]
	v_mfma_f32_16x16x32_bf16 v[80:83], v[166:169], v[190:193], v[80:83]
	v_mfma_f32_16x16x32_bf16 v[68:71], v[158:161], v[198:201], v[68:71]
	v_mfma_f32_16x16x32_bf16 v[64:67], v[166:169], v[198:201], v[64:67]
	v_mfma_f32_16x16x32_bf16 v[116:119], v[162:165], v[178:181], v[116:119]
	v_mfma_f32_16x16x32_bf16 v[112:115], v[170:173], v[178:181], v[112:115]
	v_mfma_f32_16x16x32_bf16 v[100:103], v[162:165], v[186:189], v[100:103]
	v_mfma_f32_16x16x32_bf16 v[96:99], v[170:173], v[186:189], v[96:99]
	v_mfma_f32_16x16x32_bf16 v[84:87], v[162:165], v[194:197], v[84:87]
	v_mfma_f32_16x16x32_bf16 v[80:83], v[170:173], v[194:197], v[80:83]
	v_mfma_f32_16x16x32_bf16 v[68:71], v[162:165], v[202:205], v[68:71]
	v_mfma_f32_16x16x32_bf16 v[64:67], v[170:173], v[202:205], v[64:67]
	s_setprio 0
	s_barrier
	s_add_i32 s51, s51, s36
	v_lshl_add_u64 v[142:143], s[24:25], 0, v[232:233]
	s_mov_b32 m0, s51
	ds_read_b128 v[174:177], v145 offset:16384
	ds_read_b128 v[178:181], v145 offset:17408
	ds_read_b128 v[182:185], v145 offset:18432
	ds_read_b128 v[186:189], v145 offset:19456
	ds_read_b128 v[190:193], v145 offset:20480
	ds_read_b128 v[194:197], v145 offset:21504
	ds_read_b128 v[198:201], v145 offset:22528
	ds_read_b128 v[202:205], v145 offset:23552
	global_load_lds_dwordx4 v[142:143], off
	s_add_i32 m0, s51, 0x2000
	s_add_u32 s52, s24, 0x40000
	v_lshl_add_u64 v[206:207], s[24:25], 0, v[132:133]
	s_addc_u32 s53, s25, 0
	s_add_i32 s51, s54, s36
	global_load_lds_dwordx4 v[206:207], off
	v_lshl_add_u64 v[208:209], s[52:53], 0, v[232:233]
	s_mov_b32 m0, s51
	v_lshl_add_u64 v[210:211], s[26:27], 0, v[130:131]
	global_load_lds_dwordx4 v[208:209], off
	v_lshl_add_u64 v[208:209], s[52:53], 0, v[132:133]
	s_add_i32 m0, s51, 0x2000
	s_nop 0
	global_load_lds_dwordx4 v[208:209], off
	v_lshl_add_u64 v[208:209], s[26:27], 0, v[128:129]
	s_waitcnt vmcnt(6)
	s_waitcnt lgkmcnt(0)
	s_barrier
	s_setprio 1
	s_waitcnt lgkmcnt(0)
	v_mfma_f32_16x16x32_bf16 v[60:63], v[138:141], v[174:177], v[60:63]
	v_mfma_f32_16x16x32_bf16 v[56:59], v[150:153], v[174:177], v[56:59]
	v_mfma_f32_16x16x32_bf16 v[44:47], v[138:141], v[182:185], v[44:47]
	v_mfma_f32_16x16x32_bf16 v[40:43], v[150:153], v[182:185], v[40:43]
	v_mfma_f32_16x16x32_bf16 v[28:31], v[138:141], v[190:193], v[28:31]
	v_mfma_f32_16x16x32_bf16 v[24:27], v[150:153], v[190:193], v[24:27]
	v_mfma_f32_16x16x32_bf16 v[12:15], v[138:141], v[198:201], v[12:15]
	v_mfma_f32_16x16x32_bf16 v[8:11], v[150:153], v[198:201], v[8:11]
	v_mfma_f32_16x16x32_bf16 v[60:63], v[146:149], v[178:181], v[60:63]
	v_mfma_f32_16x16x32_bf16 v[56:59], v[154:157], v[178:181], v[56:59]
	v_mfma_f32_16x16x32_bf16 v[44:47], v[146:149], v[186:189], v[44:47]
	v_mfma_f32_16x16x32_bf16 v[40:43], v[154:157], v[186:189], v[40:43]
	v_mfma_f32_16x16x32_bf16 v[28:31], v[146:149], v[194:197], v[28:31]
	v_mfma_f32_16x16x32_bf16 v[24:27], v[154:157], v[194:197], v[24:27]
	v_mfma_f32_16x16x32_bf16 v[12:15], v[146:149], v[202:205], v[12:15]
	v_mfma_f32_16x16x32_bf16 v[8:11], v[154:157], v[202:205], v[8:11]
	v_mfma_f32_16x16x32_bf16 v[52:55], v[158:161], v[174:177], v[52:55]
	v_mfma_f32_16x16x32_bf16 v[48:51], v[166:169], v[174:177], v[48:51]
	v_mfma_f32_16x16x32_bf16 v[36:39], v[158:161], v[182:185], v[36:39]
	v_mfma_f32_16x16x32_bf16 v[32:35], v[166:169], v[182:185], v[32:35]
	v_mfma_f32_16x16x32_bf16 v[20:23], v[158:161], v[190:193], v[20:23]
	v_mfma_f32_16x16x32_bf16 v[16:19], v[166:169], v[190:193], v[16:19]
	v_mfma_f32_16x16x32_bf16 v[4:7], v[158:161], v[198:201], v[4:7]
	v_mfma_f32_16x16x32_bf16 v[0:3], v[166:169], v[198:201], v[0:3]
	v_mfma_f32_16x16x32_bf16 v[52:55], v[162:165], v[178:181], v[52:55]
	v_mfma_f32_16x16x32_bf16 v[48:51], v[170:173], v[178:181], v[48:51]
	v_mfma_f32_16x16x32_bf16 v[36:39], v[162:165], v[186:189], v[36:39]
	v_mfma_f32_16x16x32_bf16 v[32:35], v[170:173], v[186:189], v[32:35]
	v_mfma_f32_16x16x32_bf16 v[20:23], v[162:165], v[194:197], v[20:23]
	v_mfma_f32_16x16x32_bf16 v[16:19], v[170:173], v[194:197], v[16:19]
	v_mfma_f32_16x16x32_bf16 v[4:7], v[162:165], v[202:205], v[4:7]
	v_mfma_f32_16x16x32_bf16 v[0:3], v[170:173], v[202:205], v[0:3]
	s_setprio 0
	s_barrier
.Lzmid_2:
	s_add_i32 s51, 0, 0x18000
	s_add_i32 s52, 0, 0x1c000
	v_add_u32_e32 v154, s51, v144
	v_add_u32_e32 v170, s52, v144
	ds_read_b128 v[138:141], v154
	ds_read_b128 v[146:149], v154 offset:1024
	ds_read_b128 v[150:153], v154 offset:2048
	ds_read_b128 v[154:157], v154 offset:3072
	ds_read_b128 v[158:161], v170
	ds_read_b128 v[162:165], v170 offset:1024
	ds_read_b128 v[166:169], v170 offset:2048
	ds_read_b128 v[170:173], v170 offset:3072
	s_add_u32 s26, s26, 0x40000
	s_addc_u32 s27, s27, 0
	s_mov_b32 m0, s37
	s_nop 0
	global_load_lds_dwordx4 v[208:209], off
	s_mov_b32 m0, s38
	s_nop 0
	global_load_lds_dwordx4 v[210:211], off
	s_mov_b32 m0, s39
	v_lshl_add_u64 v[212:213], s[26:27], 0, v[128:129]
	ds_read_b128 v[174:177], v145 offset:32768
	ds_read_b128 v[178:181], v145 offset:33792
	ds_read_b128 v[182:185], v145 offset:34816
	ds_read_b128 v[186:189], v145 offset:35840
	ds_read_b128 v[190:193], v145 offset:36864
	ds_read_b128 v[194:197], v145 offset:37888
	ds_read_b128 v[198:201], v145 offset:38912
	ds_read_b128 v[202:205], v145 offset:39936
	global_load_lds_dwordx4 v[212:213], off
	v_lshl_add_u64 v[212:213], s[26:27], 0, v[130:131]
	s_mov_b32 m0, s40
	s_nop 0
	global_load_lds_dwordx4 v[212:213], off
	s_waitcnt vmcnt(8)
	s_waitcnt lgkmcnt(0)
	s_barrier
	s_setprio 1
	s_waitcnt lgkmcnt(0)
	v_mfma_f32_16x16x32_bf16 v[124:127], v[138:141], v[174:177], v[124:127]
	v_mfma_f32_16x16x32_bf16 v[120:123], v[150:153], v[174:177], v[120:123]
	v_mfma_f32_16x16x32_bf16 v[108:111], v[138:141], v[182:185], v[108:111]
	v_mfma_f32_16x16x32_bf16 v[104:107], v[150:153], v[182:185], v[104:107]
	v_mfma_f32_16x16x32_bf16 v[92:95], v[138:141], v[190:193], v[92:95]
	v_mfma_f32_16x16x32_bf16 v[88:91], v[150:153], v[190:193], v[88:91]
	v_mfma_f32_16x16x32_bf16 v[76:79], v[138:141], v[198:201], v[76:79]
	v_mfma_f32_16x16x32_bf16 v[72:75], v[150:153], v[198:201], v[72:75]
	v_mfma_f32_16x16x32_bf16 v[124:127], v[146:149], v[178:181], v[124:127]
	v_mfma_f32_16x16x32_bf16 v[120:123], v[154:157], v[178:181], v[120:123]
	v_mfma_f32_16x16x32_bf16 v[108:111], v[146:149], v[186:189], v[108:111]
	v_mfma_f32_16x16x32_bf16 v[104:107], v[154:157], v[186:189], v[104:107]
	v_mfma_f32_16x16x32_bf16 v[92:95], v[146:149], v[194:197], v[92:95]
	v_mfma_f32_16x16x32_bf16 v[88:91], v[154:157], v[194:197], v[88:91]
	v_mfma_f32_16x16x32_bf16 v[76:79], v[146:149], v[202:205], v[76:79]
	v_mfma_f32_16x16x32_bf16 v[72:75], v[154:157], v[202:205], v[72:75]
	v_mfma_f32_16x16x32_bf16 v[116:119], v[158:161], v[174:177], v[116:119]
	v_mfma_f32_16x16x32_bf16 v[112:115], v[166:169], v[174:177], v[112:115]
	v_mfma_f32_16x16x32_bf16 v[100:103], v[158:161], v[182:185], v[100:103]
	v_mfma_f32_16x16x32_bf16 v[96:99], v[166:169], v[182:185], v[96:99]
	v_mfma_f32_16x16x32_bf16 v[84:87], v[158:161], v[190:193], v[84:87]
	v_mfma_f32_16x16x32_bf16 v[80:83], v[166:169], v[190:193], v[80:83]
	v_mfma_f32_16x16x32_bf16 v[68:71], v[158:161], v[198:201], v[68:71]
	v_mfma_f32_16x16x32_bf16 v[64:67], v[166:169], v[198:201], v[64:67]
	v_mfma_f32_16x16x32_bf16 v[116:119], v[162:165], v[178:181], v[116:119]
	v_mfma_f32_16x16x32_bf16 v[112:115], v[170:173], v[178:181], v[112:115]
	v_mfma_f32_16x16x32_bf16 v[100:103], v[162:165], v[186:189], v[100:103]
	v_mfma_f32_16x16x32_bf16 v[96:99], v[170:173], v[186:189], v[96:99]
	v_mfma_f32_16x16x32_bf16 v[84:87], v[162:165], v[194:197], v[84:87]
	v_mfma_f32_16x16x32_bf16 v[80:83], v[170:173], v[194:197], v[80:83]
	v_mfma_f32_16x16x32_bf16 v[68:71], v[162:165], v[202:205], v[68:71]
	v_mfma_f32_16x16x32_bf16 v[64:67], v[170:173], v[202:205], v[64:67]
	s_setprio 0
	s_barrier
	s_add_i32 s26, s51, s36
	v_lshl_add_u64 v[142:143], v[142:143], 0, s[94:95]
	s_mov_b32 m0, s26
	ds_read_b128 v[174:177], v145 offset:49152
	ds_read_b128 v[178:181], v145 offset:50176
	ds_read_b128 v[182:185], v145 offset:51200
	ds_read_b128 v[186:189], v145 offset:52224
	ds_read_b128 v[190:193], v145 offset:53248
	ds_read_b128 v[194:197], v145 offset:54272
	ds_read_b128 v[198:201], v145 offset:55296
	ds_read_b128 v[202:205], v145 offset:56320
	global_load_lds_dwordx4 v[142:143], off
	s_add_i32 m0, s26, 0x2000
	s_add_u32 s24, s24, 0x40080
	v_lshl_add_u64 v[142:143], v[206:207], 0, s[94:95]
	s_addc_u32 s25, s25, 0
	s_add_i32 s26, s52, s36
	global_load_lds_dwordx4 v[142:143], off
	v_lshl_add_u64 v[142:143], s[24:25], 0, v[232:233]
	s_mov_b32 m0, s26
	s_nop 0
	global_load_lds_dwordx4 v[142:143], off
	v_lshl_add_u64 v[142:143], s[24:25], 0, v[132:133]
	s_add_i32 m0, s26, 0x2000
	s_nop 0
	global_load_lds_dwordx4 v[142:143], off
	v_lshl_add_u64 v[142:143], v[208:209], 0, s[94:95]
	s_mov_b32 m0, s43
	s_nop 0
	global_load_lds_dwordx4 v[142:143], off
	v_lshl_add_u64 v[142:143], v[210:211], 0, s[94:95]
	s_mov_b32 m0, s44
	s_nop 0
	global_load_lds_dwordx4 v[142:143], off
	s_waitcnt vmcnt(8)
	s_waitcnt lgkmcnt(0)
	s_barrier
	s_setprio 1
	s_waitcnt lgkmcnt(0)
	v_mfma_f32_16x16x32_bf16 v[60:63], v[138:141], v[174:177], v[60:63]
	v_mfma_f32_16x16x32_bf16 v[56:59], v[150:153], v[174:177], v[56:59]
	v_mfma_f32_16x16x32_bf16 v[44:47], v[138:141], v[182:185], v[44:47]
	v_mfma_f32_16x16x32_bf16 v[40:43], v[150:153], v[182:185], v[40:43]
	v_mfma_f32_16x16x32_bf16 v[28:31], v[138:141], v[190:193], v[28:31]
	v_mfma_f32_16x16x32_bf16 v[24:27], v[150:153], v[190:193], v[24:27]
	v_mfma_f32_16x16x32_bf16 v[12:15], v[138:141], v[198:201], v[12:15]
	v_mfma_f32_16x16x32_bf16 v[8:11], v[150:153], v[198:201], v[8:11]
	v_mfma_f32_16x16x32_bf16 v[60:63], v[146:149], v[178:181], v[60:63]
	v_mfma_f32_16x16x32_bf16 v[56:59], v[154:157], v[178:181], v[56:59]
	v_mfma_f32_16x16x32_bf16 v[44:47], v[146:149], v[186:189], v[44:47]
	v_mfma_f32_16x16x32_bf16 v[40:43], v[154:157], v[186:189], v[40:43]
	v_mfma_f32_16x16x32_bf16 v[28:31], v[146:149], v[194:197], v[28:31]
	v_mfma_f32_16x16x32_bf16 v[24:27], v[154:157], v[194:197], v[24:27]
	v_mfma_f32_16x16x32_bf16 v[12:15], v[146:149], v[202:205], v[12:15]
	v_mfma_f32_16x16x32_bf16 v[8:11], v[154:157], v[202:205], v[8:11]
	v_mfma_f32_16x16x32_bf16 v[52:55], v[158:161], v[174:177], v[52:55]
	v_mfma_f32_16x16x32_bf16 v[48:51], v[166:169], v[174:177], v[48:51]
	v_mfma_f32_16x16x32_bf16 v[36:39], v[158:161], v[182:185], v[36:39]
	v_mfma_f32_16x16x32_bf16 v[32:35], v[166:169], v[182:185], v[32:35]
	v_mfma_f32_16x16x32_bf16 v[20:23], v[158:161], v[190:193], v[20:23]
	v_mfma_f32_16x16x32_bf16 v[16:19], v[166:169], v[190:193], v[16:19]
	v_mfma_f32_16x16x32_bf16 v[4:7], v[158:161], v[198:201], v[4:7]
	v_mfma_f32_16x16x32_bf16 v[0:3], v[166:169], v[198:201], v[0:3]
	v_mfma_f32_16x16x32_bf16 v[52:55], v[162:165], v[178:181], v[52:55]
	v_mfma_f32_16x16x32_bf16 v[48:51], v[170:173], v[178:181], v[48:51]
	v_mfma_f32_16x16x32_bf16 v[36:39], v[162:165], v[186:189], v[36:39]
	v_mfma_f32_16x16x32_bf16 v[32:35], v[170:173], v[186:189], v[32:35]
	v_mfma_f32_16x16x32_bf16 v[20:23], v[162:165], v[194:197], v[20:23]
	v_mfma_f32_16x16x32_bf16 v[16:19], v[170:173], v[194:197], v[16:19]
	v_mfma_f32_16x16x32_bf16 v[4:7], v[162:165], v[202:205], v[4:7]
	v_mfma_f32_16x16x32_bf16 v[0:3], v[170:173], v[202:205], v[0:3]
	s_setprio 0
	s_barrier
	s_add_i32 s50, s50, 2
	s_add_u32 s48, s48, 0x100
	s_addc_u32 s49, s49, 0
	s_add_u32 s22, s22, 0x100
	s_addc_u32 s23, s23, 0
	s_cmp_gt_u32 s50, 13
	s_cbranch_scc0 .LBB0_912
	s_and_b64 vcc, exec, s[10:11]
	s_cbranch_vccz .LBB0_915
	s_barrier

.LBB0_1018:
	s_ashr_i32 s15, s14, 31
	s_ashr_i32 s13, s12, 31
	s_lshl_b64 s[16:17], s[14:15], 19
	s_lshl_b64 s[18:19], s[12:13], 9
	s_add_u32 s13, s34, s16
	s_addc_u32 s15, s35, s17
	s_add_u32 s16, s13, s18
	s_addc_u32 s17, s15, s19
	s_and_b64 s[18:19], s[2:3], exec
	s_cselect_b32 s29, s17, s23
	s_cselect_b32 s28, s16, s22
	s_lshl_b32 s13, s12, 2
	s_add_i32 s18, s13, s51
	s_ashr_i32 s19, s18, 31
	s_lshl_b64 s[18:19], s[18:19], 17
	s_add_u32 s18, s36, s18
	s_addc_u32 s19, s37, s19
	s_and_b64 s[26:27], s[2:3], exec
	s_cselect_b32 s27, s19, s25
	s_cselect_b32 s26, s18, s24
	s_add_i32 s15, 0, 0x10000
	s_add_i32 s21, 0, 0x14000
	v_add_u32_e32 v253, 0x10000, v174
	v_add_u32_e32 v252, 0x14000, v174
	ds_read_b128 v[128:131], v253
	ds_read_b128 v[132:135], v253 offset:1024
	ds_read_b128 v[136:139], v253 offset:2048
	ds_read_b128 v[140:143], v253 offset:3072
	ds_read_b128 v[144:147], v252
	ds_read_b128 v[148:151], v252 offset:1024
	ds_read_b128 v[152:155], v252 offset:2048
	ds_read_b128 v[156:159], v252 offset:3072
	s_add_u32 s52, s22, 0x40080
	s_addc_u32 s53, s23, 0
	s_add_i32 s55, s39, 0xc000
	s_waitcnt vmcnt(0)
	s_mov_b32 m0, s55
	s_add_i32 s13, s39, 0xe000
	ds_read_b128 v[168:171], v175
	ds_read_b128 v[176:179], v175 offset:1024
	ds_read_b128 v[180:183], v175 offset:2048
	ds_read_b128 v[184:187], v175 offset:3072
	ds_read_b128 v[188:191], v175 offset:4096
	ds_read_b128 v[192:195], v175 offset:5120
	ds_read_b128 v[196:199], v175 offset:6144
	ds_read_b128 v[200:203], v175 offset:7168
	global_load_lds_dwordx4 v160, s[52:53]
	s_mov_b32 m0, s13
	s_nop 0
	global_load_lds_dwordx4 v162, s[52:53]
	s_waitcnt vmcnt(8)
	s_waitcnt lgkmcnt(0)
	s_barrier
	s_setprio 1
	s_waitcnt lgkmcnt(0)
	v_mfma_f32_16x16x32_bf16 v[0:3], v[128:131], v[168:171], 0
	v_mfma_f32_16x16x32_bf16 v[4:7], v[136:139], v[168:171], 0
	v_mfma_f32_16x16x32_bf16 v[16:19], v[128:131], v[180:183], 0
	v_mfma_f32_16x16x32_bf16 v[20:23], v[136:139], v[180:183], 0
	v_mfma_f32_16x16x32_bf16 v[32:35], v[128:131], v[188:191], 0
	v_mfma_f32_16x16x32_bf16 v[36:39], v[136:139], v[188:191], 0
	v_mfma_f32_16x16x32_bf16 v[48:51], v[128:131], v[196:199], 0
	v_mfma_f32_16x16x32_bf16 v[52:55], v[136:139], v[196:199], 0
	v_mfma_f32_16x16x32_bf16 v[0:3], v[132:135], v[176:179], v[0:3]
	v_mfma_f32_16x16x32_bf16 v[4:7], v[140:143], v[176:179], v[4:7]
	v_mfma_f32_16x16x32_bf16 v[16:19], v[132:135], v[184:187], v[16:19]
	v_mfma_f32_16x16x32_bf16 v[20:23], v[140:143], v[184:187], v[20:23]
	v_mfma_f32_16x16x32_bf16 v[32:35], v[132:135], v[192:195], v[32:35]
	v_mfma_f32_16x16x32_bf16 v[36:39], v[140:143], v[192:195], v[36:39]
	v_mfma_f32_16x16x32_bf16 v[48:51], v[132:135], v[200:203], v[48:51]
	v_mfma_f32_16x16x32_bf16 v[52:55], v[140:143], v[200:203], v[52:55]
	v_mfma_f32_16x16x32_bf16 v[8:11], v[144:147], v[168:171], 0
	v_mfma_f32_16x16x32_bf16 v[12:15], v[152:155], v[168:171], 0
	v_mfma_f32_16x16x32_bf16 v[8:11], v[148:151], v[176:179], v[8:11]
	v_mfma_f32_16x16x32_bf16 v[12:15], v[156:159], v[176:179], v[12:15]
	v_mfma_f32_16x16x32_bf16 v[24:27], v[144:147], v[180:183], 0
	v_mfma_f32_16x16x32_bf16 v[28:31], v[152:155], v[180:183], 0
	v_mfma_f32_16x16x32_bf16 v[24:27], v[148:151], v[184:187], v[24:27]
	v_mfma_f32_16x16x32_bf16 v[28:31], v[156:159], v[184:187], v[28:31]
	v_mfma_f32_16x16x32_bf16 v[40:43], v[144:147], v[188:191], 0
	v_mfma_f32_16x16x32_bf16 v[44:47], v[152:155], v[188:191], 0
	v_mfma_f32_16x16x32_bf16 v[40:43], v[148:151], v[192:195], v[40:43]
	v_mfma_f32_16x16x32_bf16 v[44:47], v[156:159], v[192:195], v[44:47]
	v_mfma_f32_16x16x32_bf16 v[56:59], v[144:147], v[196:199], 0
	v_mfma_f32_16x16x32_bf16 v[60:63], v[152:155], v[196:199], 0
	v_mfma_f32_16x16x32_bf16 v[56:59], v[148:151], v[200:203], v[56:59]
	v_mfma_f32_16x16x32_bf16 v[60:63], v[156:159], v[200:203], v[60:63]
	s_setprio 0
	s_barrier
	s_add_i32 s53, s15, s38
	s_mov_b64 s[58:59], 0x100
	s_add_i32 s15, s53, 0x2000
	s_add_u32 s68, s24, s58
	s_addc_u32 s69, s25, s59
	s_mov_b32 m0, s53
	s_add_u32 s70, s24, s58
	s_addc_u32 s71, s25, s59
	s_add_u32 s56, s24, 0x10100
	ds_read_b128 v[168:171], v175 offset:16384
	ds_read_b128 v[176:179], v175 offset:17408
	ds_read_b128 v[180:183], v175 offset:18432
	ds_read_b128 v[184:187], v175 offset:19456
	ds_read_b128 v[188:191], v175 offset:20480
	ds_read_b128 v[192:195], v175 offset:21504
	ds_read_b128 v[196:199], v175 offset:22528
	ds_read_b128 v[200:203], v175 offset:23552
	global_load_lds_dwordx4 v232, s[68:69]
	s_mov_b32 m0, s15
	s_addc_u32 s57, s25, 0
	s_add_i32 s21, s21, s38
	global_load_lds_dwordx4 v164, s[70:71]
	s_mov_b32 m0, s21
	s_add_i32 s52, s21, 0x2000
	global_load_lds_dwordx4 v232, s[56:57]
	s_mov_b32 m0, s52
	global_load_lds_dwordx4 v164, s[56:57]
	s_add_u32 s68, s22, s58
	s_addc_u32 s69, s23, s59
	s_mov_b32 m0, s39
	global_load_lds_dwordx4 v160, s[68:69]
	s_add_u32 s68, s22, s58
	s_addc_u32 s69, s23, s59
	s_mov_b32 m0, s40
	s_nop 0
	global_load_lds_dwordx4 v162, s[68:69]
	s_waitcnt vmcnt(8)
	s_waitcnt lgkmcnt(0)
	s_barrier
	s_setprio 1
	s_waitcnt lgkmcnt(0)
	v_mfma_f32_16x16x32_bf16 v[64:67], v[128:131], v[168:171], 0
	v_mfma_f32_16x16x32_bf16 v[80:83], v[128:131], v[180:183], 0
	v_mfma_f32_16x16x32_bf16 v[96:99], v[128:131], v[188:191], 0
	v_mfma_f32_16x16x32_bf16 v[112:115], v[128:131], v[196:199], 0
	v_mfma_f32_16x16x32_bf16 v[64:67], v[132:135], v[176:179], v[64:67]
	v_mfma_f32_16x16x32_bf16 v[68:71], v[136:139], v[168:171], 0
	v_mfma_f32_16x16x32_bf16 v[80:83], v[132:135], v[184:187], v[80:83]
	v_mfma_f32_16x16x32_bf16 v[84:87], v[136:139], v[180:183], 0
	v_mfma_f32_16x16x32_bf16 v[96:99], v[132:135], v[192:195], v[96:99]
	v_mfma_f32_16x16x32_bf16 v[112:115], v[132:135], v[200:203], v[112:115]
	v_mfma_f32_16x16x32_bf16 v[116:119], v[136:139], v[196:199], 0
	v_mfma_f32_16x16x32_bf16 v[68:71], v[140:143], v[176:179], v[68:71]
	v_mfma_f32_16x16x32_bf16 v[84:87], v[140:143], v[184:187], v[84:87]
	v_mfma_f32_16x16x32_bf16 v[100:103], v[136:139], v[188:191], 0
	v_mfma_f32_16x16x32_bf16 v[116:119], v[140:143], v[200:203], v[116:119]
	v_mfma_f32_16x16x32_bf16 v[100:103], v[140:143], v[192:195], v[100:103]
	v_mfma_f32_16x16x32_bf16 v[72:75], v[144:147], v[168:171], 0
	v_mfma_f32_16x16x32_bf16 v[76:79], v[152:155], v[168:171], 0
	v_mfma_f32_16x16x32_bf16 v[72:75], v[148:151], v[176:179], v[72:75]
	v_mfma_f32_16x16x32_bf16 v[76:79], v[156:159], v[176:179], v[76:79]
	v_mfma_f32_16x16x32_bf16 v[88:91], v[144:147], v[180:183], 0
	v_mfma_f32_16x16x32_bf16 v[92:95], v[152:155], v[180:183], 0
	v_mfma_f32_16x16x32_bf16 v[104:107], v[144:147], v[188:191], 0
	v_mfma_f32_16x16x32_bf16 v[120:123], v[144:147], v[196:199], 0
	v_mfma_f32_16x16x32_bf16 v[88:91], v[148:151], v[184:187], v[88:91]
	v_mfma_f32_16x16x32_bf16 v[92:95], v[156:159], v[184:187], v[92:95]
	v_mfma_f32_16x16x32_bf16 v[104:107], v[148:151], v[192:195], v[104:107]
	v_mfma_f32_16x16x32_bf16 v[108:111], v[152:155], v[188:191], 0
	v_mfma_f32_16x16x32_bf16 v[120:123], v[148:151], v[200:203], v[120:123]
	v_mfma_f32_16x16x32_bf16 v[124:127], v[152:155], v[196:199], 0
	v_mfma_f32_16x16x32_bf16 v[108:111], v[156:159], v[192:195], v[108:111]
	v_mfma_f32_16x16x32_bf16 v[124:127], v[156:159], v[200:203], v[124:127]
	s_setprio 0
	s_barrier
	s_add_i32 s54, 0, 0x18000
	s_add_i32 s60, 0, 0x1c000
	v_add_u32_e32 v253, 0x18000, v174
	v_add_u32_e32 v252, 0x1c000, v174
	ds_read_b128 v[128:131], v253
	ds_read_b128 v[132:135], v253 offset:1024
	ds_read_b128 v[136:139], v253 offset:2048
	ds_read_b128 v[140:143], v253 offset:3072
	ds_read_b128 v[144:147], v252
	ds_read_b128 v[148:151], v252 offset:1024
	ds_read_b128 v[152:155], v252 offset:2048
	ds_read_b128 v[156:159], v252 offset:3072
	s_add_u32 s56, s22, 0x40100
	s_addc_u32 s57, s23, 0
	s_mov_b32 m0, s41
	ds_read_b128 v[168:171], v175 offset:32768
	ds_read_b128 v[176:179], v175 offset:33792
	ds_read_b128 v[180:183], v175 offset:34816
	ds_read_b128 v[184:187], v175 offset:35840
	ds_read_b128 v[188:191], v175 offset:36864
	ds_read_b128 v[192:195], v175 offset:37888
	ds_read_b128 v[196:199], v175 offset:38912
	ds_read_b128 v[200:203], v175 offset:39936
	global_load_lds_dwordx4 v160, s[56:57]
	s_mov_b32 m0, s42
	s_nop 0
	global_load_lds_dwordx4 v162, s[56:57]
	s_waitcnt vmcnt(8)
	s_waitcnt lgkmcnt(0)
	s_barrier
	s_setprio 1
	s_waitcnt lgkmcnt(0)
	v_mfma_f32_16x16x32_bf16 v[0:3], v[128:131], v[168:171], v[0:3]
	v_mfma_f32_16x16x32_bf16 v[4:7], v[136:139], v[168:171], v[4:7]
	v_mfma_f32_16x16x32_bf16 v[16:19], v[128:131], v[180:183], v[16:19]
	v_mfma_f32_16x16x32_bf16 v[20:23], v[136:139], v[180:183], v[20:23]
	v_mfma_f32_16x16x32_bf16 v[32:35], v[128:131], v[188:191], v[32:35]
	v_mfma_f32_16x16x32_bf16 v[36:39], v[136:139], v[188:191], v[36:39]
	v_mfma_f32_16x16x32_bf16 v[48:51], v[128:131], v[196:199], v[48:51]
	v_mfma_f32_16x16x32_bf16 v[52:55], v[136:139], v[196:199], v[52:55]
	v_mfma_f32_16x16x32_bf16 v[0:3], v[132:135], v[176:179], v[0:3]
	v_mfma_f32_16x16x32_bf16 v[4:7], v[140:143], v[176:179], v[4:7]
	v_mfma_f32_16x16x32_bf16 v[16:19], v[132:135], v[184:187], v[16:19]
	v_mfma_f32_16x16x32_bf16 v[20:23], v[140:143], v[184:187], v[20:23]
	v_mfma_f32_16x16x32_bf16 v[32:35], v[132:135], v[192:195], v[32:35]
	v_mfma_f32_16x16x32_bf16 v[36:39], v[140:143], v[192:195], v[36:39]
	v_mfma_f32_16x16x32_bf16 v[48:51], v[132:135], v[200:203], v[48:51]
	v_mfma_f32_16x16x32_bf16 v[52:55], v[140:143], v[200:203], v[52:55]
	v_mfma_f32_16x16x32_bf16 v[8:11], v[144:147], v[168:171], v[8:11]
	v_mfma_f32_16x16x32_bf16 v[24:27], v[144:147], v[180:183], v[24:27]
	v_mfma_f32_16x16x32_bf16 v[28:31], v[152:155], v[180:183], v[28:31]
	v_mfma_f32_16x16x32_bf16 v[44:47], v[152:155], v[188:191], v[44:47]
	v_mfma_f32_16x16x32_bf16 v[56:59], v[144:147], v[196:199], v[56:59]
	v_mfma_f32_16x16x32_bf16 v[60:63], v[152:155], v[196:199], v[60:63]
	v_mfma_f32_16x16x32_bf16 v[8:11], v[148:151], v[176:179], v[8:11]
	v_mfma_f32_16x16x32_bf16 v[12:15], v[152:155], v[168:171], v[12:15]
	v_mfma_f32_16x16x32_bf16 v[24:27], v[148:151], v[184:187], v[24:27]
	v_mfma_f32_16x16x32_bf16 v[28:31], v[156:159], v[184:187], v[28:31]
	v_mfma_f32_16x16x32_bf16 v[40:43], v[144:147], v[188:191], v[40:43]
	v_mfma_f32_16x16x32_bf16 v[44:47], v[156:159], v[192:195], v[44:47]
	v_mfma_f32_16x16x32_bf16 v[56:59], v[148:151], v[200:203], v[56:59]
	v_mfma_f32_16x16x32_bf16 v[60:63], v[156:159], v[200:203], v[60:63]
	v_mfma_f32_16x16x32_bf16 v[12:15], v[156:159], v[176:179], v[12:15]
	v_mfma_f32_16x16x32_bf16 v[40:43], v[148:151], v[192:195], v[40:43]
	s_setprio 0
	s_barrier
	s_add_i32 s56, s54, s38
	s_mov_b64 s[62:63], 0x180
	s_add_i32 s54, s56, 0x2000
	s_add_u32 s68, s24, s62
	s_addc_u32 s69, s25, s63
	s_mov_b32 m0, s56
	s_add_u32 s70, s24, s62
	s_addc_u32 s71, s25, s63
	s_add_u32 s58, s24, 0x10180
	ds_read_b128 v[168:171], v175 offset:49152
	ds_read_b128 v[176:179], v175 offset:50176
	ds_read_b128 v[180:183], v175 offset:51200
	ds_read_b128 v[184:187], v175 offset:52224
	ds_read_b128 v[188:191], v175 offset:53248
	ds_read_b128 v[192:195], v175 offset:54272
	ds_read_b128 v[196:199], v175 offset:55296
	ds_read_b128 v[200:203], v175 offset:56320
	global_load_lds_dwordx4 v232, s[68:69]
	s_mov_b32 m0, s54
	s_addc_u32 s59, s25, 0
	s_add_i32 s24, s60, s38
	global_load_lds_dwordx4 v164, s[70:71]
	s_mov_b32 m0, s24
	s_add_i32 s25, s24, 0x2000
	global_load_lds_dwordx4 v232, s[58:59]
	s_mov_b32 m0, s25
	s_nop 0
	global_load_lds_dwordx4 v164, s[58:59]
	s_add_u32 s68, s22, s62
	s_addc_u32 s69, s23, s63
	s_mov_b32 m0, s47
	s_nop 0
	global_load_lds_dwordx4 v160, s[68:69]
	s_add_u32 s68, s22, s62
	s_addc_u32 s69, s23, s63
	s_mov_b32 m0, s48
	s_nop 0
	global_load_lds_dwordx4 v162, s[68:69]
	s_waitcnt vmcnt(8)
	s_waitcnt lgkmcnt(0)
	s_barrier
	s_setprio 1
	s_waitcnt lgkmcnt(0)
	v_mfma_f32_16x16x32_bf16 v[64:67], v[128:131], v[168:171], v[64:67]
	v_mfma_f32_16x16x32_bf16 v[68:71], v[136:139], v[168:171], v[68:71]
	v_mfma_f32_16x16x32_bf16 v[84:87], v[136:139], v[180:183], v[84:87]
	v_mfma_f32_16x16x32_bf16 v[96:99], v[128:131], v[188:191], v[96:99]
	v_mfma_f32_16x16x32_bf16 v[112:115], v[128:131], v[196:199], v[112:115]
	v_mfma_f32_16x16x32_bf16 v[116:119], v[136:139], v[196:199], v[116:119]
	v_mfma_f32_16x16x32_bf16 v[64:67], v[132:135], v[176:179], v[64:67]
	v_mfma_f32_16x16x32_bf16 v[68:71], v[140:143], v[176:179], v[68:71]
	v_mfma_f32_16x16x32_bf16 v[80:83], v[128:131], v[180:183], v[80:83]
	v_mfma_f32_16x16x32_bf16 v[84:87], v[140:143], v[184:187], v[84:87]
	v_mfma_f32_16x16x32_bf16 v[96:99], v[132:135], v[192:195], v[96:99]
	v_mfma_f32_16x16x32_bf16 v[100:103], v[136:139], v[188:191], v[100:103]
	v_mfma_f32_16x16x32_bf16 v[112:115], v[132:135], v[200:203], v[112:115]
	v_mfma_f32_16x16x32_bf16 v[116:119], v[140:143], v[200:203], v[116:119]
	v_mfma_f32_16x16x32_bf16 v[80:83], v[132:135], v[184:187], v[80:83]
	v_mfma_f32_16x16x32_bf16 v[100:103], v[140:143], v[192:195], v[100:103]
	v_mfma_f32_16x16x32_bf16 v[72:75], v[144:147], v[168:171], v[72:75]
	v_mfma_f32_16x16x32_bf16 v[76:79], v[152:155], v[168:171], v[76:79]
	v_mfma_f32_16x16x32_bf16 v[88:91], v[144:147], v[180:183], v[88:91]
	v_mfma_f32_16x16x32_bf16 v[92:95], v[152:155], v[180:183], v[92:95]
	v_mfma_f32_16x16x32_bf16 v[104:107], v[144:147], v[188:191], v[104:107]
	v_mfma_f32_16x16x32_bf16 v[108:111], v[152:155], v[188:191], v[108:111]
	v_mfma_f32_16x16x32_bf16 v[124:127], v[152:155], v[196:199], v[124:127]
	v_mfma_f32_16x16x32_bf16 v[72:75], v[148:151], v[176:179], v[72:75]
	v_mfma_f32_16x16x32_bf16 v[76:79], v[156:159], v[176:179], v[76:79]
	v_mfma_f32_16x16x32_bf16 v[92:95], v[156:159], v[184:187], v[92:95]
	v_mfma_f32_16x16x32_bf16 v[104:107], v[148:151], v[192:195], v[104:107]
	v_mfma_f32_16x16x32_bf16 v[108:111], v[156:159], v[192:195], v[108:111]
	v_mfma_f32_16x16x32_bf16 v[120:123], v[144:147], v[196:199], v[120:123]
	v_mfma_f32_16x16x32_bf16 v[124:127], v[156:159], v[200:203], v[124:127]
	v_mfma_f32_16x16x32_bf16 v[88:91], v[148:151], v[184:187], v[88:91]
	v_mfma_f32_16x16x32_bf16 v[120:123], v[148:151], v[200:203], v[120:123]
	s_setprio 0
	s_barrier
	v_add_u32_e32 v253, 0x10000, v174
	ds_read_b128 v[128:131], v253
	ds_read_b128 v[132:135], v253 offset:1024
	ds_read_b128 v[136:139], v253 offset:2048
	ds_read_b128 v[140:143], v253 offset:3072
	v_add_u32_e32 v253, 0x14000, v174
	ds_read_b128 v[144:147], v253
	ds_read_b128 v[148:151], v253 offset:1024
	ds_read_b128 v[152:155], v253 offset:2048
	ds_read_b128 v[156:159], v253 offset:3072
	s_add_u32 s22, s22, 0x40180
	s_addc_u32 s23, s23, 0
	s_mov_b32 m0, s55
	ds_read_b128 v[168:171], v175
	ds_read_b128 v[176:179], v175 offset:1024
	ds_read_b128 v[180:183], v175 offset:2048
	ds_read_b128 v[184:187], v175 offset:3072
	ds_read_b128 v[188:191], v175 offset:4096
	ds_read_b128 v[192:195], v175 offset:5120
	ds_read_b128 v[196:199], v175 offset:6144
	ds_read_b128 v[200:203], v175 offset:7168
	global_load_lds_dwordx4 v160, s[22:23]
	s_mov_b32 m0, s13
	s_nop 0
	global_load_lds_dwordx4 v162, s[22:23]
	s_waitcnt vmcnt(8)
	s_waitcnt lgkmcnt(0)
	s_barrier
	s_setprio 1
	s_waitcnt lgkmcnt(0)
	v_mfma_f32_16x16x32_bf16 v[0:3], v[128:131], v[168:171], v[0:3]
	v_mfma_f32_16x16x32_bf16 v[4:7], v[136:139], v[168:171], v[4:7]
	v_mfma_f32_16x16x32_bf16 v[16:19], v[128:131], v[180:183], v[16:19]
	v_mfma_f32_16x16x32_bf16 v[20:23], v[136:139], v[180:183], v[20:23]
	v_mfma_f32_16x16x32_bf16 v[32:35], v[128:131], v[188:191], v[32:35]
	v_mfma_f32_16x16x32_bf16 v[36:39], v[136:139], v[188:191], v[36:39]
	v_mfma_f32_16x16x32_bf16 v[48:51], v[128:131], v[196:199], v[48:51]
	v_mfma_f32_16x16x32_bf16 v[0:3], v[132:135], v[176:179], v[0:3]
	v_mfma_f32_16x16x32_bf16 v[4:7], v[140:143], v[176:179], v[4:7]
	v_mfma_f32_16x16x32_bf16 v[16:19], v[132:135], v[184:187], v[16:19]
	v_mfma_f32_16x16x32_bf16 v[20:23], v[140:143], v[184:187], v[20:23]
	v_mfma_f32_16x16x32_bf16 v[32:35], v[132:135], v[192:195], v[32:35]
	v_mfma_f32_16x16x32_bf16 v[36:39], v[140:143], v[192:195], v[36:39]
	v_mfma_f32_16x16x32_bf16 v[48:51], v[132:135], v[200:203], v[48:51]
	v_mfma_f32_16x16x32_bf16 v[52:55], v[136:139], v[196:199], v[52:55]
	v_mfma_f32_16x16x32_bf16 v[52:55], v[140:143], v[200:203], v[52:55]
	v_mfma_f32_16x16x32_bf16 v[8:11], v[144:147], v[168:171], v[8:11]
	v_mfma_f32_16x16x32_bf16 v[24:27], v[144:147], v[180:183], v[24:27]
	v_mfma_f32_16x16x32_bf16 v[28:31], v[152:155], v[180:183], v[28:31]
	v_mfma_f32_16x16x32_bf16 v[44:47], v[152:155], v[188:191], v[44:47]
	v_mfma_f32_16x16x32_bf16 v[56:59], v[144:147], v[196:199], v[56:59]
	v_mfma_f32_16x16x32_bf16 v[60:63], v[152:155], v[196:199], v[60:63]
	v_mfma_f32_16x16x32_bf16 v[8:11], v[148:151], v[176:179], v[8:11]
	v_mfma_f32_16x16x32_bf16 v[12:15], v[152:155], v[168:171], v[12:15]
	v_mfma_f32_16x16x32_bf16 v[24:27], v[148:151], v[184:187], v[24:27]
	v_mfma_f32_16x16x32_bf16 v[28:31], v[156:159], v[184:187], v[28:31]
	v_mfma_f32_16x16x32_bf16 v[40:43], v[144:147], v[188:191], v[40:43]
	v_mfma_f32_16x16x32_bf16 v[44:47], v[156:159], v[192:195], v[44:47]
	v_mfma_f32_16x16x32_bf16 v[56:59], v[148:151], v[200:203], v[56:59]
	v_mfma_f32_16x16x32_bf16 v[60:63], v[156:159], v[200:203], v[60:63]
	v_mfma_f32_16x16x32_bf16 v[12:15], v[156:159], v[176:179], v[12:15]
	v_mfma_f32_16x16x32_bf16 v[40:43], v[148:151], v[192:195], v[40:43]
	s_setprio 0
	s_barrier
	s_mov_b32 m0, s53
	s_add_u32 s22, s26, 0x10000
	ds_read_b128 v[168:171], v175 offset:16384
	ds_read_b128 v[176:179], v175 offset:17408
	ds_read_b128 v[180:183], v175 offset:18432
	ds_read_b128 v[184:187], v175 offset:19456
	ds_read_b128 v[188:191], v175 offset:20480
	ds_read_b128 v[192:195], v175 offset:21504
	ds_read_b128 v[196:199], v175 offset:22528
	ds_read_b128 v[200:203], v175 offset:23552
	global_load_lds_dwordx4 v232, s[26:27]
	s_mov_b32 m0, s15
	s_addc_u32 s23, s27, 0
	global_load_lds_dwordx4 v164, s[26:27]
	s_mov_b32 m0, s21
	s_nop 0
	global_load_lds_dwordx4 v232, s[22:23]
	s_mov_b32 m0, s52
	s_nop 0
	global_load_lds_dwordx4 v164, s[22:23]
	s_mov_b32 m0, s39
	s_nop 0
	global_load_lds_dwordx4 v160, s[28:29]
	s_mov_b32 m0, s40
	s_nop 0
	global_load_lds_dwordx4 v162, s[28:29]
	s_waitcnt vmcnt(8)
	s_waitcnt lgkmcnt(0)
	s_barrier
	s_setprio 1
	s_waitcnt lgkmcnt(0)
	v_mfma_f32_16x16x32_bf16 v[64:67], v[128:131], v[168:171], v[64:67]
	v_mfma_f32_16x16x32_bf16 v[64:67], v[132:135], v[176:179], v[64:67]
	v_mfma_f32_16x16x32_bf16 v[68:71], v[136:139], v[168:171], v[68:71]
	v_mfma_f32_16x16x32_bf16 v[68:71], v[140:143], v[176:179], v[68:71]
	v_mfma_f32_16x16x32_bf16 v[80:83], v[128:131], v[180:183], v[80:83]
	v_mfma_f32_16x16x32_bf16 v[80:83], v[132:135], v[184:187], v[80:83]
	v_mfma_f32_16x16x32_bf16 v[84:87], v[136:139], v[180:183], v[84:87]
	v_mfma_f32_16x16x32_bf16 v[84:87], v[140:143], v[184:187], v[84:87]
	v_mfma_f32_16x16x32_bf16 v[96:99], v[128:131], v[188:191], v[96:99]
	v_mfma_f32_16x16x32_bf16 v[112:115], v[128:131], v[196:199], v[112:115]
	v_mfma_f32_16x16x32_bf16 v[116:119], v[136:139], v[196:199], v[116:119]
	v_mfma_f32_16x16x32_bf16 v[96:99], v[132:135], v[192:195], v[96:99]
	v_mfma_f32_16x16x32_bf16 v[100:103], v[136:139], v[188:191], v[100:103]
	v_mfma_f32_16x16x32_bf16 v[112:115], v[132:135], v[200:203], v[112:115]
	v_mfma_f32_16x16x32_bf16 v[116:119], v[140:143], v[200:203], v[116:119]
	v_mfma_f32_16x16x32_bf16 v[100:103], v[140:143], v[192:195], v[100:103]
	v_mfma_f32_16x16x32_bf16 v[72:75], v[144:147], v[168:171], v[72:75]
	v_mfma_f32_16x16x32_bf16 v[72:75], v[148:151], v[176:179], v[72:75]
	v_mfma_f32_16x16x32_bf16 v[76:79], v[152:155], v[168:171], v[76:79]
	v_mfma_f32_16x16x32_bf16 v[76:79], v[156:159], v[176:179], v[76:79]
	v_mfma_f32_16x16x32_bf16 v[88:91], v[144:147], v[180:183], v[88:91]
	v_mfma_f32_16x16x32_bf16 v[88:91], v[148:151], v[184:187], v[88:91]
	v_mfma_f32_16x16x32_bf16 v[92:95], v[152:155], v[180:183], v[92:95]
	v_mfma_f32_16x16x32_bf16 v[92:95], v[156:159], v[184:187], v[92:95]
	v_mfma_f32_16x16x32_bf16 v[104:107], v[144:147], v[188:191], v[104:107]
	v_mfma_f32_16x16x32_bf16 v[104:107], v[148:151], v[192:195], v[104:107]
	v_mfma_f32_16x16x32_bf16 v[108:111], v[152:155], v[188:191], v[108:111]
	v_mfma_f32_16x16x32_bf16 v[108:111], v[156:159], v[192:195], v[108:111]
	v_mfma_f32_16x16x32_bf16 v[120:123], v[144:147], v[196:199], v[120:123]
	v_mfma_f32_16x16x32_bf16 v[120:123], v[148:151], v[200:203], v[120:123]
	v_mfma_f32_16x16x32_bf16 v[124:127], v[152:155], v[196:199], v[124:127]
	v_mfma_f32_16x16x32_bf16 v[124:127], v[156:159], v[200:203], v[124:127]
	s_setprio 0
	s_barrier
	s_nop 4
	v_add_u32_e32 v253, 0x18000, v174
	ds_read_b128 v[128:131], v253
	ds_read_b128 v[132:135], v253 offset:1024
	ds_read_b128 v[136:139], v253 offset:2048
	ds_read_b128 v[140:143], v253 offset:3072
	v_add_u32_e32 v253, 0x1c000, v174
	ds_read_b128 v[144:147], v253
	ds_read_b128 v[148:151], v253 offset:1024
	ds_read_b128 v[152:155], v253 offset:2048
	ds_read_b128 v[156:159], v253 offset:3072
	s_add_u32 s22, s28, 0x40000
	s_addc_u32 s23, s29, 0
	s_mov_b32 m0, s41
	ds_read_b128 v[168:171], v175 offset:32768
	ds_read_b128 v[176:179], v175 offset:33792
	ds_read_b128 v[180:183], v175 offset:34816
	ds_read_b128 v[184:187], v175 offset:35840
	ds_read_b128 v[188:191], v175 offset:36864
	ds_read_b128 v[192:195], v175 offset:37888
	ds_read_b128 v[196:199], v175 offset:38912
	ds_read_b128 v[200:203], v175 offset:39936
	global_load_lds_dwordx4 v160, s[22:23]
	s_mov_b32 m0, s42
	s_nop 0
	global_load_lds_dwordx4 v162, s[22:23]
	s_waitcnt vmcnt(8)
	s_waitcnt lgkmcnt(0)
	s_barrier
	s_setprio 1
	s_waitcnt lgkmcnt(0)
	v_mfma_f32_16x16x32_bf16 v[0:3], v[128:131], v[168:171], v[0:3]
	v_mfma_f32_16x16x32_bf16 v[0:3], v[132:135], v[176:179], v[0:3]
	v_mfma_f32_16x16x32_bf16 v[4:7], v[136:139], v[168:171], v[4:7]
	v_mfma_f32_16x16x32_bf16 v[4:7], v[140:143], v[176:179], v[4:7]
	v_mfma_f32_16x16x32_bf16 v[16:19], v[128:131], v[180:183], v[16:19]
	v_mfma_f32_16x16x32_bf16 v[16:19], v[132:135], v[184:187], v[16:19]
	v_mfma_f32_16x16x32_bf16 v[20:23], v[136:139], v[180:183], v[20:23]
	v_mfma_f32_16x16x32_bf16 v[20:23], v[140:143], v[184:187], v[20:23]
	v_mfma_f32_16x16x32_bf16 v[32:35], v[128:131], v[188:191], v[32:35]
	v_mfma_f32_16x16x32_bf16 v[32:35], v[132:135], v[192:195], v[32:35]
	v_mfma_f32_16x16x32_bf16 v[36:39], v[136:139], v[188:191], v[36:39]
	v_mfma_f32_16x16x32_bf16 v[36:39], v[140:143], v[192:195], v[36:39]
	v_mfma_f32_16x16x32_bf16 v[48:51], v[128:131], v[196:199], v[48:51]
	v_mfma_f32_16x16x32_bf16 v[48:51], v[132:135], v[200:203], v[48:51]
	v_mfma_f32_16x16x32_bf16 v[52:55], v[136:139], v[196:199], v[52:55]
	v_mfma_f32_16x16x32_bf16 v[52:55], v[140:143], v[200:203], v[52:55]
	v_mfma_f32_16x16x32_bf16 v[12:15], v[152:155], v[168:171], v[12:15]
	v_mfma_f32_16x16x32_bf16 v[12:15], v[156:159], v[176:179], v[12:15]
	v_mfma_f32_16x16x32_bf16 v[24:27], v[144:147], v[180:183], v[24:27]
	v_mfma_f32_16x16x32_bf16 v[24:27], v[148:151], v[184:187], v[24:27]
	v_mfma_f32_16x16x32_bf16 v[28:31], v[152:155], v[180:183], v[28:31]
	v_mfma_f32_16x16x32_bf16 v[8:11], v[144:147], v[168:171], v[8:11]
	v_mfma_f32_16x16x32_bf16 v[28:31], v[156:159], v[184:187], v[28:31]
	v_mfma_f32_16x16x32_bf16 v[40:43], v[144:147], v[188:191], v[40:43]
	v_mfma_f32_16x16x32_bf16 v[8:11], v[148:151], v[176:179], v[8:11]
	v_mfma_f32_16x16x32_bf16 v[40:43], v[148:151], v[192:195], v[40:43]
	v_mfma_f32_16x16x32_bf16 v[44:47], v[152:155], v[188:191], v[44:47]
	v_mfma_f32_16x16x32_bf16 v[44:47], v[156:159], v[192:195], v[44:47]
	v_mfma_f32_16x16x32_bf16 v[56:59], v[144:147], v[196:199], v[56:59]
	v_mfma_f32_16x16x32_bf16 v[56:59], v[148:151], v[200:203], v[56:59]
	v_mfma_f32_16x16x32_bf16 v[60:63], v[152:155], v[196:199], v[60:63]
	v_mfma_f32_16x16x32_bf16 v[60:63], v[156:159], v[200:203], v[60:63]
	s_setprio 0
	s_barrier
	s_mov_b32 m0, s56
	s_add_u32 s68, s26, s94
	s_addc_u32 s69, s27, s95
	s_add_u32 s70, s26, s94
	s_addc_u32 s71, s27, s95
	s_add_u32 s22, s26, 0x10080
	s_nop 1
	ds_read_b128 v[168:171], v175 offset:49152
	ds_read_b128 v[176:179], v175 offset:50176
	ds_read_b128 v[180:183], v175 offset:51200
	ds_read_b128 v[184:187], v175 offset:52224
	ds_read_b128 v[188:191], v175 offset:53248
	ds_read_b128 v[192:195], v175 offset:54272
	ds_read_b128 v[196:199], v175 offset:55296
	ds_read_b128 v[200:203], v175 offset:56320
	global_load_lds_dwordx4 v232, s[68:69]
	s_mov_b32 m0, s54
	s_addc_u32 s23, s27, 0
	global_load_lds_dwordx4 v164, s[70:71]
	s_mov_b32 m0, s24
	s_nop 0
	global_load_lds_dwordx4 v232, s[22:23]
	s_mov_b32 m0, s25
	s_nop 0
	global_load_lds_dwordx4 v164, s[22:23]
	s_add_u32 s68, s28, s94
	s_addc_u32 s69, s29, s95
	s_mov_b32 m0, s47
	s_nop 0
	global_load_lds_dwordx4 v160, s[68:69]
	s_add_u32 s68, s28, s94
	s_addc_u32 s69, s29, s95
	s_mov_b32 m0, s48
	s_nop 0
	global_load_lds_dwordx4 v162, s[68:69]
	s_waitcnt vmcnt(8)
	s_waitcnt lgkmcnt(0)
	s_barrier
	s_setprio 1
	s_waitcnt lgkmcnt(0)
	v_mfma_f32_16x16x32_bf16 v[64:67], v[128:131], v[168:171], v[64:67]
	v_mfma_f32_16x16x32_bf16 v[64:67], v[132:135], v[176:179], v[64:67]
	v_mfma_f32_16x16x32_bf16 v[68:71], v[136:139], v[168:171], v[68:71]
	v_mfma_f32_16x16x32_bf16 v[68:71], v[140:143], v[176:179], v[68:71]
	v_mfma_f32_16x16x32_bf16 v[80:83], v[128:131], v[180:183], v[80:83]
	v_mfma_f32_16x16x32_bf16 v[80:83], v[132:135], v[184:187], v[80:83]
	v_mfma_f32_16x16x32_bf16 v[84:87], v[136:139], v[180:183], v[84:87]
	v_mfma_f32_16x16x32_bf16 v[84:87], v[140:143], v[184:187], v[84:87]
	v_mfma_f32_16x16x32_bf16 v[96:99], v[128:131], v[188:191], v[96:99]
	v_mfma_f32_16x16x32_bf16 v[112:115], v[128:131], v[196:199], v[112:115]
	v_mfma_f32_16x16x32_bf16 v[96:99], v[132:135], v[192:195], v[96:99]
	v_mfma_f32_16x16x32_bf16 v[100:103], v[136:139], v[188:191], v[100:103]
	v_mfma_f32_16x16x32_bf16 v[112:115], v[132:135], v[200:203], v[112:115]
	v_mfma_f32_16x16x32_bf16 v[116:119], v[136:139], v[196:199], v[116:119]
	v_mfma_f32_16x16x32_bf16 v[100:103], v[140:143], v[192:195], v[100:103]
	v_mfma_f32_16x16x32_bf16 v[116:119], v[140:143], v[200:203], v[116:119]
	v_mfma_f32_16x16x32_bf16 v[72:75], v[144:147], v[168:171], v[72:75]
	v_mfma_f32_16x16x32_bf16 v[72:75], v[148:151], v[176:179], v[72:75]
	v_mfma_f32_16x16x32_bf16 v[76:79], v[152:155], v[168:171], v[76:79]
	v_mfma_f32_16x16x32_bf16 v[76:79], v[156:159], v[176:179], v[76:79]
	v_mfma_f32_16x16x32_bf16 v[88:91], v[144:147], v[180:183], v[88:91]
	v_mfma_f32_16x16x32_bf16 v[88:91], v[148:151], v[184:187], v[88:91]
	v_mfma_f32_16x16x32_bf16 v[92:95], v[152:155], v[180:183], v[92:95]
	v_mfma_f32_16x16x32_bf16 v[92:95], v[156:159], v[184:187], v[92:95]
	v_mfma_f32_16x16x32_bf16 v[104:107], v[144:147], v[188:191], v[104:107]
	v_mfma_f32_16x16x32_bf16 v[104:107], v[148:151], v[192:195], v[104:107]
	v_mfma_f32_16x16x32_bf16 v[108:111], v[152:155], v[188:191], v[108:111]
	v_mfma_f32_16x16x32_bf16 v[108:111], v[156:159], v[192:195], v[108:111]
	v_mfma_f32_16x16x32_bf16 v[120:123], v[144:147], v[196:199], v[120:123]
	v_mfma_f32_16x16x32_bf16 v[120:123], v[148:151], v[200:203], v[120:123]
	v_mfma_f32_16x16x32_bf16 v[124:127], v[152:155], v[196:199], v[124:127]
	v_mfma_f32_16x16x32_bf16 v[124:127], v[156:159], v[200:203], v[124:127]
	s_setprio 0
	s_barrier
	s_andn2_b64 vcc, exec, s[10:11]
	s_cbranch_vccnz .LBB0_1020
	s_barrier

.LBB0_1163:
	s_ashr_i32 s23, s22, 31
	s_lshl_b64 s[24:25], s[22:23], 19
	s_add_u32 s24, s42, s24
	s_addc_u32 s25, s43, s25
	s_and_b64 s[26:27], s[4:5], exec
	s_cselect_b32 s23, s25, s35
	s_cselect_b32 s56, s24, s34
	s_ashr_i32 s21, s20, 31
	s_lshl_b64 s[26:27], s[20:21], 19
	s_add_u32 s26, s44, s26
	s_addc_u32 s27, s45, s27
	s_and_b64 s[36:37], s[4:5], exec
	s_cselect_b32 s21, s27, s31
	s_cselect_b32 s57, s26, s30
	s_add_u32 s58, s30, 0x100
	s_addc_u32 s59, s31, 0
	s_add_u32 s30, s34, 0x40080
	s_addc_u32 s31, s35, 0
	s_mov_b32 s60, -2
	s_waitcnt vmcnt(0)
	s_add_u32 s34, s30, 0xfffc0080
	s_addc_u32 s35, s31, -1
	s_add_i32 s61, 0, 0x10000
	s_cmp_eq_u32 s60, 12
	s_cselect_b32 s37, s23, s35
	s_cselect_b32 s36, s56, s34
	s_cselect_b32 s35, s21, s59
	s_cselect_b32 s34, s57, s58
	s_add_i32 s64, 0, 0x14000
	v_add_u32_e32 v140, s61, v174
	v_add_u32_e32 v166, s64, v174
	ds_read_b128 v[128:131], v140
	ds_read_b128 v[132:135], v140 offset:1024
	ds_read_b128 v[136:139], v140 offset:2048
	ds_read_b128 v[140:143], v140 offset:3072
	ds_read_b128 v[154:157], v166
	ds_read_b128 v[158:161], v166 offset:1024
	ds_read_b128 v[162:165], v166 offset:2048
	ds_read_b128 v[166:169], v166 offset:3072
	v_lshl_add_u64 v[204:205], s[30:31], 0, v[152:153]
	s_add_i32 m0, s29, 0xc000
	ds_read_b128 v[170:173], v175
	ds_read_b128 v[176:179], v175 offset:1024
	ds_read_b128 v[180:183], v175 offset:2048
	ds_read_b128 v[184:187], v175 offset:3072
	ds_read_b128 v[188:191], v175 offset:4096
	ds_read_b128 v[192:195], v175 offset:5120
	ds_read_b128 v[196:199], v175 offset:6144
	ds_read_b128 v[200:203], v175 offset:7168
	global_load_lds_dwordx4 v[204:205], off
	v_lshl_add_u64 v[204:205], s[30:31], 0, v[150:151]
	s_add_i32 m0, s29, 0xe000
	s_nop 0
	global_load_lds_dwordx4 v[204:205], off
	s_waitcnt vmcnt(8)
	s_waitcnt lgkmcnt(0)
	s_barrier
	s_setprio 1
	s_waitcnt lgkmcnt(0)
	v_mfma_f32_16x16x32_bf16 v[124:127], v[128:131], v[170:173], 0
	v_mfma_f32_16x16x32_bf16 v[120:123], v[136:139], v[170:173], 0
	v_mfma_f32_16x16x32_bf16 v[108:111], v[128:131], v[180:183], 0
	v_mfma_f32_16x16x32_bf16 v[104:107], v[136:139], v[180:183], 0
	v_mfma_f32_16x16x32_bf16 v[92:95], v[128:131], v[188:191], 0
	v_mfma_f32_16x16x32_bf16 v[88:91], v[136:139], v[188:191], 0
	v_mfma_f32_16x16x32_bf16 v[80:83], v[128:131], v[196:199], 0
	v_mfma_f32_16x16x32_bf16 v[72:75], v[136:139], v[196:199], 0
	v_mfma_f32_16x16x32_bf16 v[124:127], v[132:135], v[176:179], v[124:127]
	v_mfma_f32_16x16x32_bf16 v[120:123], v[140:143], v[176:179], v[120:123]
	v_mfma_f32_16x16x32_bf16 v[108:111], v[132:135], v[184:187], v[108:111]
	v_mfma_f32_16x16x32_bf16 v[104:107], v[140:143], v[184:187], v[104:107]
	v_mfma_f32_16x16x32_bf16 v[92:95], v[132:135], v[192:195], v[92:95]
	v_mfma_f32_16x16x32_bf16 v[88:91], v[140:143], v[192:195], v[88:91]
	v_mfma_f32_16x16x32_bf16 v[80:83], v[132:135], v[200:203], v[80:83]
	v_mfma_f32_16x16x32_bf16 v[72:75], v[140:143], v[200:203], v[72:75]
	v_mfma_f32_16x16x32_bf16 v[116:119], v[154:157], v[170:173], 0
	v_mfma_f32_16x16x32_bf16 v[112:115], v[162:165], v[170:173], 0
	v_mfma_f32_16x16x32_bf16 v[100:103], v[154:157], v[180:183], 0
	v_mfma_f32_16x16x32_bf16 v[96:99], v[162:165], v[180:183], 0
	v_mfma_f32_16x16x32_bf16 v[84:87], v[154:157], v[188:191], 0
	v_mfma_f32_16x16x32_bf16 v[76:79], v[162:165], v[188:191], 0
	v_mfma_f32_16x16x32_bf16 v[68:71], v[154:157], v[196:199], 0
	v_mfma_f32_16x16x32_bf16 v[64:67], v[162:165], v[196:199], 0
	v_mfma_f32_16x16x32_bf16 v[116:119], v[158:161], v[176:179], v[116:119]
	v_mfma_f32_16x16x32_bf16 v[112:115], v[166:169], v[176:179], v[112:115]
	v_mfma_f32_16x16x32_bf16 v[100:103], v[158:161], v[184:187], v[100:103]
	v_mfma_f32_16x16x32_bf16 v[96:99], v[166:169], v[184:187], v[96:99]
	v_mfma_f32_16x16x32_bf16 v[84:87], v[158:161], v[192:195], v[84:87]
	v_mfma_f32_16x16x32_bf16 v[76:79], v[166:169], v[192:195], v[76:79]
	v_mfma_f32_16x16x32_bf16 v[68:71], v[158:161], v[200:203], v[68:71]
	v_mfma_f32_16x16x32_bf16 v[64:67], v[166:169], v[200:203], v[64:67]
	s_setprio 0
	s_barrier
	s_add_i32 s61, s61, s41
	v_lshl_add_u64 v[204:205], s[34:35], 0, v[232:233]
	s_mov_b32 m0, s61
	ds_read_b128 v[170:173], v175 offset:16384
	ds_read_b128 v[176:179], v175 offset:17408
	ds_read_b128 v[180:183], v175 offset:18432
	ds_read_b128 v[184:187], v175 offset:19456
	ds_read_b128 v[188:191], v175 offset:20480
	ds_read_b128 v[192:195], v175 offset:21504
	ds_read_b128 v[196:199], v175 offset:22528
	ds_read_b128 v[200:203], v175 offset:23552
	global_load_lds_dwordx4 v[204:205], off
	s_add_i32 m0, s61, 0x2000
	s_add_u32 s62, s34, 0x40000
	v_lshl_add_u64 v[206:207], s[34:35], 0, v[148:149]
	s_addc_u32 s63, s35, 0
	s_add_i32 s61, s64, s41
	global_load_lds_dwordx4 v[206:207], off
	v_lshl_add_u64 v[208:209], s[62:63], 0, v[232:233]
	s_mov_b32 m0, s61
	v_lshl_add_u64 v[210:211], s[36:37], 0, v[146:147]
	global_load_lds_dwordx4 v[208:209], off
	v_lshl_add_u64 v[208:209], s[62:63], 0, v[148:149]
	s_add_i32 m0, s61, 0x2000
	s_nop 0
	global_load_lds_dwordx4 v[208:209], off
	v_lshl_add_u64 v[208:209], s[36:37], 0, v[144:145]
	s_waitcnt vmcnt(6)
	s_waitcnt lgkmcnt(0)
	s_barrier
	s_setprio 1
	s_waitcnt lgkmcnt(0)
	v_mfma_f32_16x16x32_bf16 v[60:63], v[128:131], v[170:173], 0
	v_mfma_f32_16x16x32_bf16 v[56:59], v[136:139], v[170:173], 0
	v_mfma_f32_16x16x32_bf16 v[48:51], v[128:131], v[180:183], 0
	v_mfma_f32_16x16x32_bf16 v[40:43], v[136:139], v[180:183], 0
	v_mfma_f32_16x16x32_bf16 v[28:31], v[128:131], v[188:191], 0
	v_mfma_f32_16x16x32_bf16 v[24:27], v[136:139], v[188:191], 0
	v_mfma_f32_16x16x32_bf16 v[16:19], v[128:131], v[196:199], 0
	v_mfma_f32_16x16x32_bf16 v[8:11], v[136:139], v[196:199], 0
	v_mfma_f32_16x16x32_bf16 v[60:63], v[132:135], v[176:179], v[60:63]
	v_mfma_f32_16x16x32_bf16 v[56:59], v[140:143], v[176:179], v[56:59]
	v_mfma_f32_16x16x32_bf16 v[48:51], v[132:135], v[184:187], v[48:51]
	v_mfma_f32_16x16x32_bf16 v[40:43], v[140:143], v[184:187], v[40:43]
	v_mfma_f32_16x16x32_bf16 v[28:31], v[132:135], v[192:195], v[28:31]
	v_mfma_f32_16x16x32_bf16 v[24:27], v[140:143], v[192:195], v[24:27]
	v_mfma_f32_16x16x32_bf16 v[16:19], v[132:135], v[200:203], v[16:19]
	v_mfma_f32_16x16x32_bf16 v[8:11], v[140:143], v[200:203], v[8:11]
	v_mfma_f32_16x16x32_bf16 v[52:55], v[154:157], v[170:173], 0
	v_mfma_f32_16x16x32_bf16 v[44:47], v[162:165], v[170:173], 0
	v_mfma_f32_16x16x32_bf16 v[36:39], v[154:157], v[180:183], 0
	v_mfma_f32_16x16x32_bf16 v[32:35], v[162:165], v[180:183], 0
	v_mfma_f32_16x16x32_bf16 v[20:23], v[154:157], v[188:191], 0
	v_mfma_f32_16x16x32_bf16 v[12:15], v[162:165], v[188:191], 0
	v_mfma_f32_16x16x32_bf16 v[4:7], v[154:157], v[196:199], 0
	v_mfma_f32_16x16x32_bf16 v[0:3], v[162:165], v[196:199], 0
	v_mfma_f32_16x16x32_bf16 v[52:55], v[158:161], v[176:179], v[52:55]
	v_mfma_f32_16x16x32_bf16 v[44:47], v[166:169], v[176:179], v[44:47]
	v_mfma_f32_16x16x32_bf16 v[36:39], v[158:161], v[184:187], v[36:39]
	v_mfma_f32_16x16x32_bf16 v[32:35], v[166:169], v[184:187], v[32:35]
	v_mfma_f32_16x16x32_bf16 v[20:23], v[158:161], v[192:195], v[20:23]
	v_mfma_f32_16x16x32_bf16 v[12:15], v[166:169], v[192:195], v[12:15]
	v_mfma_f32_16x16x32_bf16 v[4:7], v[158:161], v[200:203], v[4:7]
	v_mfma_f32_16x16x32_bf16 v[0:3], v[166:169], v[200:203], v[0:3]
	s_setprio 0
	s_barrier
	s_branch .Lzmid_3
.LBB0_1164:
	s_add_u32 s34, s30, 0xfffc0080
	s_addc_u32 s35, s31, -1
	s_add_i32 s61, 0, 0x10000
	s_cmp_eq_u32 s60, 12
	s_cselect_b32 s37, s23, s35
	s_cselect_b32 s36, s56, s34
	s_cselect_b32 s35, s21, s59
	s_cselect_b32 s34, s57, s58
	s_add_i32 s64, 0, 0x14000
	v_add_u32_e32 v140, s61, v174
	v_add_u32_e32 v166, s64, v174
	ds_read_b128 v[128:131], v140
	ds_read_b128 v[132:135], v140 offset:1024
	ds_read_b128 v[136:139], v140 offset:2048
	ds_read_b128 v[140:143], v140 offset:3072
	ds_read_b128 v[154:157], v166
	ds_read_b128 v[158:161], v166 offset:1024
	ds_read_b128 v[162:165], v166 offset:2048
	ds_read_b128 v[166:169], v166 offset:3072
	v_lshl_add_u64 v[204:205], s[30:31], 0, v[152:153]
	s_add_i32 m0, s29, 0xc000
	ds_read_b128 v[170:173], v175
	ds_read_b128 v[176:179], v175 offset:1024
	ds_read_b128 v[180:183], v175 offset:2048
	ds_read_b128 v[184:187], v175 offset:3072
	ds_read_b128 v[188:191], v175 offset:4096
	ds_read_b128 v[192:195], v175 offset:5120
	ds_read_b128 v[196:199], v175 offset:6144
	ds_read_b128 v[200:203], v175 offset:7168
	global_load_lds_dwordx4 v[204:205], off
	v_lshl_add_u64 v[204:205], s[30:31], 0, v[150:151]
	s_add_i32 m0, s29, 0xe000
	s_nop 0
	global_load_lds_dwordx4 v[204:205], off
	s_waitcnt vmcnt(8)
	s_waitcnt lgkmcnt(0)
	s_barrier
	s_setprio 1
	s_waitcnt lgkmcnt(0)
	v_mfma_f32_16x16x32_bf16 v[124:127], v[128:131], v[170:173], v[124:127]
	v_mfma_f32_16x16x32_bf16 v[120:123], v[136:139], v[170:173], v[120:123]
	v_mfma_f32_16x16x32_bf16 v[108:111], v[128:131], v[180:183], v[108:111]
	v_mfma_f32_16x16x32_bf16 v[104:107], v[136:139], v[180:183], v[104:107]
	v_mfma_f32_16x16x32_bf16 v[92:95], v[128:131], v[188:191], v[92:95]
	v_mfma_f32_16x16x32_bf16 v[88:91], v[136:139], v[188:191], v[88:91]
	v_mfma_f32_16x16x32_bf16 v[80:83], v[128:131], v[196:199], v[80:83]
	v_mfma_f32_16x16x32_bf16 v[72:75], v[136:139], v[196:199], v[72:75]
	v_mfma_f32_16x16x32_bf16 v[124:127], v[132:135], v[176:179], v[124:127]
	v_mfma_f32_16x16x32_bf16 v[120:123], v[140:143], v[176:179], v[120:123]
	v_mfma_f32_16x16x32_bf16 v[108:111], v[132:135], v[184:187], v[108:111]
	v_mfma_f32_16x16x32_bf16 v[104:107], v[140:143], v[184:187], v[104:107]
	v_mfma_f32_16x16x32_bf16 v[92:95], v[132:135], v[192:195], v[92:95]
	v_mfma_f32_16x16x32_bf16 v[88:91], v[140:143], v[192:195], v[88:91]
	v_mfma_f32_16x16x32_bf16 v[80:83], v[132:135], v[200:203], v[80:83]
	v_mfma_f32_16x16x32_bf16 v[72:75], v[140:143], v[200:203], v[72:75]
	v_mfma_f32_16x16x32_bf16 v[116:119], v[154:157], v[170:173], v[116:119]
	v_mfma_f32_16x16x32_bf16 v[112:115], v[162:165], v[170:173], v[112:115]
	v_mfma_f32_16x16x32_bf16 v[100:103], v[154:157], v[180:183], v[100:103]
	v_mfma_f32_16x16x32_bf16 v[96:99], v[162:165], v[180:183], v[96:99]
	v_mfma_f32_16x16x32_bf16 v[84:87], v[154:157], v[188:191], v[84:87]
	v_mfma_f32_16x16x32_bf16 v[76:79], v[162:165], v[188:191], v[76:79]
	v_mfma_f32_16x16x32_bf16 v[68:71], v[154:157], v[196:199], v[68:71]
	v_mfma_f32_16x16x32_bf16 v[64:67], v[162:165], v[196:199], v[64:67]
	v_mfma_f32_16x16x32_bf16 v[116:119], v[158:161], v[176:179], v[116:119]
	v_mfma_f32_16x16x32_bf16 v[112:115], v[166:169], v[176:179], v[112:115]
	v_mfma_f32_16x16x32_bf16 v[100:103], v[158:161], v[184:187], v[100:103]
	v_mfma_f32_16x16x32_bf16 v[96:99], v[166:169], v[184:187], v[96:99]
	v_mfma_f32_16x16x32_bf16 v[84:87], v[158:161], v[192:195], v[84:87]
	v_mfma_f32_16x16x32_bf16 v[76:79], v[166:169], v[192:195], v[76:79]
	v_mfma_f32_16x16x32_bf16 v[68:71], v[158:161], v[200:203], v[68:71]
	v_mfma_f32_16x16x32_bf16 v[64:67], v[166:169], v[200:203], v[64:67]
	s_setprio 0
	s_barrier
	s_add_i32 s61, s61, s41
	v_lshl_add_u64 v[204:205], s[34:35], 0, v[232:233]
	s_mov_b32 m0, s61
	ds_read_b128 v[170:173], v175 offset:16384
	ds_read_b128 v[176:179], v175 offset:17408
	ds_read_b128 v[180:183], v175 offset:18432
	ds_read_b128 v[184:187], v175 offset:19456
	ds_read_b128 v[188:191], v175 offset:20480
	ds_read_b128 v[192:195], v175 offset:21504
	ds_read_b128 v[196:199], v175 offset:22528
	ds_read_b128 v[200:203], v175 offset:23552
	global_load_lds_dwordx4 v[204:205], off
	s_add_i32 m0, s61, 0x2000
	s_add_u32 s62, s34, 0x40000
	v_lshl_add_u64 v[206:207], s[34:35], 0, v[148:149]
	s_addc_u32 s63, s35, 0
	s_add_i32 s61, s64, s41
	global_load_lds_dwordx4 v[206:207], off
	v_lshl_add_u64 v[208:209], s[62:63], 0, v[232:233]
	s_mov_b32 m0, s61
	v_lshl_add_u64 v[210:211], s[36:37], 0, v[146:147]
	global_load_lds_dwordx4 v[208:209], off
	v_lshl_add_u64 v[208:209], s[62:63], 0, v[148:149]
	s_add_i32 m0, s61, 0x2000
	s_nop 0
	global_load_lds_dwordx4 v[208:209], off
	v_lshl_add_u64 v[208:209], s[36:37], 0, v[144:145]
	s_waitcnt vmcnt(6)
	s_waitcnt lgkmcnt(0)
	s_barrier
	s_setprio 1
	s_waitcnt lgkmcnt(0)
	v_mfma_f32_16x16x32_bf16 v[60:63], v[128:131], v[170:173], v[60:63]
	v_mfma_f32_16x16x32_bf16 v[56:59], v[136:139], v[170:173], v[56:59]
	v_mfma_f32_16x16x32_bf16 v[48:51], v[128:131], v[180:183], v[48:51]
	v_mfma_f32_16x16x32_bf16 v[40:43], v[136:139], v[180:183], v[40:43]
	v_mfma_f32_16x16x32_bf16 v[28:31], v[128:131], v[188:191], v[28:31]
	v_mfma_f32_16x16x32_bf16 v[24:27], v[136:139], v[188:191], v[24:27]
	v_mfma_f32_16x16x32_bf16 v[16:19], v[128:131], v[196:199], v[16:19]
	v_mfma_f32_16x16x32_bf16 v[8:11], v[136:139], v[196:199], v[8:11]
	v_mfma_f32_16x16x32_bf16 v[60:63], v[132:135], v[176:179], v[60:63]
	v_mfma_f32_16x16x32_bf16 v[56:59], v[140:143], v[176:179], v[56:59]
	v_mfma_f32_16x16x32_bf16 v[48:51], v[132:135], v[184:187], v[48:51]
	v_mfma_f32_16x16x32_bf16 v[40:43], v[140:143], v[184:187], v[40:43]
	v_mfma_f32_16x16x32_bf16 v[28:31], v[132:135], v[192:195], v[28:31]
	v_mfma_f32_16x16x32_bf16 v[24:27], v[140:143], v[192:195], v[24:27]
	v_mfma_f32_16x16x32_bf16 v[16:19], v[132:135], v[200:203], v[16:19]
	v_mfma_f32_16x16x32_bf16 v[8:11], v[140:143], v[200:203], v[8:11]
	v_mfma_f32_16x16x32_bf16 v[52:55], v[154:157], v[170:173], v[52:55]
	v_mfma_f32_16x16x32_bf16 v[44:47], v[162:165], v[170:173], v[44:47]
	v_mfma_f32_16x16x32_bf16 v[36:39], v[154:157], v[180:183], v[36:39]
	v_mfma_f32_16x16x32_bf16 v[32:35], v[162:165], v[180:183], v[32:35]
	v_mfma_f32_16x16x32_bf16 v[20:23], v[154:157], v[188:191], v[20:23]
	v_mfma_f32_16x16x32_bf16 v[12:15], v[162:165], v[188:191], v[12:15]
	v_mfma_f32_16x16x32_bf16 v[4:7], v[154:157], v[196:199], v[4:7]
	v_mfma_f32_16x16x32_bf16 v[0:3], v[162:165], v[196:199], v[0:3]
	v_mfma_f32_16x16x32_bf16 v[52:55], v[158:161], v[176:179], v[52:55]
	v_mfma_f32_16x16x32_bf16 v[44:47], v[166:169], v[176:179], v[44:47]
	v_mfma_f32_16x16x32_bf16 v[36:39], v[158:161], v[184:187], v[36:39]
	v_mfma_f32_16x16x32_bf16 v[32:35], v[166:169], v[184:187], v[32:35]
	v_mfma_f32_16x16x32_bf16 v[20:23], v[158:161], v[192:195], v[20:23]
	v_mfma_f32_16x16x32_bf16 v[12:15], v[166:169], v[192:195], v[12:15]
	v_mfma_f32_16x16x32_bf16 v[4:7], v[158:161], v[200:203], v[4:7]
	v_mfma_f32_16x16x32_bf16 v[0:3], v[166:169], v[200:203], v[0:3]
	s_setprio 0
	s_barrier
.Lzmid_3:
	s_add_i32 s61, 0, 0x18000
	s_add_i32 s62, 0, 0x1c000
	v_add_u32_e32 v140, s61, v174
	v_add_u32_e32 v166, s62, v174
	ds_read_b128 v[128:131], v140
	ds_read_b128 v[132:135], v140 offset:1024
	ds_read_b128 v[136:139], v140 offset:2048
	ds_read_b128 v[140:143], v140 offset:3072
	ds_read_b128 v[154:157], v166
	ds_read_b128 v[158:161], v166 offset:1024
	ds_read_b128 v[162:165], v166 offset:2048
	ds_read_b128 v[166:169], v166 offset:3072
	s_add_u32 s36, s36, 0x40000
	s_addc_u32 s37, s37, 0
	s_mov_b32 m0, s29
	s_nop 0
	global_load_lds_dwordx4 v[208:209], off
	s_mov_b32 m0, s46
	s_nop 0
	global_load_lds_dwordx4 v[210:211], off
	s_mov_b32 m0, s47
	v_lshl_add_u64 v[212:213], s[36:37], 0, v[144:145]
	ds_read_b128 v[170:173], v175 offset:32768
	ds_read_b128 v[176:179], v175 offset:33792
	ds_read_b128 v[180:183], v175 offset:34816
	ds_read_b128 v[184:187], v175 offset:35840
	ds_read_b128 v[188:191], v175 offset:36864
	ds_read_b128 v[192:195], v175 offset:37888
	ds_read_b128 v[196:199], v175 offset:38912
	ds_read_b128 v[200:203], v175 offset:39936
	global_load_lds_dwordx4 v[212:213], off
	v_lshl_add_u64 v[212:213], s[36:37], 0, v[146:147]
	s_mov_b32 m0, s48
	s_nop 0
	global_load_lds_dwordx4 v[212:213], off
	s_waitcnt vmcnt(8)
	s_waitcnt lgkmcnt(0)
	s_barrier
	s_setprio 1
	s_waitcnt lgkmcnt(0)
	v_mfma_f32_16x16x32_bf16 v[124:127], v[128:131], v[170:173], v[124:127]
	v_mfma_f32_16x16x32_bf16 v[120:123], v[136:139], v[170:173], v[120:123]
	v_mfma_f32_16x16x32_bf16 v[108:111], v[128:131], v[180:183], v[108:111]
	v_mfma_f32_16x16x32_bf16 v[104:107], v[136:139], v[180:183], v[104:107]
	v_mfma_f32_16x16x32_bf16 v[92:95], v[128:131], v[188:191], v[92:95]
	v_mfma_f32_16x16x32_bf16 v[88:91], v[136:139], v[188:191], v[88:91]
	v_mfma_f32_16x16x32_bf16 v[80:83], v[128:131], v[196:199], v[80:83]
	v_mfma_f32_16x16x32_bf16 v[72:75], v[136:139], v[196:199], v[72:75]
	v_mfma_f32_16x16x32_bf16 v[124:127], v[132:135], v[176:179], v[124:127]
	v_mfma_f32_16x16x32_bf16 v[120:123], v[140:143], v[176:179], v[120:123]
	v_mfma_f32_16x16x32_bf16 v[108:111], v[132:135], v[184:187], v[108:111]
	v_mfma_f32_16x16x32_bf16 v[104:107], v[140:143], v[184:187], v[104:107]
	v_mfma_f32_16x16x32_bf16 v[92:95], v[132:135], v[192:195], v[92:95]
	v_mfma_f32_16x16x32_bf16 v[88:91], v[140:143], v[192:195], v[88:91]
	v_mfma_f32_16x16x32_bf16 v[80:83], v[132:135], v[200:203], v[80:83]
	v_mfma_f32_16x16x32_bf16 v[72:75], v[140:143], v[200:203], v[72:75]
	v_mfma_f32_16x16x32_bf16 v[116:119], v[154:157], v[170:173], v[116:119]
	v_mfma_f32_16x16x32_bf16 v[112:115], v[162:165], v[170:173], v[112:115]
	v_mfma_f32_16x16x32_bf16 v[100:103], v[154:157], v[180:183], v[100:103]
	v_mfma_f32_16x16x32_bf16 v[96:99], v[162:165], v[180:183], v[96:99]
	v_mfma_f32_16x16x32_bf16 v[84:87], v[154:157], v[188:191], v[84:87]
	v_mfma_f32_16x16x32_bf16 v[76:79], v[162:165], v[188:191], v[76:79]
	v_mfma_f32_16x16x32_bf16 v[68:71], v[154:157], v[196:199], v[68:71]
	v_mfma_f32_16x16x32_bf16 v[64:67], v[162:165], v[196:199], v[64:67]
	v_mfma_f32_16x16x32_bf16 v[116:119], v[158:161], v[176:179], v[116:119]
	v_mfma_f32_16x16x32_bf16 v[112:115], v[166:169], v[176:179], v[112:115]
	v_mfma_f32_16x16x32_bf16 v[100:103], v[158:161], v[184:187], v[100:103]
	v_mfma_f32_16x16x32_bf16 v[96:99], v[166:169], v[184:187], v[96:99]
	v_mfma_f32_16x16x32_bf16 v[84:87], v[158:161], v[192:195], v[84:87]
	v_mfma_f32_16x16x32_bf16 v[76:79], v[166:169], v[192:195], v[76:79]
	v_mfma_f32_16x16x32_bf16 v[68:71], v[158:161], v[200:203], v[68:71]
	v_mfma_f32_16x16x32_bf16 v[64:67], v[166:169], v[200:203], v[64:67]
	s_setprio 0
	s_barrier
	s_add_i32 s36, s61, s41
	v_lshl_add_u64 v[204:205], v[204:205], 0, s[94:95]
	s_mov_b32 m0, s36
	ds_read_b128 v[170:173], v175 offset:49152
	ds_read_b128 v[176:179], v175 offset:50176
	ds_read_b128 v[180:183], v175 offset:51200
	ds_read_b128 v[184:187], v175 offset:52224
	ds_read_b128 v[188:191], v175 offset:53248
	ds_read_b128 v[192:195], v175 offset:54272
	ds_read_b128 v[196:199], v175 offset:55296
	ds_read_b128 v[200:203], v175 offset:56320
	global_load_lds_dwordx4 v[204:205], off
	s_add_i32 m0, s36, 0x2000
	s_add_u32 s34, s34, 0x40080
	v_lshl_add_u64 v[204:205], v[206:207], 0, s[94:95]
	s_addc_u32 s35, s35, 0
	s_add_i32 s36, s62, s41
	global_load_lds_dwordx4 v[204:205], off
	v_lshl_add_u64 v[204:205], s[34:35], 0, v[232:233]
	s_mov_b32 m0, s36
	s_nop 0
	global_load_lds_dwordx4 v[204:205], off
	v_lshl_add_u64 v[204:205], s[34:35], 0, v[148:149]
	s_add_i32 m0, s36, 0x2000
	s_nop 0
	global_load_lds_dwordx4 v[204:205], off
	v_lshl_add_u64 v[204:205], v[208:209], 0, s[94:95]
	s_mov_b32 m0, s51
	s_nop 0
	global_load_lds_dwordx4 v[204:205], off
	v_lshl_add_u64 v[204:205], v[210:211], 0, s[94:95]
	s_mov_b32 m0, s52
	s_nop 0
	global_load_lds_dwordx4 v[204:205], off
	s_waitcnt vmcnt(8)
	s_waitcnt lgkmcnt(0)
	s_barrier
	s_setprio 1
	s_waitcnt lgkmcnt(0)
	v_mfma_f32_16x16x32_bf16 v[60:63], v[128:131], v[170:173], v[60:63]
	v_mfma_f32_16x16x32_bf16 v[56:59], v[136:139], v[170:173], v[56:59]
	v_mfma_f32_16x16x32_bf16 v[48:51], v[128:131], v[180:183], v[48:51]
	v_mfma_f32_16x16x32_bf16 v[40:43], v[136:139], v[180:183], v[40:43]
	v_mfma_f32_16x16x32_bf16 v[28:31], v[128:131], v[188:191], v[28:31]
	v_mfma_f32_16x16x32_bf16 v[24:27], v[136:139], v[188:191], v[24:27]
	v_mfma_f32_16x16x32_bf16 v[16:19], v[128:131], v[196:199], v[16:19]
	v_mfma_f32_16x16x32_bf16 v[8:11], v[136:139], v[196:199], v[8:11]
	v_mfma_f32_16x16x32_bf16 v[60:63], v[132:135], v[176:179], v[60:63]
	v_mfma_f32_16x16x32_bf16 v[56:59], v[140:143], v[176:179], v[56:59]
	v_mfma_f32_16x16x32_bf16 v[48:51], v[132:135], v[184:187], v[48:51]
	v_mfma_f32_16x16x32_bf16 v[40:43], v[140:143], v[184:187], v[40:43]
	v_mfma_f32_16x16x32_bf16 v[28:31], v[132:135], v[192:195], v[28:31]
	v_mfma_f32_16x16x32_bf16 v[24:27], v[140:143], v[192:195], v[24:27]
	v_mfma_f32_16x16x32_bf16 v[16:19], v[132:135], v[200:203], v[16:19]
	v_mfma_f32_16x16x32_bf16 v[8:11], v[140:143], v[200:203], v[8:11]
	v_mfma_f32_16x16x32_bf16 v[52:55], v[154:157], v[170:173], v[52:55]
	v_mfma_f32_16x16x32_bf16 v[44:47], v[162:165], v[170:173], v[44:47]
	v_mfma_f32_16x16x32_bf16 v[36:39], v[154:157], v[180:183], v[36:39]
	v_mfma_f32_16x16x32_bf16 v[32:35], v[162:165], v[180:183], v[32:35]
	v_mfma_f32_16x16x32_bf16 v[20:23], v[154:157], v[188:191], v[20:23]
	v_mfma_f32_16x16x32_bf16 v[12:15], v[162:165], v[188:191], v[12:15]
	v_mfma_f32_16x16x32_bf16 v[4:7], v[154:157], v[196:199], v[4:7]
	v_mfma_f32_16x16x32_bf16 v[0:3], v[162:165], v[196:199], v[0:3]
	v_mfma_f32_16x16x32_bf16 v[52:55], v[158:161], v[176:179], v[52:55]
	v_mfma_f32_16x16x32_bf16 v[44:47], v[166:169], v[176:179], v[44:47]
	v_mfma_f32_16x16x32_bf16 v[36:39], v[158:161], v[184:187], v[36:39]
	v_mfma_f32_16x16x32_bf16 v[32:35], v[166:169], v[184:187], v[32:35]
	v_mfma_f32_16x16x32_bf16 v[20:23], v[158:161], v[192:195], v[20:23]
	v_mfma_f32_16x16x32_bf16 v[12:15], v[166:169], v[192:195], v[12:15]
	v_mfma_f32_16x16x32_bf16 v[4:7], v[158:161], v[200:203], v[4:7]
	v_mfma_f32_16x16x32_bf16 v[0:3], v[166:169], v[200:203], v[0:3]
	s_setprio 0
	s_barrier
	s_add_i32 s60, s60, 2
	s_add_u32 s58, s58, 0x100
	s_addc_u32 s59, s59, 0
	s_add_u32 s30, s30, 0x100
	s_addc_u32 s31, s31, 0
	s_cmp_gt_u32 s60, 13
	s_cbranch_scc0 .LBB0_1164
	s_and_b64 vcc, exec, s[18:19]
	s_cbranch_vccz .LBB0_1167
	s_barrier

.LBB0_1306:
	s_ashr_i32 s17, s16, 31
	s_lshl_b64 s[18:19], s[16:17], 19
	s_add_u32 s18, s34, s18
	s_addc_u32 s19, s35, s19
	s_and_b64 s[20:21], s[4:5], exec
	s_cselect_b32 s7, s19, s27
	s_cselect_b32 s17, s18, s26
	s_ashr_i32 s15, s14, 31
	s_lshl_b64 s[20:21], s[14:15], 19
	s_add_u32 s20, s36, s20
	s_addc_u32 s21, s37, s21
	s_and_b64 s[28:29], s[4:5], exec
	s_cselect_b32 s15, s21, s25
	s_cselect_b32 s23, s20, s24
	s_add_u32 s50, s24, 0x100
	s_addc_u32 s51, s25, 0
	s_add_u32 s24, s26, 0x40080
	s_addc_u32 s25, s27, 0
	s_mov_b32 s52, -2
	s_add_u32 s26, s24, 0xfffc0080
	s_addc_u32 s27, s25, -1
	s_add_i32 s53, 0, 0x10000
	s_cmp_eq_u32 s52, 12
	s_cselect_b32 s29, s7, s27
	s_cselect_b32 s28, s17, s26
	v_add_u32_e32 v142, s53, v144
	s_cselect_b32 s27, s15, s51
	s_cselect_b32 s26, s23, s50
	s_add_i32 s56, 0, 0x14000
	ds_read_b128 v[138:141], v142
	ds_read_b128 v[146:149], v142 offset:1024
	ds_read_b128 v[150:153], v142 offset:2048
	ds_read_b128 v[154:157], v142 offset:3072
	v_add_u32_e32 v142, s56, v144
	ds_read_b128 v[158:161], v142
	ds_read_b128 v[162:165], v142 offset:1024
	ds_read_b128 v[166:169], v142 offset:2048
	ds_read_b128 v[170:173], v142 offset:3072
	v_lshl_add_u64 v[142:143], s[24:25], 0, v[136:137]
	s_add_i32 m0, s39, 0xc000
	ds_read_b128 v[174:177], v145
	ds_read_b128 v[178:181], v145 offset:1024
	ds_read_b128 v[182:185], v145 offset:2048
	ds_read_b128 v[186:189], v145 offset:3072
	ds_read_b128 v[190:193], v145 offset:4096
	ds_read_b128 v[194:197], v145 offset:5120
	ds_read_b128 v[198:201], v145 offset:6144
	ds_read_b128 v[202:205], v145 offset:7168
	global_load_lds_dwordx4 v[142:143], off
	v_lshl_add_u64 v[142:143], s[24:25], 0, v[134:135]
	s_add_i32 m0, s39, 0xe000
	s_nop 0
	global_load_lds_dwordx4 v[142:143], off
	s_waitcnt vmcnt(8)
	s_waitcnt lgkmcnt(0)
	s_barrier
	s_setprio 1
	s_waitcnt lgkmcnt(0)
	v_mfma_f32_16x16x32_bf16 v[124:127], v[138:141], v[174:177], 0
	v_mfma_f32_16x16x32_bf16 v[120:123], v[150:153], v[174:177], 0
	v_mfma_f32_16x16x32_bf16 v[108:111], v[138:141], v[182:185], 0
	v_mfma_f32_16x16x32_bf16 v[104:107], v[150:153], v[182:185], 0
	v_mfma_f32_16x16x32_bf16 v[92:95], v[138:141], v[190:193], 0
	v_mfma_f32_16x16x32_bf16 v[88:91], v[150:153], v[190:193], 0
	v_mfma_f32_16x16x32_bf16 v[76:79], v[138:141], v[198:201], 0
	v_mfma_f32_16x16x32_bf16 v[72:75], v[150:153], v[198:201], 0
	v_mfma_f32_16x16x32_bf16 v[124:127], v[146:149], v[178:181], v[124:127]
	v_mfma_f32_16x16x32_bf16 v[120:123], v[154:157], v[178:181], v[120:123]
	v_mfma_f32_16x16x32_bf16 v[108:111], v[146:149], v[186:189], v[108:111]
	v_mfma_f32_16x16x32_bf16 v[104:107], v[154:157], v[186:189], v[104:107]
	v_mfma_f32_16x16x32_bf16 v[92:95], v[146:149], v[194:197], v[92:95]
	v_mfma_f32_16x16x32_bf16 v[88:91], v[154:157], v[194:197], v[88:91]
	v_mfma_f32_16x16x32_bf16 v[76:79], v[146:149], v[202:205], v[76:79]
	v_mfma_f32_16x16x32_bf16 v[72:75], v[154:157], v[202:205], v[72:75]
	v_mfma_f32_16x16x32_bf16 v[116:119], v[158:161], v[174:177], 0
	v_mfma_f32_16x16x32_bf16 v[112:115], v[166:169], v[174:177], 0
	v_mfma_f32_16x16x32_bf16 v[100:103], v[158:161], v[182:185], 0
	v_mfma_f32_16x16x32_bf16 v[96:99], v[166:169], v[182:185], 0
	v_mfma_f32_16x16x32_bf16 v[84:87], v[158:161], v[190:193], 0
	v_mfma_f32_16x16x32_bf16 v[80:83], v[166:169], v[190:193], 0
	v_mfma_f32_16x16x32_bf16 v[68:71], v[158:161], v[198:201], 0
	v_mfma_f32_16x16x32_bf16 v[64:67], v[166:169], v[198:201], 0
	v_mfma_f32_16x16x32_bf16 v[116:119], v[162:165], v[178:181], v[116:119]
	v_mfma_f32_16x16x32_bf16 v[112:115], v[170:173], v[178:181], v[112:115]
	v_mfma_f32_16x16x32_bf16 v[100:103], v[162:165], v[186:189], v[100:103]
	v_mfma_f32_16x16x32_bf16 v[96:99], v[170:173], v[186:189], v[96:99]
	v_mfma_f32_16x16x32_bf16 v[84:87], v[162:165], v[194:197], v[84:87]
	v_mfma_f32_16x16x32_bf16 v[80:83], v[170:173], v[194:197], v[80:83]
	v_mfma_f32_16x16x32_bf16 v[68:71], v[162:165], v[202:205], v[68:71]
	v_mfma_f32_16x16x32_bf16 v[64:67], v[170:173], v[202:205], v[64:67]
	s_setprio 0
	s_barrier
	s_add_i32 s53, s53, s38
	v_lshl_add_u64 v[142:143], s[26:27], 0, v[232:233]
	s_mov_b32 m0, s53
	ds_read_b128 v[174:177], v145 offset:16384
	ds_read_b128 v[178:181], v145 offset:17408
	ds_read_b128 v[182:185], v145 offset:18432
	ds_read_b128 v[186:189], v145 offset:19456
	ds_read_b128 v[190:193], v145 offset:20480
	ds_read_b128 v[194:197], v145 offset:21504
	ds_read_b128 v[198:201], v145 offset:22528
	ds_read_b128 v[202:205], v145 offset:23552
	global_load_lds_dwordx4 v[142:143], off
	s_add_i32 m0, s53, 0x2000
	s_add_u32 s54, s26, 0x40000
	v_lshl_add_u64 v[206:207], s[26:27], 0, v[132:133]
	s_addc_u32 s55, s27, 0
	s_add_i32 s53, s56, s38
	global_load_lds_dwordx4 v[206:207], off
	v_lshl_add_u64 v[208:209], s[54:55], 0, v[232:233]
	s_mov_b32 m0, s53
	v_lshl_add_u64 v[210:211], s[28:29], 0, v[130:131]
	global_load_lds_dwordx4 v[208:209], off
	v_lshl_add_u64 v[208:209], s[54:55], 0, v[132:133]
	s_add_i32 m0, s53, 0x2000
	s_nop 0
	global_load_lds_dwordx4 v[208:209], off
	v_lshl_add_u64 v[208:209], s[28:29], 0, v[128:129]
	s_waitcnt vmcnt(6)
	s_waitcnt lgkmcnt(0)
	s_barrier
	s_setprio 1
	s_waitcnt lgkmcnt(0)
	v_mfma_f32_16x16x32_bf16 v[60:63], v[138:141], v[174:177], 0
	v_mfma_f32_16x16x32_bf16 v[56:59], v[150:153], v[174:177], 0
	v_mfma_f32_16x16x32_bf16 v[44:47], v[138:141], v[182:185], 0
	v_mfma_f32_16x16x32_bf16 v[40:43], v[150:153], v[182:185], 0
	v_mfma_f32_16x16x32_bf16 v[28:31], v[138:141], v[190:193], 0
	v_mfma_f32_16x16x32_bf16 v[24:27], v[150:153], v[190:193], 0
	v_mfma_f32_16x16x32_bf16 v[12:15], v[138:141], v[198:201], 0
	v_mfma_f32_16x16x32_bf16 v[8:11], v[150:153], v[198:201], 0
	v_mfma_f32_16x16x32_bf16 v[60:63], v[146:149], v[178:181], v[60:63]
	v_mfma_f32_16x16x32_bf16 v[56:59], v[154:157], v[178:181], v[56:59]
	v_mfma_f32_16x16x32_bf16 v[44:47], v[146:149], v[186:189], v[44:47]
	v_mfma_f32_16x16x32_bf16 v[40:43], v[154:157], v[186:189], v[40:43]
	v_mfma_f32_16x16x32_bf16 v[28:31], v[146:149], v[194:197], v[28:31]
	v_mfma_f32_16x16x32_bf16 v[24:27], v[154:157], v[194:197], v[24:27]
	v_mfma_f32_16x16x32_bf16 v[12:15], v[146:149], v[202:205], v[12:15]
	v_mfma_f32_16x16x32_bf16 v[8:11], v[154:157], v[202:205], v[8:11]
	v_mfma_f32_16x16x32_bf16 v[52:55], v[158:161], v[174:177], 0
	v_mfma_f32_16x16x32_bf16 v[48:51], v[166:169], v[174:177], 0
	v_mfma_f32_16x16x32_bf16 v[36:39], v[158:161], v[182:185], 0
	v_mfma_f32_16x16x32_bf16 v[32:35], v[166:169], v[182:185], 0
	v_mfma_f32_16x16x32_bf16 v[20:23], v[158:161], v[190:193], 0
	v_mfma_f32_16x16x32_bf16 v[16:19], v[166:169], v[190:193], 0
	v_mfma_f32_16x16x32_bf16 v[4:7], v[158:161], v[198:201], 0
	v_mfma_f32_16x16x32_bf16 v[0:3], v[166:169], v[198:201], 0
	v_mfma_f32_16x16x32_bf16 v[52:55], v[162:165], v[178:181], v[52:55]
	v_mfma_f32_16x16x32_bf16 v[48:51], v[170:173], v[178:181], v[48:51]
	v_mfma_f32_16x16x32_bf16 v[36:39], v[162:165], v[186:189], v[36:39]
	v_mfma_f32_16x16x32_bf16 v[32:35], v[170:173], v[186:189], v[32:35]
	v_mfma_f32_16x16x32_bf16 v[20:23], v[162:165], v[194:197], v[20:23]
	v_mfma_f32_16x16x32_bf16 v[16:19], v[170:173], v[194:197], v[16:19]
	v_mfma_f32_16x16x32_bf16 v[4:7], v[162:165], v[202:205], v[4:7]
	v_mfma_f32_16x16x32_bf16 v[0:3], v[170:173], v[202:205], v[0:3]
	s_setprio 0
	s_barrier
	s_branch .Lzmid_4
.LBB0_1307:
	s_add_u32 s26, s24, 0xfffc0080
	s_addc_u32 s27, s25, -1
	s_add_i32 s53, 0, 0x10000
	s_cmp_eq_u32 s52, 12
	s_cselect_b32 s29, s7, s27
	s_cselect_b32 s28, s17, s26
	v_add_u32_e32 v142, s53, v144
	s_cselect_b32 s27, s15, s51
	s_cselect_b32 s26, s23, s50
	s_add_i32 s56, 0, 0x14000
	ds_read_b128 v[138:141], v142
	ds_read_b128 v[146:149], v142 offset:1024
	ds_read_b128 v[150:153], v142 offset:2048
	ds_read_b128 v[154:157], v142 offset:3072
	v_add_u32_e32 v142, s56, v144
	ds_read_b128 v[158:161], v142
	ds_read_b128 v[162:165], v142 offset:1024
	ds_read_b128 v[166:169], v142 offset:2048
	ds_read_b128 v[170:173], v142 offset:3072
	v_lshl_add_u64 v[142:143], s[24:25], 0, v[136:137]
	s_add_i32 m0, s39, 0xc000
	ds_read_b128 v[174:177], v145
	ds_read_b128 v[178:181], v145 offset:1024
	ds_read_b128 v[182:185], v145 offset:2048
	ds_read_b128 v[186:189], v145 offset:3072
	ds_read_b128 v[190:193], v145 offset:4096
	ds_read_b128 v[194:197], v145 offset:5120
	ds_read_b128 v[198:201], v145 offset:6144
	ds_read_b128 v[202:205], v145 offset:7168
	global_load_lds_dwordx4 v[142:143], off
	v_lshl_add_u64 v[142:143], s[24:25], 0, v[134:135]
	s_add_i32 m0, s39, 0xe000
	s_nop 0
	global_load_lds_dwordx4 v[142:143], off
	s_waitcnt vmcnt(8)
	s_waitcnt lgkmcnt(0)
	s_barrier
	s_setprio 1
	s_waitcnt lgkmcnt(0)
	v_mfma_f32_16x16x32_bf16 v[124:127], v[138:141], v[174:177], v[124:127]
	v_mfma_f32_16x16x32_bf16 v[120:123], v[150:153], v[174:177], v[120:123]
	v_mfma_f32_16x16x32_bf16 v[108:111], v[138:141], v[182:185], v[108:111]
	v_mfma_f32_16x16x32_bf16 v[104:107], v[150:153], v[182:185], v[104:107]
	v_mfma_f32_16x16x32_bf16 v[92:95], v[138:141], v[190:193], v[92:95]
	v_mfma_f32_16x16x32_bf16 v[88:91], v[150:153], v[190:193], v[88:91]
	v_mfma_f32_16x16x32_bf16 v[76:79], v[138:141], v[198:201], v[76:79]
	v_mfma_f32_16x16x32_bf16 v[72:75], v[150:153], v[198:201], v[72:75]
	v_mfma_f32_16x16x32_bf16 v[124:127], v[146:149], v[178:181], v[124:127]
	v_mfma_f32_16x16x32_bf16 v[120:123], v[154:157], v[178:181], v[120:123]
	v_mfma_f32_16x16x32_bf16 v[108:111], v[146:149], v[186:189], v[108:111]
	v_mfma_f32_16x16x32_bf16 v[104:107], v[154:157], v[186:189], v[104:107]
	v_mfma_f32_16x16x32_bf16 v[92:95], v[146:149], v[194:197], v[92:95]
	v_mfma_f32_16x16x32_bf16 v[88:91], v[154:157], v[194:197], v[88:91]
	v_mfma_f32_16x16x32_bf16 v[76:79], v[146:149], v[202:205], v[76:79]
	v_mfma_f32_16x16x32_bf16 v[72:75], v[154:157], v[202:205], v[72:75]
	v_mfma_f32_16x16x32_bf16 v[116:119], v[158:161], v[174:177], v[116:119]
	v_mfma_f32_16x16x32_bf16 v[112:115], v[166:169], v[174:177], v[112:115]
	v_mfma_f32_16x16x32_bf16 v[100:103], v[158:161], v[182:185], v[100:103]
	v_mfma_f32_16x16x32_bf16 v[96:99], v[166:169], v[182:185], v[96:99]
	v_mfma_f32_16x16x32_bf16 v[84:87], v[158:161], v[190:193], v[84:87]
	v_mfma_f32_16x16x32_bf16 v[80:83], v[166:169], v[190:193], v[80:83]
	v_mfma_f32_16x16x32_bf16 v[68:71], v[158:161], v[198:201], v[68:71]
	v_mfma_f32_16x16x32_bf16 v[64:67], v[166:169], v[198:201], v[64:67]
	v_mfma_f32_16x16x32_bf16 v[116:119], v[162:165], v[178:181], v[116:119]
	v_mfma_f32_16x16x32_bf16 v[112:115], v[170:173], v[178:181], v[112:115]
	v_mfma_f32_16x16x32_bf16 v[100:103], v[162:165], v[186:189], v[100:103]
	v_mfma_f32_16x16x32_bf16 v[96:99], v[170:173], v[186:189], v[96:99]
	v_mfma_f32_16x16x32_bf16 v[84:87], v[162:165], v[194:197], v[84:87]
	v_mfma_f32_16x16x32_bf16 v[80:83], v[170:173], v[194:197], v[80:83]
	v_mfma_f32_16x16x32_bf16 v[68:71], v[162:165], v[202:205], v[68:71]
	v_mfma_f32_16x16x32_bf16 v[64:67], v[170:173], v[202:205], v[64:67]
	s_setprio 0
	s_barrier
	s_add_i32 s53, s53, s38
	v_lshl_add_u64 v[142:143], s[26:27], 0, v[232:233]
	s_mov_b32 m0, s53
	ds_read_b128 v[174:177], v145 offset:16384
	ds_read_b128 v[178:181], v145 offset:17408
	ds_read_b128 v[182:185], v145 offset:18432
	ds_read_b128 v[186:189], v145 offset:19456
	ds_read_b128 v[190:193], v145 offset:20480
	ds_read_b128 v[194:197], v145 offset:21504
	ds_read_b128 v[198:201], v145 offset:22528
	ds_read_b128 v[202:205], v145 offset:23552
	global_load_lds_dwordx4 v[142:143], off
	s_add_i32 m0, s53, 0x2000
	s_add_u32 s54, s26, 0x40000
	v_lshl_add_u64 v[206:207], s[26:27], 0, v[132:133]
	s_addc_u32 s55, s27, 0
	s_add_i32 s53, s56, s38
	global_load_lds_dwordx4 v[206:207], off
	v_lshl_add_u64 v[208:209], s[54:55], 0, v[232:233]
	s_mov_b32 m0, s53
	v_lshl_add_u64 v[210:211], s[28:29], 0, v[130:131]
	global_load_lds_dwordx4 v[208:209], off
	v_lshl_add_u64 v[208:209], s[54:55], 0, v[132:133]
	s_add_i32 m0, s53, 0x2000
	s_nop 0
	global_load_lds_dwordx4 v[208:209], off
	v_lshl_add_u64 v[208:209], s[28:29], 0, v[128:129]
	s_waitcnt vmcnt(6)
	s_waitcnt lgkmcnt(0)
	s_barrier
	s_setprio 1
	s_waitcnt lgkmcnt(0)
	v_mfma_f32_16x16x32_bf16 v[60:63], v[138:141], v[174:177], v[60:63]
	v_mfma_f32_16x16x32_bf16 v[56:59], v[150:153], v[174:177], v[56:59]
	v_mfma_f32_16x16x32_bf16 v[44:47], v[138:141], v[182:185], v[44:47]
	v_mfma_f32_16x16x32_bf16 v[40:43], v[150:153], v[182:185], v[40:43]
	v_mfma_f32_16x16x32_bf16 v[28:31], v[138:141], v[190:193], v[28:31]
	v_mfma_f32_16x16x32_bf16 v[24:27], v[150:153], v[190:193], v[24:27]
	v_mfma_f32_16x16x32_bf16 v[12:15], v[138:141], v[198:201], v[12:15]
	v_mfma_f32_16x16x32_bf16 v[8:11], v[150:153], v[198:201], v[8:11]
	v_mfma_f32_16x16x32_bf16 v[60:63], v[146:149], v[178:181], v[60:63]
	v_mfma_f32_16x16x32_bf16 v[56:59], v[154:157], v[178:181], v[56:59]
	v_mfma_f32_16x16x32_bf16 v[44:47], v[146:149], v[186:189], v[44:47]
	v_mfma_f32_16x16x32_bf16 v[40:43], v[154:157], v[186:189], v[40:43]
	v_mfma_f32_16x16x32_bf16 v[28:31], v[146:149], v[194:197], v[28:31]
	v_mfma_f32_16x16x32_bf16 v[24:27], v[154:157], v[194:197], v[24:27]
	v_mfma_f32_16x16x32_bf16 v[12:15], v[146:149], v[202:205], v[12:15]
	v_mfma_f32_16x16x32_bf16 v[8:11], v[154:157], v[202:205], v[8:11]
	v_mfma_f32_16x16x32_bf16 v[52:55], v[158:161], v[174:177], v[52:55]
	v_mfma_f32_16x16x32_bf16 v[48:51], v[166:169], v[174:177], v[48:51]
	v_mfma_f32_16x16x32_bf16 v[36:39], v[158:161], v[182:185], v[36:39]
	v_mfma_f32_16x16x32_bf16 v[32:35], v[166:169], v[182:185], v[32:35]
	v_mfma_f32_16x16x32_bf16 v[20:23], v[158:161], v[190:193], v[20:23]
	v_mfma_f32_16x16x32_bf16 v[16:19], v[166:169], v[190:193], v[16:19]
	v_mfma_f32_16x16x32_bf16 v[4:7], v[158:161], v[198:201], v[4:7]
	v_mfma_f32_16x16x32_bf16 v[0:3], v[166:169], v[198:201], v[0:3]
	v_mfma_f32_16x16x32_bf16 v[52:55], v[162:165], v[178:181], v[52:55]
	v_mfma_f32_16x16x32_bf16 v[48:51], v[170:173], v[178:181], v[48:51]
	v_mfma_f32_16x16x32_bf16 v[36:39], v[162:165], v[186:189], v[36:39]
	v_mfma_f32_16x16x32_bf16 v[32:35], v[170:173], v[186:189], v[32:35]
	v_mfma_f32_16x16x32_bf16 v[20:23], v[162:165], v[194:197], v[20:23]
	v_mfma_f32_16x16x32_bf16 v[16:19], v[170:173], v[194:197], v[16:19]
	v_mfma_f32_16x16x32_bf16 v[4:7], v[162:165], v[202:205], v[4:7]
	v_mfma_f32_16x16x32_bf16 v[0:3], v[170:173], v[202:205], v[0:3]
	s_setprio 0
	s_barrier
.Lzmid_4:
	s_add_i32 s53, 0, 0x18000
	s_add_i32 s54, 0, 0x1c000
	v_add_u32_e32 v154, s53, v144
	v_add_u32_e32 v170, s54, v144
	ds_read_b128 v[138:141], v154
	ds_read_b128 v[146:149], v154 offset:1024
	ds_read_b128 v[150:153], v154 offset:2048
	ds_read_b128 v[154:157], v154 offset:3072
	ds_read_b128 v[158:161], v170
	ds_read_b128 v[162:165], v170 offset:1024
	ds_read_b128 v[166:169], v170 offset:2048
	ds_read_b128 v[170:173], v170 offset:3072
	s_add_u32 s28, s28, 0x40000
	s_addc_u32 s29, s29, 0
	s_mov_b32 m0, s39
	s_nop 0
	global_load_lds_dwordx4 v[208:209], off
	s_mov_b32 m0, s40
	s_nop 0
	global_load_lds_dwordx4 v[210:211], off
	s_mov_b32 m0, s41
	v_lshl_add_u64 v[212:213], s[28:29], 0, v[128:129]
	ds_read_b128 v[174:177], v145 offset:32768
	ds_read_b128 v[178:181], v145 offset:33792
	ds_read_b128 v[182:185], v145 offset:34816
	ds_read_b128 v[186:189], v145 offset:35840
	ds_read_b128 v[190:193], v145 offset:36864
	ds_read_b128 v[194:197], v145 offset:37888
	ds_read_b128 v[198:201], v145 offset:38912
	ds_read_b128 v[202:205], v145 offset:39936
	global_load_lds_dwordx4 v[212:213], off
	v_lshl_add_u64 v[212:213], s[28:29], 0, v[130:131]
	s_mov_b32 m0, s42
	s_nop 0
	global_load_lds_dwordx4 v[212:213], off
	s_waitcnt vmcnt(8)
	s_waitcnt lgkmcnt(0)
	s_barrier
	s_setprio 1
	s_waitcnt lgkmcnt(0)
	v_mfma_f32_16x16x32_bf16 v[124:127], v[138:141], v[174:177], v[124:127]
	v_mfma_f32_16x16x32_bf16 v[120:123], v[150:153], v[174:177], v[120:123]
	v_mfma_f32_16x16x32_bf16 v[108:111], v[138:141], v[182:185], v[108:111]
	v_mfma_f32_16x16x32_bf16 v[104:107], v[150:153], v[182:185], v[104:107]
	v_mfma_f32_16x16x32_bf16 v[92:95], v[138:141], v[190:193], v[92:95]
	v_mfma_f32_16x16x32_bf16 v[88:91], v[150:153], v[190:193], v[88:91]
	v_mfma_f32_16x16x32_bf16 v[76:79], v[138:141], v[198:201], v[76:79]
	v_mfma_f32_16x16x32_bf16 v[72:75], v[150:153], v[198:201], v[72:75]
	v_mfma_f32_16x16x32_bf16 v[124:127], v[146:149], v[178:181], v[124:127]
	v_mfma_f32_16x16x32_bf16 v[120:123], v[154:157], v[178:181], v[120:123]
	v_mfma_f32_16x16x32_bf16 v[108:111], v[146:149], v[186:189], v[108:111]
	v_mfma_f32_16x16x32_bf16 v[104:107], v[154:157], v[186:189], v[104:107]
	v_mfma_f32_16x16x32_bf16 v[92:95], v[146:149], v[194:197], v[92:95]
	v_mfma_f32_16x16x32_bf16 v[88:91], v[154:157], v[194:197], v[88:91]
	v_mfma_f32_16x16x32_bf16 v[76:79], v[146:149], v[202:205], v[76:79]
	v_mfma_f32_16x16x32_bf16 v[72:75], v[154:157], v[202:205], v[72:75]
	v_mfma_f32_16x16x32_bf16 v[116:119], v[158:161], v[174:177], v[116:119]
	v_mfma_f32_16x16x32_bf16 v[112:115], v[166:169], v[174:177], v[112:115]
	v_mfma_f32_16x16x32_bf16 v[100:103], v[158:161], v[182:185], v[100:103]
	v_mfma_f32_16x16x32_bf16 v[96:99], v[166:169], v[182:185], v[96:99]
	v_mfma_f32_16x16x32_bf16 v[84:87], v[158:161], v[190:193], v[84:87]
	v_mfma_f32_16x16x32_bf16 v[80:83], v[166:169], v[190:193], v[80:83]
	v_mfma_f32_16x16x32_bf16 v[68:71], v[158:161], v[198:201], v[68:71]
	v_mfma_f32_16x16x32_bf16 v[64:67], v[166:169], v[198:201], v[64:67]
	v_mfma_f32_16x16x32_bf16 v[116:119], v[162:165], v[178:181], v[116:119]
	v_mfma_f32_16x16x32_bf16 v[112:115], v[170:173], v[178:181], v[112:115]
	v_mfma_f32_16x16x32_bf16 v[100:103], v[162:165], v[186:189], v[100:103]
	v_mfma_f32_16x16x32_bf16 v[96:99], v[170:173], v[186:189], v[96:99]
	v_mfma_f32_16x16x32_bf16 v[84:87], v[162:165], v[194:197], v[84:87]
	v_mfma_f32_16x16x32_bf16 v[80:83], v[170:173], v[194:197], v[80:83]
	v_mfma_f32_16x16x32_bf16 v[68:71], v[162:165], v[202:205], v[68:71]
	v_mfma_f32_16x16x32_bf16 v[64:67], v[170:173], v[202:205], v[64:67]
	s_setprio 0
	s_barrier
	s_add_i32 s28, s53, s38
	v_lshl_add_u64 v[142:143], v[142:143], 0, s[94:95]
	s_mov_b32 m0, s28
	ds_read_b128 v[174:177], v145 offset:49152
	ds_read_b128 v[178:181], v145 offset:50176
	ds_read_b128 v[182:185], v145 offset:51200
	ds_read_b128 v[186:189], v145 offset:52224
	ds_read_b128 v[190:193], v145 offset:53248
	ds_read_b128 v[194:197], v145 offset:54272
	ds_read_b128 v[198:201], v145 offset:55296
	ds_read_b128 v[202:205], v145 offset:56320
	global_load_lds_dwordx4 v[142:143], off
	s_add_i32 m0, s28, 0x2000
	s_add_u32 s26, s26, 0x40080
	v_lshl_add_u64 v[142:143], v[206:207], 0, s[94:95]
	s_addc_u32 s27, s27, 0
	s_add_i32 s28, s54, s38
	global_load_lds_dwordx4 v[142:143], off
	v_lshl_add_u64 v[142:143], s[26:27], 0, v[232:233]
	s_mov_b32 m0, s28
	s_nop 0
	global_load_lds_dwordx4 v[142:143], off
	v_lshl_add_u64 v[142:143], s[26:27], 0, v[132:133]
	s_add_i32 m0, s28, 0x2000
	s_nop 0
	global_load_lds_dwordx4 v[142:143], off
	v_lshl_add_u64 v[142:143], v[208:209], 0, s[94:95]
	s_mov_b32 m0, s45
	s_nop 0
	global_load_lds_dwordx4 v[142:143], off
	v_lshl_add_u64 v[142:143], v[210:211], 0, s[94:95]
	s_mov_b32 m0, s46
	s_nop 0
	global_load_lds_dwordx4 v[142:143], off
	s_waitcnt vmcnt(8)
	s_waitcnt lgkmcnt(0)
	s_barrier
	s_setprio 1
	s_waitcnt lgkmcnt(0)
	v_mfma_f32_16x16x32_bf16 v[60:63], v[138:141], v[174:177], v[60:63]
	v_mfma_f32_16x16x32_bf16 v[56:59], v[150:153], v[174:177], v[56:59]
	v_mfma_f32_16x16x32_bf16 v[44:47], v[138:141], v[182:185], v[44:47]
	v_mfma_f32_16x16x32_bf16 v[40:43], v[150:153], v[182:185], v[40:43]
	v_mfma_f32_16x16x32_bf16 v[28:31], v[138:141], v[190:193], v[28:31]
	v_mfma_f32_16x16x32_bf16 v[24:27], v[150:153], v[190:193], v[24:27]
	v_mfma_f32_16x16x32_bf16 v[12:15], v[138:141], v[198:201], v[12:15]
	v_mfma_f32_16x16x32_bf16 v[8:11], v[150:153], v[198:201], v[8:11]
	v_mfma_f32_16x16x32_bf16 v[60:63], v[146:149], v[178:181], v[60:63]
	v_mfma_f32_16x16x32_bf16 v[56:59], v[154:157], v[178:181], v[56:59]
	v_mfma_f32_16x16x32_bf16 v[44:47], v[146:149], v[186:189], v[44:47]
	v_mfma_f32_16x16x32_bf16 v[40:43], v[154:157], v[186:189], v[40:43]
	v_mfma_f32_16x16x32_bf16 v[28:31], v[146:149], v[194:197], v[28:31]
	v_mfma_f32_16x16x32_bf16 v[24:27], v[154:157], v[194:197], v[24:27]
	v_mfma_f32_16x16x32_bf16 v[12:15], v[146:149], v[202:205], v[12:15]
	v_mfma_f32_16x16x32_bf16 v[8:11], v[154:157], v[202:205], v[8:11]
	v_mfma_f32_16x16x32_bf16 v[52:55], v[158:161], v[174:177], v[52:55]
	v_mfma_f32_16x16x32_bf16 v[48:51], v[166:169], v[174:177], v[48:51]
	v_mfma_f32_16x16x32_bf16 v[36:39], v[158:161], v[182:185], v[36:39]
	v_mfma_f32_16x16x32_bf16 v[32:35], v[166:169], v[182:185], v[32:35]
	v_mfma_f32_16x16x32_bf16 v[20:23], v[158:161], v[190:193], v[20:23]
	v_mfma_f32_16x16x32_bf16 v[16:19], v[166:169], v[190:193], v[16:19]
	v_mfma_f32_16x16x32_bf16 v[4:7], v[158:161], v[198:201], v[4:7]
	v_mfma_f32_16x16x32_bf16 v[0:3], v[166:169], v[198:201], v[0:3]
	v_mfma_f32_16x16x32_bf16 v[52:55], v[162:165], v[178:181], v[52:55]
	v_mfma_f32_16x16x32_bf16 v[48:51], v[170:173], v[178:181], v[48:51]
	v_mfma_f32_16x16x32_bf16 v[36:39], v[162:165], v[186:189], v[36:39]
	v_mfma_f32_16x16x32_bf16 v[32:35], v[170:173], v[186:189], v[32:35]
	v_mfma_f32_16x16x32_bf16 v[20:23], v[162:165], v[194:197], v[20:23]
	v_mfma_f32_16x16x32_bf16 v[16:19], v[170:173], v[194:197], v[16:19]
	v_mfma_f32_16x16x32_bf16 v[4:7], v[162:165], v[202:205], v[4:7]
	v_mfma_f32_16x16x32_bf16 v[0:3], v[170:173], v[202:205], v[0:3]
	s_setprio 0
	s_barrier
	s_add_i32 s52, s52, 2
	s_add_u32 s50, s50, 0x100
	s_addc_u32 s51, s51, 0
	s_add_u32 s24, s24, 0x100
	s_addc_u32 s25, s25, 0
	s_cmp_gt_u32 s52, 13
	s_cbranch_scc0 .LBB0_1307
	s_and_b64 vcc, exec, s[12:13]
	s_cbranch_vccz .LBB0_1310
	s_barrier

.LBB0_1420:
	s_ashr_i32 s17, s16, 31
	s_lshl_b64 s[18:19], s[16:17], 17
	s_add_u32 s18, s35, s18
	s_addc_u32 s19, s36, s19
	s_and_b64 s[20:21], s[4:5], exec
	s_cselect_b32 s31, s19, s25
	s_cselect_b32 s30, s18, s24
	s_ashr_i32 s15, s14, 31
	s_lshl_b64 s[20:21], s[14:15], 17
	s_add_u32 s20, s37, s20
	s_addc_u32 s21, s38, s21
	s_and_b64 s[28:29], s[4:5], exec
	s_cselect_b32 s29, s21, s27
	s_cselect_b32 s28, s20, s26
	s_add_i32 s17, 0, 0x10000
	s_add_i32 s49, 0, 0x14000
	v_add_u32_e32 v210, s17, v164
	v_add_u32_e32 v211, s49, v164
	ds_read_b128 v[0:3], v210
	ds_read_b128 v[4:7], v210 offset:1024
	ds_read_b128 v[8:11], v210 offset:2048
	ds_read_b128 v[12:15], v210 offset:3072
	ds_read_b128 v[16:19], v211
	ds_read_b128 v[20:23], v211 offset:1024
	ds_read_b128 v[24:27], v211 offset:2048
	ds_read_b128 v[28:31], v211 offset:3072
	v_mov_b64_e32 v[246:247], 0xff
	v_mov_b32_e32 v250, 0x3727c5ac
	s_add_u32 s50, s24, 0x10080
	s_addc_u32 s51, s25, 0
	s_add_i32 s53, s40, 0xc000
	s_waitcnt vmcnt(0)
	v_lshl_add_u64 v[64:65], s[50:51], 0, v[148:149]
	s_mov_b32 m0, s53
	s_add_i32 s15, s40, 0xe000
	ds_read_b128 v[32:35], v165
	ds_read_b128 v[36:39], v165 offset:1024
	ds_read_b128 v[40:43], v165 offset:2048
	ds_read_b128 v[44:47], v165 offset:3072
	ds_read_b128 v[48:51], v165 offset:4096
	ds_read_b128 v[52:55], v165 offset:5120
	ds_read_b128 v[56:59], v165 offset:6144
	ds_read_b128 v[60:63], v165 offset:7168
	global_load_lds_dwordx4 v[64:65], off
	v_lshl_add_u64 v[64:65], s[50:51], 0, v[150:151]
	s_mov_b32 m0, s15
	s_nop 0
	global_load_lds_dwordx4 v[64:65], off
	s_waitcnt vmcnt(8)
	s_waitcnt lgkmcnt(0)
	s_barrier
	s_setprio 1
	s_waitcnt lgkmcnt(0)
	v_mfma_f32_16x16x32_bf16 v[64:67], v[0:3], v[32:35], 0
	v_mfma_f32_16x16x32_bf16 v[68:71], v[8:11], v[32:35], 0
	v_mfma_f32_16x16x32_bf16 v[72:75], v[0:3], v[40:43], 0
	v_mfma_f32_16x16x32_bf16 v[76:79], v[8:11], v[40:43], 0
	v_mfma_f32_16x16x32_bf16 v[80:83], v[0:3], v[48:51], 0
	v_mfma_f32_16x16x32_bf16 v[84:87], v[8:11], v[48:51], 0
	v_mfma_f32_16x16x32_bf16 v[88:91], v[0:3], v[56:59], 0
	v_mfma_f32_16x16x32_bf16 v[92:95], v[8:11], v[56:59], 0
	v_mfma_f32_16x16x32_bf16 v[64:67], v[4:7], v[36:39], v[64:67]
	v_mfma_f32_16x16x32_bf16 v[68:71], v[12:15], v[36:39], v[68:71]
	v_mfma_f32_16x16x32_bf16 v[72:75], v[4:7], v[44:47], v[72:75]
	v_mfma_f32_16x16x32_bf16 v[76:79], v[12:15], v[44:47], v[76:79]
	v_mfma_f32_16x16x32_bf16 v[80:83], v[4:7], v[52:55], v[80:83]
	v_mfma_f32_16x16x32_bf16 v[84:87], v[12:15], v[52:55], v[84:87]
	v_mfma_f32_16x16x32_bf16 v[88:91], v[4:7], v[60:63], v[88:91]
	v_mfma_f32_16x16x32_bf16 v[92:95], v[12:15], v[60:63], v[92:95]
	v_mfma_f32_16x16x32_bf16 v[96:99], v[16:19], v[32:35], 0
	v_mfma_f32_16x16x32_bf16 v[32:35], v[24:27], v[32:35], 0
	v_mfma_f32_16x16x32_bf16 v[96:99], v[20:23], v[36:39], v[96:99]
	v_mfma_f32_16x16x32_bf16 v[32:35], v[28:31], v[36:39], v[32:35]
	v_mfma_f32_16x16x32_bf16 v[36:39], v[16:19], v[40:43], 0
	v_mfma_f32_16x16x32_bf16 v[40:43], v[24:27], v[40:43], 0
	v_mfma_f32_16x16x32_bf16 v[36:39], v[20:23], v[44:47], v[36:39]
	v_mfma_f32_16x16x32_bf16 v[40:43], v[28:31], v[44:47], v[40:43]
	v_mfma_f32_16x16x32_bf16 v[44:47], v[16:19], v[48:51], 0
	v_mfma_f32_16x16x32_bf16 v[48:51], v[24:27], v[48:51], 0
	v_mfma_f32_16x16x32_bf16 v[44:47], v[20:23], v[52:55], v[44:47]
	v_mfma_f32_16x16x32_bf16 v[48:51], v[28:31], v[52:55], v[48:51]
	v_mfma_f32_16x16x32_bf16 v[52:55], v[16:19], v[56:59], 0
	v_mfma_f32_16x16x32_bf16 v[56:59], v[24:27], v[56:59], 0
	v_mfma_f32_16x16x32_bf16 v[52:55], v[20:23], v[60:63], v[52:55]
	v_mfma_f32_16x16x32_bf16 v[56:59], v[28:31], v[60:63], v[56:59]
	s_setprio 0
	s_barrier
	s_add_i32 s51, s17, s39
	v_lshl_add_u64 v[162:163], s[26:27], 0, v[232:233]
	s_mov_b64 s[56:57], 0x100
	s_add_i32 s17, s51, 0x2000
	v_lshl_add_u64 v[128:129], v[162:163], 0, s[56:57]
	s_mov_b32 m0, s51
	v_lshl_add_u64 v[202:203], s[26:27], 0, v[152:153]
	s_add_u32 s54, s26, 0x10100
	ds_read_b128 v[60:63], v165 offset:16384
	ds_read_b128 v[100:103], v165 offset:17408
	ds_read_b128 v[104:107], v165 offset:18432
	ds_read_b128 v[108:111], v165 offset:19456
	ds_read_b128 v[112:115], v165 offset:20480
	ds_read_b128 v[116:119], v165 offset:21504
	ds_read_b128 v[120:123], v165 offset:22528
	ds_read_b128 v[124:127], v165 offset:23552
	global_load_lds_dwordx4 v[128:129], off
	v_lshl_add_u64 v[128:129], v[202:203], 0, s[56:57]
	s_mov_b32 m0, s17
	s_addc_u32 s55, s27, 0
	s_add_i32 s49, s49, s39
	global_load_lds_dwordx4 v[128:129], off
	v_lshl_add_u64 v[128:129], s[54:55], 0, v[232:233]
	s_mov_b32 m0, s49
	s_add_i32 s50, s49, 0x2000
	global_load_lds_dwordx4 v[128:129], off
	v_lshl_add_u64 v[128:129], s[54:55], 0, v[152:153]
	s_mov_b32 m0, s50
	v_lshl_add_u64 v[204:205], s[24:25], 0, v[148:149]
	global_load_lds_dwordx4 v[128:129], off
	v_lshl_add_u64 v[128:129], v[204:205], 0, s[56:57]
	s_mov_b32 m0, s40
	v_lshl_add_u64 v[206:207], s[24:25], 0, v[150:151]
	global_load_lds_dwordx4 v[128:129], off
	v_lshl_add_u64 v[128:129], v[206:207], 0, s[56:57]
	s_mov_b32 m0, s41
	s_nop 0
	global_load_lds_dwordx4 v[128:129], off
	s_waitcnt vmcnt(8)
	s_waitcnt lgkmcnt(0)
	s_barrier
	s_setprio 1
	s_waitcnt lgkmcnt(0)
	v_mfma_f32_16x16x32_bf16 v[128:131], v[0:3], v[60:63], 0
	v_mfma_f32_16x16x32_bf16 v[136:139], v[0:3], v[104:107], 0
	v_mfma_f32_16x16x32_bf16 v[144:147], v[0:3], v[112:115], 0
	v_mfma_f32_16x16x32_bf16 v[0:3], v[0:3], v[120:123], 0
	v_mfma_f32_16x16x32_bf16 v[128:131], v[4:7], v[100:103], v[128:131]
	v_mfma_f32_16x16x32_bf16 v[132:135], v[8:11], v[60:63], 0
	v_mfma_f32_16x16x32_bf16 v[136:139], v[4:7], v[108:111], v[136:139]
	v_mfma_f32_16x16x32_bf16 v[140:143], v[8:11], v[104:107], 0
	v_mfma_f32_16x16x32_bf16 v[144:147], v[4:7], v[116:119], v[144:147]
	v_mfma_f32_16x16x32_bf16 v[0:3], v[4:7], v[124:127], v[0:3]
	v_mfma_f32_16x16x32_bf16 v[4:7], v[8:11], v[120:123], 0
	v_mfma_f32_16x16x32_bf16 v[132:135], v[12:15], v[100:103], v[132:135]
	v_mfma_f32_16x16x32_bf16 v[140:143], v[12:15], v[108:111], v[140:143]
	v_mfma_f32_16x16x32_bf16 v[154:157], v[8:11], v[112:115], 0
	v_mfma_f32_16x16x32_bf16 v[4:7], v[12:15], v[124:127], v[4:7]
	v_mfma_f32_16x16x32_bf16 v[154:157], v[12:15], v[116:119], v[154:157]
	v_mfma_f32_16x16x32_bf16 v[8:11], v[16:19], v[60:63], 0
	v_mfma_f32_16x16x32_bf16 v[12:15], v[24:27], v[60:63], 0
	v_mfma_f32_16x16x32_bf16 v[8:11], v[20:23], v[100:103], v[8:11]
	v_mfma_f32_16x16x32_bf16 v[12:15], v[28:31], v[100:103], v[12:15]
	v_mfma_f32_16x16x32_bf16 v[60:63], v[16:19], v[104:107], 0
	v_mfma_f32_16x16x32_bf16 v[100:103], v[24:27], v[104:107], 0
	v_mfma_f32_16x16x32_bf16 v[104:107], v[16:19], v[112:115], 0
	v_mfma_f32_16x16x32_bf16 v[16:19], v[16:19], v[120:123], 0
	v_mfma_f32_16x16x32_bf16 v[60:63], v[20:23], v[108:111], v[60:63]
	v_mfma_f32_16x16x32_bf16 v[104:107], v[20:23], v[116:119], v[104:107]
	v_mfma_f32_16x16x32_bf16 v[16:19], v[20:23], v[124:127], v[16:19]
	v_mfma_f32_16x16x32_bf16 v[20:23], v[24:27], v[120:123], 0
	v_mfma_f32_16x16x32_bf16 v[100:103], v[28:31], v[108:111], v[100:103]
	v_mfma_f32_16x16x32_bf16 v[108:111], v[24:27], v[112:115], 0
	v_mfma_f32_16x16x32_bf16 v[20:23], v[28:31], v[124:127], v[20:23]
	v_mfma_f32_16x16x32_bf16 v[108:111], v[28:31], v[116:119], v[108:111]
	s_setprio 0
	s_barrier
	s_add_i32 s52, 0, 0x18000
	s_add_i32 s58, 0, 0x1c000
	v_add_u32_e32 v222, s52, v164
	v_add_u32_e32 v223, s58, v164
	ds_read_b128 v[24:27], v222
	ds_read_b128 v[28:31], v222 offset:1024
	ds_read_b128 v[112:115], v222 offset:2048
	ds_read_b128 v[116:119], v222 offset:3072
	ds_read_b128 v[120:123], v223
	ds_read_b128 v[124:127], v223 offset:1024
	ds_read_b128 v[158:161], v223 offset:2048
	ds_read_b128 v[166:169], v223 offset:3072
	s_add_u32 s54, s24, 0x10100
	s_addc_u32 s55, s25, 0
	s_mov_b32 m0, s42
	v_lshl_add_u64 v[208:209], s[54:55], 0, v[148:149]
	ds_read_b128 v[170:173], v165 offset:32768
	ds_read_b128 v[174:177], v165 offset:33792
	ds_read_b128 v[178:181], v165 offset:34816
	ds_read_b128 v[182:185], v165 offset:35840
	ds_read_b128 v[186:189], v165 offset:36864
	ds_read_b128 v[190:193], v165 offset:37888
	ds_read_b128 v[194:197], v165 offset:38912
	ds_read_b128 v[198:201], v165 offset:39936
	global_load_lds_dwordx4 v[208:209], off
	v_lshl_add_u64 v[208:209], s[54:55], 0, v[150:151]
	s_mov_b32 m0, s43
	s_nop 0
	global_load_lds_dwordx4 v[208:209], off
	s_waitcnt vmcnt(8)
	s_waitcnt lgkmcnt(0)
	s_barrier
	s_setprio 1
	s_waitcnt lgkmcnt(0)
	v_mfma_f32_16x16x32_bf16 v[64:67], v[24:27], v[170:173], v[64:67]
	v_mfma_f32_16x16x32_bf16 v[68:71], v[112:115], v[170:173], v[68:71]
	v_mfma_f32_16x16x32_bf16 v[72:75], v[24:27], v[178:181], v[72:75]
	v_mfma_f32_16x16x32_bf16 v[76:79], v[112:115], v[178:181], v[76:79]
	v_mfma_f32_16x16x32_bf16 v[80:83], v[24:27], v[186:189], v[80:83]
	v_mfma_f32_16x16x32_bf16 v[84:87], v[112:115], v[186:189], v[84:87]
	v_mfma_f32_16x16x32_bf16 v[88:91], v[24:27], v[194:197], v[88:91]
	v_mfma_f32_16x16x32_bf16 v[92:95], v[112:115], v[194:197], v[92:95]
	v_mfma_f32_16x16x32_bf16 v[64:67], v[28:31], v[174:177], v[64:67]
	v_mfma_f32_16x16x32_bf16 v[68:71], v[116:119], v[174:177], v[68:71]
	v_mfma_f32_16x16x32_bf16 v[72:75], v[28:31], v[182:185], v[72:75]
	v_mfma_f32_16x16x32_bf16 v[76:79], v[116:119], v[182:185], v[76:79]
	v_mfma_f32_16x16x32_bf16 v[80:83], v[28:31], v[190:193], v[80:83]
	v_mfma_f32_16x16x32_bf16 v[84:87], v[116:119], v[190:193], v[84:87]
	v_mfma_f32_16x16x32_bf16 v[88:91], v[28:31], v[198:201], v[88:91]
	v_mfma_f32_16x16x32_bf16 v[92:95], v[116:119], v[198:201], v[92:95]
	v_mfma_f32_16x16x32_bf16 v[96:99], v[120:123], v[170:173], v[96:99]
	v_mfma_f32_16x16x32_bf16 v[32:35], v[158:161], v[170:173], v[32:35]
	v_mfma_f32_16x16x32_bf16 v[36:39], v[120:123], v[178:181], v[36:39]
	v_mfma_f32_16x16x32_bf16 v[40:43], v[158:161], v[178:181], v[40:43]
	v_mfma_f32_16x16x32_bf16 v[44:47], v[120:123], v[186:189], v[44:47]
	v_mfma_f32_16x16x32_bf16 v[48:51], v[158:161], v[186:189], v[48:51]
	v_mfma_f32_16x16x32_bf16 v[52:55], v[120:123], v[194:197], v[52:55]
	v_mfma_f32_16x16x32_bf16 v[56:59], v[158:161], v[194:197], v[56:59]
	v_mfma_f32_16x16x32_bf16 v[96:99], v[124:127], v[174:177], v[96:99]
	v_mfma_f32_16x16x32_bf16 v[32:35], v[166:169], v[174:177], v[32:35]
	v_mfma_f32_16x16x32_bf16 v[36:39], v[124:127], v[182:185], v[36:39]
	v_mfma_f32_16x16x32_bf16 v[40:43], v[166:169], v[182:185], v[40:43]
	v_mfma_f32_16x16x32_bf16 v[44:47], v[124:127], v[190:193], v[44:47]
	v_mfma_f32_16x16x32_bf16 v[48:51], v[166:169], v[190:193], v[48:51]
	v_mfma_f32_16x16x32_bf16 v[52:55], v[124:127], v[198:201], v[52:55]
	v_mfma_f32_16x16x32_bf16 v[56:59], v[166:169], v[198:201], v[56:59]
	s_setprio 0
	s_barrier
	s_add_i32 s54, s52, s39
	s_mov_b64 s[60:61], 0x180
	s_add_i32 s52, s54, 0x2000
	v_lshl_add_u64 v[162:163], v[162:163], 0, s[60:61]
	s_mov_b32 m0, s54
	s_add_u32 s56, s26, 0x10180
	ds_read_b128 v[170:173], v165 offset:49152
	ds_read_b128 v[174:177], v165 offset:50176
	ds_read_b128 v[178:181], v165 offset:51200
	ds_read_b128 v[182:185], v165 offset:52224
	ds_read_b128 v[186:189], v165 offset:53248
	ds_read_b128 v[190:193], v165 offset:54272
	ds_read_b128 v[194:197], v165 offset:55296
	ds_read_b128 v[198:201], v165 offset:56320
	global_load_lds_dwordx4 v[162:163], off
	v_lshl_add_u64 v[162:163], v[202:203], 0, s[60:61]
	s_mov_b32 m0, s52
	s_addc_u32 s57, s27, 0
	s_add_i32 s26, s58, s39
	global_load_lds_dwordx4 v[162:163], off
	v_lshl_add_u64 v[162:163], s[56:57], 0, v[232:233]
	s_mov_b32 m0, s26
	s_add_i32 s27, s26, 0x2000
	global_load_lds_dwordx4 v[162:163], off
	v_lshl_add_u64 v[162:163], s[56:57], 0, v[152:153]
	s_mov_b32 m0, s27
	s_nop 0
	global_load_lds_dwordx4 v[162:163], off
	v_lshl_add_u64 v[162:163], v[204:205], 0, s[60:61]
	s_mov_b32 m0, s46
	s_nop 0
	global_load_lds_dwordx4 v[162:163], off
	v_lshl_add_u64 v[162:163], v[206:207], 0, s[60:61]
	s_mov_b32 m0, s47
	s_nop 0
	global_load_lds_dwordx4 v[162:163], off
	s_waitcnt vmcnt(8)
	s_waitcnt lgkmcnt(0)
	s_barrier
	s_setprio 1
	s_waitcnt lgkmcnt(0)
	v_mfma_f32_16x16x32_bf16 v[128:131], v[24:27], v[170:173], v[128:131]
	v_mfma_f32_16x16x32_bf16 v[132:135], v[112:115], v[170:173], v[132:135]
	v_mfma_f32_16x16x32_bf16 v[136:139], v[24:27], v[178:181], v[136:139]
	v_mfma_f32_16x16x32_bf16 v[140:143], v[112:115], v[178:181], v[140:143]
	v_mfma_f32_16x16x32_bf16 v[144:147], v[24:27], v[186:189], v[144:147]
	v_mfma_f32_16x16x32_bf16 v[0:3], v[24:27], v[194:197], v[0:3]
	v_mfma_f32_16x16x32_bf16 v[4:7], v[112:115], v[194:197], v[4:7]
	v_mfma_f32_16x16x32_bf16 v[128:131], v[28:31], v[174:177], v[128:131]
	v_mfma_f32_16x16x32_bf16 v[132:135], v[116:119], v[174:177], v[132:135]
	v_mfma_f32_16x16x32_bf16 v[136:139], v[28:31], v[182:185], v[136:139]
	v_mfma_f32_16x16x32_bf16 v[140:143], v[116:119], v[182:185], v[140:143]
	v_mfma_f32_16x16x32_bf16 v[144:147], v[28:31], v[190:193], v[144:147]
	v_mfma_f32_16x16x32_bf16 v[154:157], v[112:115], v[186:189], v[154:157]
	v_mfma_f32_16x16x32_bf16 v[0:3], v[28:31], v[198:201], v[0:3]
	v_mfma_f32_16x16x32_bf16 v[4:7], v[116:119], v[198:201], v[4:7]
	v_mfma_f32_16x16x32_bf16 v[154:157], v[116:119], v[190:193], v[154:157]
	v_mfma_f32_16x16x32_bf16 v[8:11], v[120:123], v[170:173], v[8:11]
	v_mfma_f32_16x16x32_bf16 v[12:15], v[158:161], v[170:173], v[12:15]
	v_mfma_f32_16x16x32_bf16 v[24:27], v[120:123], v[178:181], v[60:63]
	v_mfma_f32_16x16x32_bf16 v[28:31], v[158:161], v[178:181], v[100:103]
	v_mfma_f32_16x16x32_bf16 v[60:63], v[120:123], v[186:189], v[104:107]
	v_mfma_f32_16x16x32_bf16 v[100:103], v[158:161], v[186:189], v[108:111]
	v_mfma_f32_16x16x32_bf16 v[16:19], v[120:123], v[194:197], v[16:19]
	v_mfma_f32_16x16x32_bf16 v[20:23], v[158:161], v[194:197], v[20:23]
	v_mfma_f32_16x16x32_bf16 v[8:11], v[124:127], v[174:177], v[8:11]
	v_mfma_f32_16x16x32_bf16 v[12:15], v[166:169], v[174:177], v[12:15]
	v_mfma_f32_16x16x32_bf16 v[24:27], v[124:127], v[182:185], v[24:27]
	v_mfma_f32_16x16x32_bf16 v[28:31], v[166:169], v[182:185], v[28:31]
	v_mfma_f32_16x16x32_bf16 v[60:63], v[124:127], v[190:193], v[60:63]
	v_mfma_f32_16x16x32_bf16 v[100:103], v[166:169], v[190:193], v[100:103]
	v_mfma_f32_16x16x32_bf16 v[16:19], v[124:127], v[198:201], v[16:19]
	v_mfma_f32_16x16x32_bf16 v[20:23], v[166:169], v[198:201], v[20:23]
	s_setprio 0
	s_barrier
	ds_read_b128 v[104:107], v210
	ds_read_b128 v[108:111], v210 offset:1024
	ds_read_b128 v[112:115], v210 offset:2048
	ds_read_b128 v[116:119], v210 offset:3072
	ds_read_b128 v[120:123], v211
	ds_read_b128 v[124:127], v211 offset:1024
	ds_read_b128 v[158:161], v211 offset:2048
	ds_read_b128 v[166:169], v211 offset:3072
	s_add_u32 s24, s24, 0x10180
	s_addc_u32 s25, s25, 0
	s_mov_b32 m0, s53
	v_lshl_add_u64 v[162:163], s[24:25], 0, v[148:149]
	ds_read_b128 v[170:173], v165
	ds_read_b128 v[174:177], v165 offset:1024
	ds_read_b128 v[178:181], v165 offset:2048
	ds_read_b128 v[182:185], v165 offset:3072
	ds_read_b128 v[186:189], v165 offset:4096
	ds_read_b128 v[190:193], v165 offset:5120
	ds_read_b128 v[194:197], v165 offset:6144
	ds_read_b128 v[198:201], v165 offset:7168
	global_load_lds_dwordx4 v[162:163], off
	v_lshl_add_u64 v[162:163], s[24:25], 0, v[150:151]
	s_mov_b32 m0, s15
	s_nop 0
	global_load_lds_dwordx4 v[162:163], off
	s_waitcnt vmcnt(8)
	s_waitcnt lgkmcnt(0)
	s_barrier
	s_setprio 1
	s_waitcnt lgkmcnt(0)
	v_mfma_f32_16x16x32_bf16 v[64:67], v[104:107], v[170:173], v[64:67]
	v_mfma_f32_16x16x32_bf16 v[68:71], v[112:115], v[170:173], v[68:71]
	v_mfma_f32_16x16x32_bf16 v[72:75], v[104:107], v[178:181], v[72:75]
	v_mfma_f32_16x16x32_bf16 v[76:79], v[112:115], v[178:181], v[76:79]
	v_mfma_f32_16x16x32_bf16 v[80:83], v[104:107], v[186:189], v[80:83]
	v_mfma_f32_16x16x32_bf16 v[84:87], v[112:115], v[186:189], v[84:87]
	v_mfma_f32_16x16x32_bf16 v[88:91], v[104:107], v[194:197], v[88:91]
	v_mfma_f32_16x16x32_bf16 v[64:67], v[108:111], v[174:177], v[64:67]
	v_mfma_f32_16x16x32_bf16 v[68:71], v[116:119], v[174:177], v[68:71]
	v_mfma_f32_16x16x32_bf16 v[72:75], v[108:111], v[182:185], v[72:75]
	v_mfma_f32_16x16x32_bf16 v[76:79], v[116:119], v[182:185], v[76:79]
	v_mfma_f32_16x16x32_bf16 v[80:83], v[108:111], v[190:193], v[80:83]
	v_mfma_f32_16x16x32_bf16 v[84:87], v[116:119], v[190:193], v[84:87]
	v_mfma_f32_16x16x32_bf16 v[202:205], v[108:111], v[198:201], v[88:91]
	v_mfma_f32_16x16x32_bf16 v[88:91], v[112:115], v[194:197], v[92:95]
	v_mfma_f32_16x16x32_bf16 v[206:209], v[116:119], v[198:201], v[88:91]
	v_mfma_f32_16x16x32_bf16 v[88:91], v[120:123], v[170:173], v[96:99]
	v_mfma_f32_16x16x32_bf16 v[32:35], v[158:161], v[170:173], v[32:35]
	v_mfma_f32_16x16x32_bf16 v[36:39], v[120:123], v[178:181], v[36:39]
	v_mfma_f32_16x16x32_bf16 v[40:43], v[158:161], v[178:181], v[40:43]
	v_mfma_f32_16x16x32_bf16 v[44:47], v[120:123], v[186:189], v[44:47]
	v_mfma_f32_16x16x32_bf16 v[48:51], v[158:161], v[186:189], v[48:51]
	v_mfma_f32_16x16x32_bf16 v[52:55], v[120:123], v[194:197], v[52:55]
	v_mfma_f32_16x16x32_bf16 v[56:59], v[158:161], v[194:197], v[56:59]
	v_mfma_f32_16x16x32_bf16 v[96:99], v[124:127], v[174:177], v[88:91]
	v_mfma_f32_16x16x32_bf16 v[32:35], v[166:169], v[174:177], v[32:35]
	v_mfma_f32_16x16x32_bf16 v[36:39], v[124:127], v[182:185], v[36:39]
	v_mfma_f32_16x16x32_bf16 v[40:43], v[166:169], v[182:185], v[40:43]
	v_mfma_f32_16x16x32_bf16 v[44:47], v[124:127], v[190:193], v[44:47]
	v_mfma_f32_16x16x32_bf16 v[48:51], v[166:169], v[190:193], v[48:51]
	v_mfma_f32_16x16x32_bf16 v[52:55], v[124:127], v[198:201], v[52:55]
	v_mfma_f32_16x16x32_bf16 v[56:59], v[166:169], v[198:201], v[56:59]
	s_setprio 0
	s_barrier
	s_mov_b32 m0, s51
	v_lshl_add_u64 v[162:163], s[28:29], 0, v[232:233]
	s_add_u32 s24, s28, 0x10000
	ds_read_b128 v[88:91], v165 offset:16384
	ds_read_b128 v[92:95], v165 offset:17408
	ds_read_b128 v[170:173], v165 offset:18432
	ds_read_b128 v[174:177], v165 offset:19456
	ds_read_b128 v[178:181], v165 offset:20480
	ds_read_b128 v[182:185], v165 offset:21504
	ds_read_b128 v[186:189], v165 offset:22528
	ds_read_b128 v[190:193], v165 offset:23552
	global_load_lds_dwordx4 v[162:163], off
	v_lshl_add_u64 v[230:231], s[28:29], 0, v[152:153]
	s_mov_b32 m0, s17
	s_addc_u32 s25, s29, 0
	global_load_lds_dwordx4 v[230:231], off
	v_lshl_add_u64 v[194:195], s[24:25], 0, v[232:233]
	s_mov_b32 m0, s49
	v_lshl_add_u64 v[242:243], s[30:31], 0, v[148:149]
	global_load_lds_dwordx4 v[194:195], off
	v_lshl_add_u64 v[194:195], s[24:25], 0, v[152:153]
	s_mov_b32 m0, s50
	v_lshl_add_u64 v[244:245], s[30:31], 0, v[150:151]
	global_load_lds_dwordx4 v[194:195], off
	s_mov_b32 m0, s40
	s_nop 0
	global_load_lds_dwordx4 v[242:243], off
	s_mov_b32 m0, s41
	s_nop 0
	global_load_lds_dwordx4 v[244:245], off
	s_waitcnt vmcnt(8)
	s_waitcnt lgkmcnt(0)
	s_barrier
	s_setprio 1
	s_waitcnt lgkmcnt(0)
	v_mfma_f32_16x16x32_bf16 v[128:131], v[104:107], v[88:91], v[128:131]
	v_mfma_f32_16x16x32_bf16 v[194:197], v[108:111], v[92:95], v[128:131]
	v_mfma_f32_16x16x32_bf16 v[128:131], v[112:115], v[88:91], v[132:135]
	v_mfma_f32_16x16x32_bf16 v[198:201], v[116:119], v[92:95], v[128:131]
	v_mfma_f32_16x16x32_bf16 v[128:131], v[104:107], v[170:173], v[136:139]
	v_mfma_f32_16x16x32_bf16 v[210:213], v[108:111], v[174:177], v[128:131]
	v_mfma_f32_16x16x32_bf16 v[128:131], v[112:115], v[170:173], v[140:143]
	v_mfma_f32_16x16x32_bf16 v[214:217], v[116:119], v[174:177], v[128:131]
	v_mfma_f32_16x16x32_bf16 v[128:131], v[104:107], v[178:181], v[144:147]
	v_mfma_f32_16x16x32_bf16 v[0:3], v[104:107], v[186:189], v[0:3]
	v_mfma_f32_16x16x32_bf16 v[4:7], v[112:115], v[186:189], v[4:7]
	v_mfma_f32_16x16x32_bf16 v[218:221], v[108:111], v[182:185], v[128:131]
	v_mfma_f32_16x16x32_bf16 v[128:131], v[112:115], v[178:181], v[154:157]
	v_mfma_f32_16x16x32_bf16 v[0:3], v[108:111], v[190:193], v[0:3]
	v_mfma_f32_16x16x32_bf16 v[4:7], v[116:119], v[190:193], v[4:7]
	v_mfma_f32_16x16x32_bf16 v[154:157], v[116:119], v[182:185], v[128:131]
	v_mfma_f32_16x16x32_bf16 v[8:11], v[120:123], v[88:91], v[8:11]
	v_mfma_f32_16x16x32_bf16 v[104:107], v[124:127], v[92:95], v[8:11]
	v_mfma_f32_16x16x32_bf16 v[8:11], v[158:161], v[88:91], v[12:15]
	v_mfma_f32_16x16x32_bf16 v[108:111], v[166:169], v[92:95], v[8:11]
	v_mfma_f32_16x16x32_bf16 v[8:11], v[120:123], v[170:173], v[24:27]
	v_mfma_f32_16x16x32_bf16 v[112:115], v[124:127], v[174:177], v[8:11]
	v_mfma_f32_16x16x32_bf16 v[8:11], v[158:161], v[170:173], v[28:31]
	v_mfma_f32_16x16x32_bf16 v[116:119], v[166:169], v[174:177], v[8:11]
	v_mfma_f32_16x16x32_bf16 v[8:11], v[120:123], v[178:181], v[60:63]
	v_mfma_f32_16x16x32_bf16 v[170:173], v[124:127], v[182:185], v[8:11]
	v_mfma_f32_16x16x32_bf16 v[8:11], v[158:161], v[178:181], v[100:103]
	v_mfma_f32_16x16x32_bf16 v[174:177], v[166:169], v[182:185], v[8:11]
	v_mfma_f32_16x16x32_bf16 v[8:11], v[120:123], v[186:189], v[16:19]
	v_mfma_f32_16x16x32_bf16 v[124:127], v[124:127], v[190:193], v[8:11]
	v_mfma_f32_16x16x32_bf16 v[8:11], v[158:161], v[186:189], v[20:23]
	v_mfma_f32_16x16x32_bf16 v[158:161], v[166:169], v[190:193], v[8:11]
	s_setprio 0
	s_barrier
	s_nop 4
	ds_read_b128 v[8:11], v222
	ds_read_b128 v[12:15], v222 offset:1024
	ds_read_b128 v[16:19], v222 offset:2048
	ds_read_b128 v[20:23], v222 offset:3072
	ds_read_b128 v[166:169], v223
	ds_read_b128 v[178:181], v223 offset:1024
	ds_read_b128 v[182:185], v223 offset:2048
	ds_read_b128 v[186:189], v223 offset:3072
	s_add_u32 s24, s30, 0x10000
	s_addc_u32 s25, s31, 0
	s_mov_b32 m0, s42
	v_lshl_add_u64 v[88:89], s[24:25], 0, v[148:149]
	ds_read_b128 v[24:27], v165 offset:32768
	ds_read_b128 v[28:31], v165 offset:33792
	ds_read_b128 v[60:63], v165 offset:34816
	ds_read_b128 v[190:193], v165 offset:35840
	ds_read_b128 v[222:225], v165 offset:36864
	ds_read_b128 v[226:229], v165 offset:37888
	ds_read_b128 v[234:237], v165 offset:38912
	ds_read_b128 v[238:241], v165 offset:39936
	global_load_lds_dwordx4 v[88:89], off
	v_lshl_add_u64 v[88:89], s[24:25], 0, v[150:151]
	s_mov_b32 m0, s43
	s_nop 0
	global_load_lds_dwordx4 v[88:89], off
	s_waitcnt vmcnt(8)
	s_waitcnt lgkmcnt(0)
	s_barrier
	s_setprio 1
	s_waitcnt lgkmcnt(0)
	v_mfma_f32_16x16x32_bf16 v[64:67], v[8:11], v[24:27], v[64:67]
	v_mfma_f32_16x16x32_bf16 v[144:147], v[12:15], v[28:31], v[64:67]
	v_mfma_f32_16x16x32_bf16 v[64:67], v[16:19], v[24:27], v[68:71]
	v_mfma_f32_16x16x32_bf16 v[140:143], v[20:23], v[28:31], v[64:67]
	v_mfma_f32_16x16x32_bf16 v[64:67], v[8:11], v[60:63], v[72:75]
	v_mfma_f32_16x16x32_bf16 v[128:131], v[12:15], v[190:193], v[64:67]
	v_mfma_f32_16x16x32_bf16 v[64:67], v[16:19], v[60:63], v[76:79]
	v_mfma_f32_16x16x32_bf16 v[120:123], v[20:23], v[190:193], v[64:67]
	v_mfma_f32_16x16x32_bf16 v[64:67], v[8:11], v[222:225], v[80:83]
	v_mfma_f32_16x16x32_bf16 v[92:95], v[12:15], v[226:229], v[64:67]
	v_mfma_f32_16x16x32_bf16 v[64:67], v[16:19], v[222:225], v[84:87]
	v_mfma_f32_16x16x32_bf16 v[88:91], v[20:23], v[226:229], v[64:67]
	v_mfma_f32_16x16x32_bf16 v[64:67], v[8:11], v[234:237], v[202:205]
	v_mfma_f32_16x16x32_bf16 v[76:79], v[12:15], v[238:241], v[64:67]
	v_mfma_f32_16x16x32_bf16 v[64:67], v[16:19], v[234:237], v[206:209]
	v_mfma_f32_16x16x32_bf16 v[72:75], v[20:23], v[238:241], v[64:67]
	v_mfma_f32_16x16x32_bf16 v[64:67], v[166:169], v[24:27], v[96:99]
	v_mfma_f32_16x16x32_bf16 v[24:27], v[182:185], v[24:27], v[32:35]
	v_mfma_f32_16x16x32_bf16 v[132:135], v[186:189], v[28:31], v[24:27]
	v_mfma_f32_16x16x32_bf16 v[24:27], v[166:169], v[60:63], v[36:39]
	v_mfma_f32_16x16x32_bf16 v[100:103], v[178:181], v[190:193], v[24:27]
	v_mfma_f32_16x16x32_bf16 v[24:27], v[182:185], v[60:63], v[40:43]
	v_mfma_f32_16x16x32_bf16 v[96:99], v[186:189], v[190:193], v[24:27]
	v_mfma_f32_16x16x32_bf16 v[24:27], v[166:169], v[222:225], v[44:47]
	v_mfma_f32_16x16x32_bf16 v[84:87], v[178:181], v[226:229], v[24:27]
	v_mfma_f32_16x16x32_bf16 v[24:27], v[182:185], v[222:225], v[48:51]
	v_mfma_f32_16x16x32_bf16 v[80:83], v[186:189], v[226:229], v[24:27]
	v_mfma_f32_16x16x32_bf16 v[24:27], v[166:169], v[234:237], v[52:55]
	v_mfma_f32_16x16x32_bf16 v[68:71], v[178:181], v[238:241], v[24:27]
	v_mfma_f32_16x16x32_bf16 v[24:27], v[182:185], v[234:237], v[56:59]
	v_mfma_f32_16x16x32_bf16 v[136:139], v[178:181], v[28:31], v[64:67]
	v_mfma_f32_16x16x32_bf16 v[64:67], v[186:189], v[238:241], v[24:27]
	s_setprio 0
	s_barrier
	s_mov_b32 m0, s54
	s_nop 2
	v_lshl_add_u64 v[24:25], v[162:163], 0, s[94:95]
	s_add_u32 s24, s28, 0x10080
	ds_read_b128 v[32:35], v165 offset:49152
	ds_read_b128 v[36:39], v165 offset:50176
	ds_read_b128 v[190:193], v165 offset:51200
	ds_read_b128 v[202:205], v165 offset:52224
	ds_read_b128 v[206:209], v165 offset:53248
	ds_read_b128 v[222:225], v165 offset:54272
	ds_read_b128 v[226:229], v165 offset:55296
	ds_read_b128 v[234:237], v165 offset:56320
	global_load_lds_dwordx4 v[24:25], off
	v_lshl_add_u64 v[24:25], v[230:231], 0, s[94:95]
	s_mov_b32 m0, s52
	s_addc_u32 s25, s29, 0
	global_load_lds_dwordx4 v[24:25], off
	v_lshl_add_u64 v[24:25], s[24:25], 0, v[232:233]
	s_mov_b32 m0, s26
	s_nop 0
	global_load_lds_dwordx4 v[24:25], off
	v_lshl_add_u64 v[24:25], s[24:25], 0, v[152:153]
	s_mov_b32 m0, s27
	s_nop 0
	global_load_lds_dwordx4 v[24:25], off
	v_lshl_add_u64 v[24:25], v[242:243], 0, s[94:95]
	s_mov_b32 m0, s46
	s_nop 0
	global_load_lds_dwordx4 v[24:25], off
	v_lshl_add_u64 v[24:25], v[244:245], 0, s[94:95]
	s_mov_b32 m0, s47
	s_nop 0
	global_load_lds_dwordx4 v[24:25], off
	s_waitcnt vmcnt(8)
	s_waitcnt lgkmcnt(0)
	s_barrier
	s_setprio 1
	s_waitcnt lgkmcnt(0)
	v_mfma_f32_16x16x32_bf16 v[24:27], v[8:11], v[32:35], v[194:197]
	v_mfma_f32_16x16x32_bf16 v[60:63], v[12:15], v[36:39], v[24:27]
	v_mfma_f32_16x16x32_bf16 v[24:27], v[16:19], v[32:35], v[198:201]
	v_mfma_f32_16x16x32_bf16 v[56:59], v[20:23], v[36:39], v[24:27]
	v_mfma_f32_16x16x32_bf16 v[24:27], v[8:11], v[190:193], v[210:213]
	v_mfma_f32_16x16x32_bf16 v[44:47], v[12:15], v[202:205], v[24:27]
	v_mfma_f32_16x16x32_bf16 v[24:27], v[16:19], v[190:193], v[214:217]
	v_mfma_f32_16x16x32_bf16 v[40:43], v[20:23], v[202:205], v[24:27]
	v_mfma_f32_16x16x32_bf16 v[24:27], v[8:11], v[206:209], v[218:221]
	v_mfma_f32_16x16x32_bf16 v[0:3], v[8:11], v[226:229], v[0:3]
	v_mfma_f32_16x16x32_bf16 v[28:31], v[12:15], v[222:225], v[24:27]
	v_mfma_f32_16x16x32_bf16 v[24:27], v[16:19], v[206:209], v[154:157]
	v_mfma_f32_16x16x32_bf16 v[12:15], v[12:15], v[234:237], v[0:3]
	v_mfma_f32_16x16x32_bf16 v[0:3], v[16:19], v[226:229], v[4:7]
	v_mfma_f32_16x16x32_bf16 v[24:27], v[20:23], v[222:225], v[24:27]
	v_mfma_f32_16x16x32_bf16 v[8:11], v[20:23], v[234:237], v[0:3]
	v_mfma_f32_16x16x32_bf16 v[0:3], v[166:169], v[32:35], v[104:107]
	v_mfma_f32_16x16x32_bf16 v[52:55], v[178:181], v[36:39], v[0:3]
	v_mfma_f32_16x16x32_bf16 v[0:3], v[182:185], v[32:35], v[108:111]
	v_mfma_f32_16x16x32_bf16 v[48:51], v[186:189], v[36:39], v[0:3]
	v_mfma_f32_16x16x32_bf16 v[0:3], v[166:169], v[190:193], v[112:115]
	v_mfma_f32_16x16x32_bf16 v[36:39], v[178:181], v[202:205], v[0:3]
	v_mfma_f32_16x16x32_bf16 v[0:3], v[182:185], v[190:193], v[116:119]
	v_mfma_f32_16x16x32_bf16 v[32:35], v[186:189], v[202:205], v[0:3]
	v_mfma_f32_16x16x32_bf16 v[0:3], v[166:169], v[206:209], v[170:173]
	v_mfma_f32_16x16x32_bf16 v[20:23], v[178:181], v[222:225], v[0:3]
	v_mfma_f32_16x16x32_bf16 v[0:3], v[182:185], v[206:209], v[174:177]
	v_mfma_f32_16x16x32_bf16 v[16:19], v[186:189], v[222:225], v[0:3]
	v_mfma_f32_16x16x32_bf16 v[0:3], v[166:169], v[226:229], v[124:127]
	v_mfma_f32_16x16x32_bf16 v[4:7], v[178:181], v[234:237], v[0:3]
	v_mfma_f32_16x16x32_bf16 v[0:3], v[182:185], v[226:229], v[158:161]
	v_mfma_f32_16x16x32_bf16 v[0:3], v[186:189], v[234:237], v[0:3]
	s_setprio 0
	s_barrier
	s_andn2_b64 vcc, exec, s[10:11]
	s_cbranch_vccnz .LBB0_1422
	s_barrier

.LBB0_1491:
	s_ashr_i32 s23, s22, 31
	s_lshl_b64 s[24:25], s[22:23], 21
	s_add_u32 s24, s70, s24
	s_addc_u32 s25, s71, s25
	s_and_b64 s[26:27], s[4:5], exec
	s_cselect_b32 s23, s25, s35
	s_cselect_b32 s56, s24, s34
	s_ashr_i32 s21, s20, 31
	s_lshl_b64 s[26:27], s[20:21], 21
	s_add_u32 s26, s72, s26
	s_addc_u32 s27, s76, s27
	s_and_b64 s[36:37], s[4:5], exec
	s_cselect_b32 s21, s27, s31
	s_cselect_b32 s57, s26, s30
	s_add_u32 s58, s30, 0x100
	s_addc_u32 s59, s31, 0
	s_add_u32 s30, s34, 0x100080
	s_addc_u32 s31, s35, 0
	s_mov_b32 s60, -2
	s_waitcnt vmcnt(0)
	s_add_u32 s34, s30, 0xfff00080
	s_addc_u32 s35, s31, -1
	s_add_i32 s61, 0, 0x10000
	s_cmp_eq_u32 s60, 60
	s_cselect_b32 s37, s23, s35
	s_cselect_b32 s36, s56, s34
	s_cselect_b32 s35, s21, s59
	s_cselect_b32 s34, s57, s58
	s_add_i32 s64, 0, 0x14000
	v_add_u32_e32 v100, s61, v220
	v_add_u32_e32 v156, s64, v220
	ds_read_b128 v[88:91], v100
	ds_read_b128 v[92:95], v100 offset:1024
	ds_read_b128 v[96:99], v100 offset:2048
	ds_read_b128 v[100:103], v100 offset:3072
	ds_read_b128 v[144:147], v156
	ds_read_b128 v[148:151], v156 offset:1024
	ds_read_b128 v[152:155], v156 offset:2048
	ds_read_b128 v[156:159], v156 offset:3072
	v_lshl_add_u64 v[202:203], s[30:31], 0, v[188:189]
	s_add_i32 m0, s78, 0xc000
	ds_read_b128 v[160:163], v221
	ds_read_b128 v[164:167], v221 offset:1024
	ds_read_b128 v[168:171], v221 offset:2048
	ds_read_b128 v[172:175], v221 offset:3072
	ds_read_b128 v[176:179], v221 offset:4096
	ds_read_b128 v[190:193], v221 offset:5120
	ds_read_b128 v[194:197], v221 offset:6144
	ds_read_b128 v[198:201], v221 offset:7168
	global_load_lds_dwordx4 v[202:203], off
	v_lshl_add_u64 v[202:203], s[30:31], 0, v[186:187]
	s_add_i32 m0, s78, 0xe000
	s_nop 0
	global_load_lds_dwordx4 v[202:203], off
	s_waitcnt vmcnt(8)
	s_waitcnt lgkmcnt(0)
	s_barrier
	s_setprio 1
	s_waitcnt lgkmcnt(0)
	v_mfma_f32_16x16x32_bf16 v[140:143], v[88:91], v[160:163], 0
	v_mfma_f32_16x16x32_bf16 v[136:139], v[96:99], v[160:163], 0
	v_mfma_f32_16x16x32_bf16 v[124:127], v[88:91], v[168:171], 0
	v_mfma_f32_16x16x32_bf16 v[120:123], v[96:99], v[168:171], 0
	v_mfma_f32_16x16x32_bf16 v[108:111], v[88:91], v[176:179], 0
	v_mfma_f32_16x16x32_bf16 v[104:107], v[96:99], v[176:179], 0
	v_mfma_f32_16x16x32_bf16 v[76:79], v[88:91], v[194:197], 0
	v_mfma_f32_16x16x32_bf16 v[72:75], v[96:99], v[194:197], 0
	v_mfma_f32_16x16x32_bf16 v[140:143], v[92:95], v[164:167], v[140:143]
	v_mfma_f32_16x16x32_bf16 v[136:139], v[100:103], v[164:167], v[136:139]
	v_mfma_f32_16x16x32_bf16 v[124:127], v[92:95], v[172:175], v[124:127]
	v_mfma_f32_16x16x32_bf16 v[120:123], v[100:103], v[172:175], v[120:123]
	v_mfma_f32_16x16x32_bf16 v[108:111], v[92:95], v[190:193], v[108:111]
	v_mfma_f32_16x16x32_bf16 v[104:107], v[100:103], v[190:193], v[104:107]
	v_mfma_f32_16x16x32_bf16 v[76:79], v[92:95], v[198:201], v[76:79]
	v_mfma_f32_16x16x32_bf16 v[72:75], v[100:103], v[198:201], v[72:75]
	v_mfma_f32_16x16x32_bf16 v[132:135], v[144:147], v[160:163], 0
	v_mfma_f32_16x16x32_bf16 v[128:131], v[152:155], v[160:163], 0
	v_mfma_f32_16x16x32_bf16 v[116:119], v[144:147], v[168:171], 0
	v_mfma_f32_16x16x32_bf16 v[112:115], v[152:155], v[168:171], 0
	v_mfma_f32_16x16x32_bf16 v[84:87], v[144:147], v[176:179], 0
	v_mfma_f32_16x16x32_bf16 v[80:83], v[152:155], v[176:179], 0
	v_mfma_f32_16x16x32_bf16 v[68:71], v[144:147], v[194:197], 0
	v_mfma_f32_16x16x32_bf16 v[64:67], v[152:155], v[194:197], 0
	v_mfma_f32_16x16x32_bf16 v[132:135], v[148:151], v[164:167], v[132:135]
	v_mfma_f32_16x16x32_bf16 v[128:131], v[156:159], v[164:167], v[128:131]
	v_mfma_f32_16x16x32_bf16 v[116:119], v[148:151], v[172:175], v[116:119]
	v_mfma_f32_16x16x32_bf16 v[112:115], v[156:159], v[172:175], v[112:115]
	v_mfma_f32_16x16x32_bf16 v[84:87], v[148:151], v[190:193], v[84:87]
	v_mfma_f32_16x16x32_bf16 v[80:83], v[156:159], v[190:193], v[80:83]
	v_mfma_f32_16x16x32_bf16 v[68:71], v[148:151], v[198:201], v[68:71]
	v_mfma_f32_16x16x32_bf16 v[64:67], v[156:159], v[198:201], v[64:67]
	s_setprio 0
	s_barrier
	s_add_i32 s61, s61, s77
	v_lshl_add_u64 v[202:203], s[34:35], 0, v[232:233]
	s_mov_b32 m0, s61
	ds_read_b128 v[160:163], v221 offset:16384
	ds_read_b128 v[164:167], v221 offset:17408
	ds_read_b128 v[168:171], v221 offset:18432
	ds_read_b128 v[172:175], v221 offset:19456
	ds_read_b128 v[176:179], v221 offset:20480
	ds_read_b128 v[190:193], v221 offset:21504
	ds_read_b128 v[194:197], v221 offset:22528
	ds_read_b128 v[198:201], v221 offset:23552
	global_load_lds_dwordx4 v[202:203], off
	s_add_i32 m0, s61, 0x2000
	s_add_u32 s62, s34, 0x100000
	v_lshl_add_u64 v[204:205], s[34:35], 0, v[184:185]
	s_addc_u32 s63, s35, 0
	s_add_i32 s61, s64, s77
	global_load_lds_dwordx4 v[204:205], off
	v_lshl_add_u64 v[206:207], s[62:63], 0, v[232:233]
	s_mov_b32 m0, s61
	v_lshl_add_u64 v[208:209], s[36:37], 0, v[182:183]
	global_load_lds_dwordx4 v[206:207], off
	v_lshl_add_u64 v[206:207], s[62:63], 0, v[184:185]
	s_add_i32 m0, s61, 0x2000
	s_nop 0
	global_load_lds_dwordx4 v[206:207], off
	v_lshl_add_u64 v[206:207], s[36:37], 0, v[180:181]
	s_waitcnt vmcnt(6)
	s_waitcnt lgkmcnt(0)
	s_barrier
	s_setprio 1
	s_waitcnt lgkmcnt(0)
	v_mfma_f32_16x16x32_bf16 v[60:63], v[88:91], v[160:163], 0
	v_mfma_f32_16x16x32_bf16 v[56:59], v[96:99], v[160:163], 0
	v_mfma_f32_16x16x32_bf16 v[44:47], v[88:91], v[168:171], 0
	v_mfma_f32_16x16x32_bf16 v[40:43], v[96:99], v[168:171], 0
	v_mfma_f32_16x16x32_bf16 v[28:31], v[88:91], v[176:179], 0
	v_mfma_f32_16x16x32_bf16 v[24:27], v[96:99], v[176:179], 0
	v_mfma_f32_16x16x32_bf16 v[12:15], v[88:91], v[194:197], 0
	v_mfma_f32_16x16x32_bf16 v[8:11], v[96:99], v[194:197], 0
	v_mfma_f32_16x16x32_bf16 v[60:63], v[92:95], v[164:167], v[60:63]
	v_mfma_f32_16x16x32_bf16 v[56:59], v[100:103], v[164:167], v[56:59]
	v_mfma_f32_16x16x32_bf16 v[44:47], v[92:95], v[172:175], v[44:47]
	v_mfma_f32_16x16x32_bf16 v[40:43], v[100:103], v[172:175], v[40:43]
	v_mfma_f32_16x16x32_bf16 v[28:31], v[92:95], v[190:193], v[28:31]
	v_mfma_f32_16x16x32_bf16 v[24:27], v[100:103], v[190:193], v[24:27]
	v_mfma_f32_16x16x32_bf16 v[12:15], v[92:95], v[198:201], v[12:15]
	v_mfma_f32_16x16x32_bf16 v[8:11], v[100:103], v[198:201], v[8:11]
	v_mfma_f32_16x16x32_bf16 v[52:55], v[144:147], v[160:163], 0
	v_mfma_f32_16x16x32_bf16 v[48:51], v[152:155], v[160:163], 0
	v_mfma_f32_16x16x32_bf16 v[36:39], v[144:147], v[168:171], 0
	v_mfma_f32_16x16x32_bf16 v[32:35], v[152:155], v[168:171], 0
	v_mfma_f32_16x16x32_bf16 v[20:23], v[144:147], v[176:179], 0
	v_mfma_f32_16x16x32_bf16 v[16:19], v[152:155], v[176:179], 0
	v_mfma_f32_16x16x32_bf16 v[4:7], v[144:147], v[194:197], 0
	v_mfma_f32_16x16x32_bf16 v[0:3], v[152:155], v[194:197], 0
	v_mfma_f32_16x16x32_bf16 v[52:55], v[148:151], v[164:167], v[52:55]
	v_mfma_f32_16x16x32_bf16 v[48:51], v[156:159], v[164:167], v[48:51]
	v_mfma_f32_16x16x32_bf16 v[36:39], v[148:151], v[172:175], v[36:39]
	v_mfma_f32_16x16x32_bf16 v[32:35], v[156:159], v[172:175], v[32:35]
	v_mfma_f32_16x16x32_bf16 v[20:23], v[148:151], v[190:193], v[20:23]
	v_mfma_f32_16x16x32_bf16 v[16:19], v[156:159], v[190:193], v[16:19]
	v_mfma_f32_16x16x32_bf16 v[4:7], v[148:151], v[198:201], v[4:7]
	v_mfma_f32_16x16x32_bf16 v[0:3], v[156:159], v[198:201], v[0:3]
	s_setprio 0
	s_barrier
	s_branch .Lzmid_6
.LBB0_1492:
	s_add_u32 s34, s30, 0xfff00080
	s_addc_u32 s35, s31, -1
	s_add_i32 s61, 0, 0x10000
	s_cmp_eq_u32 s60, 60
	s_cselect_b32 s37, s23, s35
	s_cselect_b32 s36, s56, s34
	s_cselect_b32 s35, s21, s59
	s_cselect_b32 s34, s57, s58
	s_add_i32 s64, 0, 0x14000
	v_add_u32_e32 v100, s61, v220
	v_add_u32_e32 v156, s64, v220
	ds_read_b128 v[88:91], v100
	ds_read_b128 v[92:95], v100 offset:1024
	ds_read_b128 v[96:99], v100 offset:2048
	ds_read_b128 v[100:103], v100 offset:3072
	ds_read_b128 v[144:147], v156
	ds_read_b128 v[148:151], v156 offset:1024
	ds_read_b128 v[152:155], v156 offset:2048
	ds_read_b128 v[156:159], v156 offset:3072
	v_lshl_add_u64 v[202:203], s[30:31], 0, v[188:189]
	s_add_i32 m0, s78, 0xc000
	ds_read_b128 v[160:163], v221
	ds_read_b128 v[164:167], v221 offset:1024
	ds_read_b128 v[168:171], v221 offset:2048
	ds_read_b128 v[172:175], v221 offset:3072
	ds_read_b128 v[176:179], v221 offset:4096
	ds_read_b128 v[190:193], v221 offset:5120
	ds_read_b128 v[194:197], v221 offset:6144
	ds_read_b128 v[198:201], v221 offset:7168
	global_load_lds_dwordx4 v[202:203], off
	v_lshl_add_u64 v[202:203], s[30:31], 0, v[186:187]
	s_add_i32 m0, s78, 0xe000
	s_nop 0
	global_load_lds_dwordx4 v[202:203], off
	s_waitcnt vmcnt(8)
	s_waitcnt lgkmcnt(0)
	s_barrier
	s_setprio 1
	s_waitcnt lgkmcnt(0)
	v_mfma_f32_16x16x32_bf16 v[140:143], v[88:91], v[160:163], v[140:143]
	v_mfma_f32_16x16x32_bf16 v[136:139], v[96:99], v[160:163], v[136:139]
	v_mfma_f32_16x16x32_bf16 v[124:127], v[88:91], v[168:171], v[124:127]
	v_mfma_f32_16x16x32_bf16 v[120:123], v[96:99], v[168:171], v[120:123]
	v_mfma_f32_16x16x32_bf16 v[108:111], v[88:91], v[176:179], v[108:111]
	v_mfma_f32_16x16x32_bf16 v[104:107], v[96:99], v[176:179], v[104:107]
	v_mfma_f32_16x16x32_bf16 v[76:79], v[88:91], v[194:197], v[76:79]
	v_mfma_f32_16x16x32_bf16 v[72:75], v[96:99], v[194:197], v[72:75]
	v_mfma_f32_16x16x32_bf16 v[140:143], v[92:95], v[164:167], v[140:143]
	v_mfma_f32_16x16x32_bf16 v[136:139], v[100:103], v[164:167], v[136:139]
	v_mfma_f32_16x16x32_bf16 v[124:127], v[92:95], v[172:175], v[124:127]
	v_mfma_f32_16x16x32_bf16 v[120:123], v[100:103], v[172:175], v[120:123]
	v_mfma_f32_16x16x32_bf16 v[108:111], v[92:95], v[190:193], v[108:111]
	v_mfma_f32_16x16x32_bf16 v[104:107], v[100:103], v[190:193], v[104:107]
	v_mfma_f32_16x16x32_bf16 v[76:79], v[92:95], v[198:201], v[76:79]
	v_mfma_f32_16x16x32_bf16 v[72:75], v[100:103], v[198:201], v[72:75]
	v_mfma_f32_16x16x32_bf16 v[132:135], v[144:147], v[160:163], v[132:135]
	v_mfma_f32_16x16x32_bf16 v[128:131], v[152:155], v[160:163], v[128:131]
	v_mfma_f32_16x16x32_bf16 v[116:119], v[144:147], v[168:171], v[116:119]
	v_mfma_f32_16x16x32_bf16 v[112:115], v[152:155], v[168:171], v[112:115]
	v_mfma_f32_16x16x32_bf16 v[84:87], v[144:147], v[176:179], v[84:87]
	v_mfma_f32_16x16x32_bf16 v[80:83], v[152:155], v[176:179], v[80:83]
	v_mfma_f32_16x16x32_bf16 v[68:71], v[144:147], v[194:197], v[68:71]
	v_mfma_f32_16x16x32_bf16 v[64:67], v[152:155], v[194:197], v[64:67]
	v_mfma_f32_16x16x32_bf16 v[132:135], v[148:151], v[164:167], v[132:135]
	v_mfma_f32_16x16x32_bf16 v[128:131], v[156:159], v[164:167], v[128:131]
	v_mfma_f32_16x16x32_bf16 v[116:119], v[148:151], v[172:175], v[116:119]
	v_mfma_f32_16x16x32_bf16 v[112:115], v[156:159], v[172:175], v[112:115]
	v_mfma_f32_16x16x32_bf16 v[84:87], v[148:151], v[190:193], v[84:87]
	v_mfma_f32_16x16x32_bf16 v[80:83], v[156:159], v[190:193], v[80:83]
	v_mfma_f32_16x16x32_bf16 v[68:71], v[148:151], v[198:201], v[68:71]
	v_mfma_f32_16x16x32_bf16 v[64:67], v[156:159], v[198:201], v[64:67]
	s_setprio 0
	s_barrier
	s_add_i32 s61, s61, s77
	v_lshl_add_u64 v[202:203], s[34:35], 0, v[232:233]
	s_mov_b32 m0, s61
	ds_read_b128 v[160:163], v221 offset:16384
	ds_read_b128 v[164:167], v221 offset:17408
	ds_read_b128 v[168:171], v221 offset:18432
	ds_read_b128 v[172:175], v221 offset:19456
	ds_read_b128 v[176:179], v221 offset:20480
	ds_read_b128 v[190:193], v221 offset:21504
	ds_read_b128 v[194:197], v221 offset:22528
	ds_read_b128 v[198:201], v221 offset:23552
	global_load_lds_dwordx4 v[202:203], off
	s_add_i32 m0, s61, 0x2000
	s_add_u32 s62, s34, 0x100000
	v_lshl_add_u64 v[204:205], s[34:35], 0, v[184:185]
	s_addc_u32 s63, s35, 0
	s_add_i32 s61, s64, s77
	global_load_lds_dwordx4 v[204:205], off
	v_lshl_add_u64 v[206:207], s[62:63], 0, v[232:233]
	s_mov_b32 m0, s61
	v_lshl_add_u64 v[208:209], s[36:37], 0, v[182:183]
	global_load_lds_dwordx4 v[206:207], off
	v_lshl_add_u64 v[206:207], s[62:63], 0, v[184:185]
	s_add_i32 m0, s61, 0x2000
	s_nop 0
	global_load_lds_dwordx4 v[206:207], off
	v_lshl_add_u64 v[206:207], s[36:37], 0, v[180:181]
	s_waitcnt vmcnt(6)
	s_waitcnt lgkmcnt(0)
	s_barrier
	s_setprio 1
	s_waitcnt lgkmcnt(0)
	v_mfma_f32_16x16x32_bf16 v[60:63], v[88:91], v[160:163], v[60:63]
	v_mfma_f32_16x16x32_bf16 v[56:59], v[96:99], v[160:163], v[56:59]
	v_mfma_f32_16x16x32_bf16 v[44:47], v[88:91], v[168:171], v[44:47]
	v_mfma_f32_16x16x32_bf16 v[40:43], v[96:99], v[168:171], v[40:43]
	v_mfma_f32_16x16x32_bf16 v[28:31], v[88:91], v[176:179], v[28:31]
	v_mfma_f32_16x16x32_bf16 v[24:27], v[96:99], v[176:179], v[24:27]
	v_mfma_f32_16x16x32_bf16 v[12:15], v[88:91], v[194:197], v[12:15]
	v_mfma_f32_16x16x32_bf16 v[8:11], v[96:99], v[194:197], v[8:11]
	v_mfma_f32_16x16x32_bf16 v[60:63], v[92:95], v[164:167], v[60:63]
	v_mfma_f32_16x16x32_bf16 v[56:59], v[100:103], v[164:167], v[56:59]
	v_mfma_f32_16x16x32_bf16 v[44:47], v[92:95], v[172:175], v[44:47]
	v_mfma_f32_16x16x32_bf16 v[40:43], v[100:103], v[172:175], v[40:43]
	v_mfma_f32_16x16x32_bf16 v[28:31], v[92:95], v[190:193], v[28:31]
	v_mfma_f32_16x16x32_bf16 v[24:27], v[100:103], v[190:193], v[24:27]
	v_mfma_f32_16x16x32_bf16 v[12:15], v[92:95], v[198:201], v[12:15]
	v_mfma_f32_16x16x32_bf16 v[8:11], v[100:103], v[198:201], v[8:11]
	v_mfma_f32_16x16x32_bf16 v[52:55], v[144:147], v[160:163], v[52:55]
	v_mfma_f32_16x16x32_bf16 v[48:51], v[152:155], v[160:163], v[48:51]
	v_mfma_f32_16x16x32_bf16 v[36:39], v[144:147], v[168:171], v[36:39]
	v_mfma_f32_16x16x32_bf16 v[32:35], v[152:155], v[168:171], v[32:35]
	v_mfma_f32_16x16x32_bf16 v[20:23], v[144:147], v[176:179], v[20:23]
	v_mfma_f32_16x16x32_bf16 v[16:19], v[152:155], v[176:179], v[16:19]
	v_mfma_f32_16x16x32_bf16 v[4:7], v[144:147], v[194:197], v[4:7]
	v_mfma_f32_16x16x32_bf16 v[0:3], v[152:155], v[194:197], v[0:3]
	v_mfma_f32_16x16x32_bf16 v[52:55], v[148:151], v[164:167], v[52:55]
	v_mfma_f32_16x16x32_bf16 v[48:51], v[156:159], v[164:167], v[48:51]
	v_mfma_f32_16x16x32_bf16 v[36:39], v[148:151], v[172:175], v[36:39]
	v_mfma_f32_16x16x32_bf16 v[32:35], v[156:159], v[172:175], v[32:35]
	v_mfma_f32_16x16x32_bf16 v[20:23], v[148:151], v[190:193], v[20:23]
	v_mfma_f32_16x16x32_bf16 v[16:19], v[156:159], v[190:193], v[16:19]
	v_mfma_f32_16x16x32_bf16 v[4:7], v[148:151], v[198:201], v[4:7]
	v_mfma_f32_16x16x32_bf16 v[0:3], v[156:159], v[198:201], v[0:3]
	s_setprio 0
	s_barrier
.Lzmid_6:
	s_add_i32 s61, 0, 0x18000
	s_add_i32 s62, 0, 0x1c000
	v_add_u32_e32 v100, s61, v220
	v_add_u32_e32 v156, s62, v220
	ds_read_b128 v[88:91], v100
	ds_read_b128 v[92:95], v100 offset:1024
	ds_read_b128 v[96:99], v100 offset:2048
	ds_read_b128 v[100:103], v100 offset:3072
	ds_read_b128 v[144:147], v156
	ds_read_b128 v[148:151], v156 offset:1024
	ds_read_b128 v[152:155], v156 offset:2048
	ds_read_b128 v[156:159], v156 offset:3072
	s_add_u32 s36, s36, 0x100000
	s_addc_u32 s37, s37, 0
	s_mov_b32 m0, s78
	s_nop 0
	global_load_lds_dwordx4 v[206:207], off
	s_mov_b32 m0, s79
	s_nop 0
	global_load_lds_dwordx4 v[208:209], off
	s_mov_b32 m0, s80
	v_lshl_add_u64 v[210:211], s[36:37], 0, v[180:181]
	ds_read_b128 v[160:163], v221 offset:32768
	ds_read_b128 v[164:167], v221 offset:33792
	ds_read_b128 v[168:171], v221 offset:34816
	ds_read_b128 v[172:175], v221 offset:35840
	ds_read_b128 v[176:179], v221 offset:36864
	ds_read_b128 v[190:193], v221 offset:37888
	ds_read_b128 v[194:197], v221 offset:38912
	ds_read_b128 v[198:201], v221 offset:39936
	global_load_lds_dwordx4 v[210:211], off
	v_lshl_add_u64 v[210:211], s[36:37], 0, v[182:183]
	s_mov_b32 m0, s81
	s_nop 0
	global_load_lds_dwordx4 v[210:211], off
	s_waitcnt vmcnt(8)
	s_waitcnt lgkmcnt(0)
	s_barrier
	s_setprio 1
	s_waitcnt lgkmcnt(0)
	v_mfma_f32_16x16x32_bf16 v[140:143], v[88:91], v[160:163], v[140:143]
	v_mfma_f32_16x16x32_bf16 v[136:139], v[96:99], v[160:163], v[136:139]
	v_mfma_f32_16x16x32_bf16 v[124:127], v[88:91], v[168:171], v[124:127]
	v_mfma_f32_16x16x32_bf16 v[120:123], v[96:99], v[168:171], v[120:123]
	v_mfma_f32_16x16x32_bf16 v[108:111], v[88:91], v[176:179], v[108:111]
	v_mfma_f32_16x16x32_bf16 v[104:107], v[96:99], v[176:179], v[104:107]
	v_mfma_f32_16x16x32_bf16 v[76:79], v[88:91], v[194:197], v[76:79]
	v_mfma_f32_16x16x32_bf16 v[72:75], v[96:99], v[194:197], v[72:75]
	v_mfma_f32_16x16x32_bf16 v[140:143], v[92:95], v[164:167], v[140:143]
	v_mfma_f32_16x16x32_bf16 v[136:139], v[100:103], v[164:167], v[136:139]
	v_mfma_f32_16x16x32_bf16 v[124:127], v[92:95], v[172:175], v[124:127]
	v_mfma_f32_16x16x32_bf16 v[120:123], v[100:103], v[172:175], v[120:123]
	v_mfma_f32_16x16x32_bf16 v[108:111], v[92:95], v[190:193], v[108:111]
	v_mfma_f32_16x16x32_bf16 v[104:107], v[100:103], v[190:193], v[104:107]
	v_mfma_f32_16x16x32_bf16 v[76:79], v[92:95], v[198:201], v[76:79]
	v_mfma_f32_16x16x32_bf16 v[72:75], v[100:103], v[198:201], v[72:75]
	v_mfma_f32_16x16x32_bf16 v[132:135], v[144:147], v[160:163], v[132:135]
	v_mfma_f32_16x16x32_bf16 v[128:131], v[152:155], v[160:163], v[128:131]
	v_mfma_f32_16x16x32_bf16 v[116:119], v[144:147], v[168:171], v[116:119]
	v_mfma_f32_16x16x32_bf16 v[112:115], v[152:155], v[168:171], v[112:115]
	v_mfma_f32_16x16x32_bf16 v[84:87], v[144:147], v[176:179], v[84:87]
	v_mfma_f32_16x16x32_bf16 v[80:83], v[152:155], v[176:179], v[80:83]
	v_mfma_f32_16x16x32_bf16 v[68:71], v[144:147], v[194:197], v[68:71]
	v_mfma_f32_16x16x32_bf16 v[64:67], v[152:155], v[194:197], v[64:67]
	v_mfma_f32_16x16x32_bf16 v[132:135], v[148:151], v[164:167], v[132:135]
	v_mfma_f32_16x16x32_bf16 v[128:131], v[156:159], v[164:167], v[128:131]
	v_mfma_f32_16x16x32_bf16 v[116:119], v[148:151], v[172:175], v[116:119]
	v_mfma_f32_16x16x32_bf16 v[112:115], v[156:159], v[172:175], v[112:115]
	v_mfma_f32_16x16x32_bf16 v[84:87], v[148:151], v[190:193], v[84:87]
	v_mfma_f32_16x16x32_bf16 v[80:83], v[156:159], v[190:193], v[80:83]
	v_mfma_f32_16x16x32_bf16 v[68:71], v[148:151], v[198:201], v[68:71]
	v_mfma_f32_16x16x32_bf16 v[64:67], v[156:159], v[198:201], v[64:67]
	s_setprio 0
	s_barrier
	s_add_i32 s36, s61, s77
	v_lshl_add_u64 v[202:203], v[202:203], 0, s[94:95]
	s_mov_b32 m0, s36
	ds_read_b128 v[160:163], v221 offset:49152
	ds_read_b128 v[164:167], v221 offset:50176
	ds_read_b128 v[168:171], v221 offset:51200
	ds_read_b128 v[172:175], v221 offset:52224
	ds_read_b128 v[176:179], v221 offset:53248
	ds_read_b128 v[190:193], v221 offset:54272
	ds_read_b128 v[194:197], v221 offset:55296
	ds_read_b128 v[198:201], v221 offset:56320
	global_load_lds_dwordx4 v[202:203], off
	s_add_i32 m0, s36, 0x2000
	s_add_u32 s34, s34, 0x100080
	v_lshl_add_u64 v[202:203], v[204:205], 0, s[94:95]
	s_addc_u32 s35, s35, 0
	s_add_i32 s36, s62, s77
	global_load_lds_dwordx4 v[202:203], off
	v_lshl_add_u64 v[202:203], s[34:35], 0, v[232:233]
	s_mov_b32 m0, s36
	s_nop 0
	global_load_lds_dwordx4 v[202:203], off
	v_lshl_add_u64 v[202:203], s[34:35], 0, v[184:185]
	s_add_i32 m0, s36, 0x2000
	s_nop 0
	global_load_lds_dwordx4 v[202:203], off
	v_lshl_add_u64 v[202:203], v[206:207], 0, s[94:95]
	s_mov_b32 m0, s52
	s_nop 0
	global_load_lds_dwordx4 v[202:203], off
	v_lshl_add_u64 v[202:203], v[208:209], 0, s[94:95]
	s_mov_b32 m0, s53
	s_nop 0
	global_load_lds_dwordx4 v[202:203], off
	s_waitcnt vmcnt(8)
	s_waitcnt lgkmcnt(0)
	s_barrier
	s_setprio 1
	s_waitcnt lgkmcnt(0)
	v_mfma_f32_16x16x32_bf16 v[60:63], v[88:91], v[160:163], v[60:63]
	v_mfma_f32_16x16x32_bf16 v[56:59], v[96:99], v[160:163], v[56:59]
	v_mfma_f32_16x16x32_bf16 v[44:47], v[88:91], v[168:171], v[44:47]
	v_mfma_f32_16x16x32_bf16 v[40:43], v[96:99], v[168:171], v[40:43]
	v_mfma_f32_16x16x32_bf16 v[28:31], v[88:91], v[176:179], v[28:31]
	v_mfma_f32_16x16x32_bf16 v[24:27], v[96:99], v[176:179], v[24:27]
	v_mfma_f32_16x16x32_bf16 v[12:15], v[88:91], v[194:197], v[12:15]
	v_mfma_f32_16x16x32_bf16 v[8:11], v[96:99], v[194:197], v[8:11]
	v_mfma_f32_16x16x32_bf16 v[60:63], v[92:95], v[164:167], v[60:63]
	v_mfma_f32_16x16x32_bf16 v[56:59], v[100:103], v[164:167], v[56:59]
	v_mfma_f32_16x16x32_bf16 v[44:47], v[92:95], v[172:175], v[44:47]
	v_mfma_f32_16x16x32_bf16 v[40:43], v[100:103], v[172:175], v[40:43]
	v_mfma_f32_16x16x32_bf16 v[28:31], v[92:95], v[190:193], v[28:31]
	v_mfma_f32_16x16x32_bf16 v[24:27], v[100:103], v[190:193], v[24:27]
	v_mfma_f32_16x16x32_bf16 v[12:15], v[92:95], v[198:201], v[12:15]
	v_mfma_f32_16x16x32_bf16 v[8:11], v[100:103], v[198:201], v[8:11]
	v_mfma_f32_16x16x32_bf16 v[52:55], v[144:147], v[160:163], v[52:55]
	v_mfma_f32_16x16x32_bf16 v[48:51], v[152:155], v[160:163], v[48:51]
	v_mfma_f32_16x16x32_bf16 v[36:39], v[144:147], v[168:171], v[36:39]
	v_mfma_f32_16x16x32_bf16 v[32:35], v[152:155], v[168:171], v[32:35]
	v_mfma_f32_16x16x32_bf16 v[20:23], v[144:147], v[176:179], v[20:23]
	v_mfma_f32_16x16x32_bf16 v[16:19], v[152:155], v[176:179], v[16:19]
	v_mfma_f32_16x16x32_bf16 v[4:7], v[144:147], v[194:197], v[4:7]
	v_mfma_f32_16x16x32_bf16 v[0:3], v[152:155], v[194:197], v[0:3]
	v_mfma_f32_16x16x32_bf16 v[52:55], v[148:151], v[164:167], v[52:55]
	v_mfma_f32_16x16x32_bf16 v[48:51], v[156:159], v[164:167], v[48:51]
	v_mfma_f32_16x16x32_bf16 v[36:39], v[148:151], v[172:175], v[36:39]
	v_mfma_f32_16x16x32_bf16 v[32:35], v[156:159], v[172:175], v[32:35]
	v_mfma_f32_16x16x32_bf16 v[20:23], v[148:151], v[190:193], v[20:23]
	v_mfma_f32_16x16x32_bf16 v[16:19], v[156:159], v[190:193], v[16:19]
	v_mfma_f32_16x16x32_bf16 v[4:7], v[148:151], v[198:201], v[4:7]
	v_mfma_f32_16x16x32_bf16 v[0:3], v[156:159], v[198:201], v[0:3]
	s_setprio 0
	s_barrier
	s_add_i32 s60, s60, 2
	s_add_u32 s58, s58, 0x100
	s_addc_u32 s59, s59, 0
	s_add_u32 s30, s30, 0x100
	s_addc_u32 s31, s31, 0
	s_cmp_gt_u32 s60, 61
	s_cbranch_scc0 .LBB0_1492
	s_and_b64 vcc, exec, s[18:19]
	s_cbranch_vccz .LBB0_1495
	s_barrier
